# peeled GEMM tail without its redundant closing barrier
# speedup vs baseline: 1.0941x; 1.0013x over previous
; template <int NJ>
; __device__ __forceinline__ void gemm_tile(const f16* __restrict__ A, int lda, const f16* __restrict__ Bt, int ldb,
;                                           int K, f32x4 (&acc)[4][NJ], f16* sA, f16* sB, const int tid) {
;     ...
;   G_LOAD(ra0, rb0, 0)
;   if (K > 64) G_LOAD(ra1, rb1, 64)
;   __syncthreads();
;   G_STORE(ra0, rb0, 0)
;   if (K > 128) G_LOAD(ra0, rb0, 128)
;   __syncthreads();
; #pragma unroll 1
;   for (int k0 = 0; k0 < K; k0 += 128) {
;     {
;       const int kof = (k0 + 192 < K) ? k0 + 192 : K - 64;
;       G_STEP(0, ra1, rb1, true, true, kof)
.LBB0_195:
	ds_read_b128 v[204:207], v168 offset:16384
	ds_read_b128 v[208:211], v168 offset:18432
	ds_read_b128 v[212:215], v168 offset:20480
	ds_read_b128 v[216:219], v168 offset:22528
	s_add_i32 s7, s6, 0xc0
	ds_read_b128 v[192:195], v170
	ds_read_b128 v[196:199], v170 offset:2048
	s_cmpk_lt_u32 s6, 0x340
	s_cselect_b32 s42, s7, 0x3c0
	ds_read_b128 v[200:203], v170 offset:4096
	s_lshl_b64 s[8:9], s[42:43], 1
	v_lshl_add_u64 v[162:163], v[156:157], 0, s[8:9]
	ds_read_b128 v[132:135], v170 offset:6144
	ds_read_b128 v[244:247], v243 offset:16384
	ds_read_b128 v[248:251], v243 offset:18432
	ds_read_b128 v[252:255], v243 offset:20480
	s_waitcnt lgkmcnt(6)
	v_mfma_f32_16x16x32_f16 v[64:67], v[204:207], v[192:195], v[64:67]
	v_lshl_add_u64 v[160:161], v[158:159], 0, s[8:9]
	s_add_i32 s7, s6, 0x100
	s_cmpk_lt_u32 s6, 0x300
	v_mfma_f32_16x16x32_f16 v[60:63], v[208:211], v[192:195], v[60:63]
	s_cselect_b32 s42, s7, 0x3c0
	s_lshl_b64 s[8:9], s[42:43], 1
	s_add_i32 s7, s6, 0x80
	v_mfma_f32_16x16x32_f16 v[56:59], v[212:215], v[192:195], v[56:59]
	s_cmpk_lt_u32 s6, 0x280
	s_mov_b32 s6, s7
	v_mfma_f32_16x16x32_f16 v[52:55], v[216:219], v[192:195], v[52:55]
	ds_read_b128 v[192:195], v243 offset:22528
	s_waitcnt vmcnt(15)
	ds_write_b128 v167, v[68:71] offset:32768
	global_load_dwordx4 v[68:71], v[162:163], off
	s_waitcnt lgkmcnt(7)
	v_mfma_f32_16x16x32_f16 v[48:51], v[204:207], v[196:199], v[48:51]
	v_mfma_f32_16x16x32_f16 v[44:47], v[208:211], v[196:199], v[44:47]
	v_mfma_f32_16x16x32_f16 v[40:43], v[212:215], v[196:199], v[40:43]
	v_mfma_f32_16x16x32_f16 v[36:39], v[216:219], v[196:199], v[36:39]
	ds_read_b128 v[196:199], v242
	s_waitcnt vmcnt(15)
	ds_write_b128 v167, v[76:79] offset:36864
	v_add_co_u32_e32 v76, vcc, s94, v162
	s_nop 1
	v_addc_co_u32_e32 v77, vcc, 0, v163, vcc
	global_load_dwordx4 v[76:79], v[76:77], off
	s_waitcnt lgkmcnt(8)
	v_mfma_f32_16x16x32_f16 v[32:35], v[204:207], v[200:203], v[32:35]
	v_mfma_f32_16x16x32_f16 v[28:31], v[208:211], v[200:203], v[28:31]
	v_mfma_f32_16x16x32_f16 v[24:27], v[212:215], v[200:203], v[24:27]
	v_mfma_f32_16x16x32_f16 v[20:23], v[216:219], v[200:203], v[20:23]
	ds_read_b128 v[200:203], v242 offset:2048
	s_waitcnt vmcnt(15)
	ds_write_b128 v167, v[80:83] offset:40960
	v_add_co_u32_e32 v80, vcc, s72, v162
	s_nop 1
	v_addc_co_u32_e32 v81, vcc, 0, v163, vcc
	global_load_dwordx4 v[80:83], v[80:81], off
	s_waitcnt lgkmcnt(9)
	v_mfma_f32_16x16x32_f16 v[16:19], v[204:207], v[132:135], v[16:19]
	v_mfma_f32_16x16x32_f16 v[12:15], v[208:211], v[132:135], v[12:15]
	v_mfma_f32_16x16x32_f16 v[8:11], v[212:215], v[132:135], v[8:11]
	v_mfma_f32_16x16x32_f16 v[4:7], v[216:219], v[132:135], v[4:7]
	ds_read_b128 v[132:135], v242 offset:4096
	ds_read_b128 v[204:207], v242 offset:6144
	s_waitcnt vmcnt(15)
	ds_write_b128 v167, v[84:87] offset:45056
	v_add_co_u32_e32 v84, vcc, s73, v162
	s_nop 1
	v_addc_co_u32_e32 v85, vcc, 0, v163, vcc
	global_load_dwordx4 v[84:87], v[84:85], off
	s_waitcnt lgkmcnt(6)
	v_mfma_f32_16x16x32_f16 v[64:67], v[244:247], v[196:199], v[64:67]
	v_mfma_f32_16x16x32_f16 v[60:63], v[248:251], v[196:199], v[60:63]
	v_mfma_f32_16x16x32_f16 v[56:59], v[252:255], v[196:199], v[56:59]
	v_mfma_f32_16x16x32_f16 v[52:55], v[192:195], v[196:199], v[52:55]
	s_waitcnt vmcnt(15)
	ds_write_b128 v167, v[72:75] offset:49152
	global_load_dwordx4 v[72:75], v[160:161], off
	v_lshl_add_u64 v[218:219], v[156:157], 0, s[8:9]
	s_waitcnt lgkmcnt(5)
	v_mfma_f32_16x16x32_f16 v[48:51], v[244:247], v[200:203], v[48:51]
	v_lshl_add_u64 v[216:217], v[158:159], 0, s[8:9]
	v_mfma_f32_16x16x32_f16 v[44:47], v[248:251], v[200:203], v[44:47]
	v_mfma_f32_16x16x32_f16 v[40:43], v[252:255], v[200:203], v[40:43]
	v_mfma_f32_16x16x32_f16 v[36:39], v[192:195], v[200:203], v[36:39]
	s_waitcnt vmcnt(15)
	ds_write_b128 v167, v[88:91] offset:53248
	v_add_co_u32_e32 v88, vcc, s94, v160
	s_nop 1
	v_addc_co_u32_e32 v89, vcc, 0, v161, vcc
	global_load_dwordx4 v[88:91], v[88:89], off
	s_waitcnt lgkmcnt(4)
	v_mfma_f32_16x16x32_f16 v[32:35], v[244:247], v[132:135], v[32:35]
	v_mfma_f32_16x16x32_f16 v[28:31], v[248:251], v[132:135], v[28:31]
	v_mfma_f32_16x16x32_f16 v[24:27], v[252:255], v[132:135], v[24:27]
	v_mfma_f32_16x16x32_f16 v[20:23], v[192:195], v[132:135], v[20:23]
	s_waitcnt vmcnt(15)
	ds_write_b128 v167, v[96:99] offset:57344
	v_add_co_u32_e32 v96, vcc, s72, v160
	s_nop 1
	v_addc_co_u32_e32 v97, vcc, 0, v161, vcc
	global_load_dwordx4 v[96:99], v[96:97], off
	s_waitcnt lgkmcnt(4)
	v_mfma_f32_16x16x32_f16 v[16:19], v[244:247], v[204:207], v[16:19]
	v_mfma_f32_16x16x32_f16 v[12:15], v[248:251], v[204:207], v[12:15]
	v_mfma_f32_16x16x32_f16 v[8:11], v[252:255], v[204:207], v[8:11]
	v_mfma_f32_16x16x32_f16 v[4:7], v[192:195], v[204:207], v[4:7]
	s_waitcnt vmcnt(15)
	ds_write_b128 v167, v[100:103] offset:61440
	v_add_co_u32_e32 v100, vcc, s73, v160
	s_nop 1
	v_addc_co_u32_e32 v101, vcc, 0, v161, vcc
	global_load_dwordx4 v[100:103], v[100:101], off
	s_waitcnt lgkmcnt(0)
	s_barrier
; template <int NJ>
; __device__ __forceinline__ void gemm_tile(const f16* __restrict__ A, int lda, const f16* __restrict__ Bt, int ldb,
;                                           int K, f32x4 (&acc)[4][NJ], f16* sA, f16* sB, const int tid) {
;     ...
;   G_LOAD(ra0, rb0, 0)
;   if (K > 64) G_LOAD(ra1, rb1, 64)
;   __syncthreads();
;   G_STORE(ra0, rb0, 0)
;   if (K > 128) G_LOAD(ra0, rb0, 128)
;   __syncthreads();
; #pragma unroll 1
;   for (int k0 = 0; k0 < K; k0 += 128) {
;     {
;       const int kof = (k0 + 192 < K) ? k0 + 192 : K - 64;
;       G_STEP(0, ra1, rb1, true, true, kof)
;     }
;     __syncthreads();
;     if (k0 + 64 >= K) break;
;     {
;       const int kof = (k0 + 256 < K) ? k0 + 256 : K - 64;
;       G_STEP(1, ra0, rb0, true, true, kof)
;     }
;     __syncthreads();
	ds_read_b128 v[200:203], v168 offset:49152
	ds_read_b128 v[204:207], v168 offset:51200
	ds_read_b128 v[208:211], v168 offset:53248
	ds_read_b128 v[212:215], v168 offset:55296
	ds_read_b128 v[132:135], v170 offset:32768
	ds_read_b128 v[160:163], v170 offset:34816
	ds_read_b128 v[192:195], v170 offset:36864
	ds_read_b128 v[196:199], v170 offset:38912
	ds_read_b128 v[244:247], v243 offset:49152
	ds_read_b128 v[248:251], v243 offset:51200
	ds_read_b128 v[252:255], v243 offset:53248
	s_waitcnt lgkmcnt(6)
	v_mfma_f32_16x16x32_f16 v[64:67], v[200:203], v[132:135], v[64:67]
	v_mfma_f32_16x16x32_f16 v[60:63], v[204:207], v[132:135], v[60:63]
	v_mfma_f32_16x16x32_f16 v[56:59], v[208:211], v[132:135], v[56:59]
	v_mfma_f32_16x16x32_f16 v[52:55], v[212:215], v[132:135], v[52:55]
	ds_read_b128 v[132:135], v243 offset:55296
	s_waitcnt vmcnt(13)
	ds_write_b128 v167, v[92:95]
	global_load_dwordx4 v[92:95], v[218:219], off
	s_waitcnt lgkmcnt(7)
	v_mfma_f32_16x16x32_f16 v[48:51], v[200:203], v[160:163], v[48:51]
	v_mfma_f32_16x16x32_f16 v[44:47], v[204:207], v[160:163], v[44:47]
	v_mfma_f32_16x16x32_f16 v[40:43], v[208:211], v[160:163], v[40:43]
	v_mfma_f32_16x16x32_f16 v[36:39], v[212:215], v[160:163], v[36:39]
	ds_read_b128 v[160:163], v242 offset:32768
	ds_write_b128 v167, v[108:111] offset:4096
	v_add_co_u32_e32 v108, vcc, s94, v218
	s_nop 1
	v_addc_co_u32_e32 v109, vcc, 0, v219, vcc
	global_load_dwordx4 v[108:111], v[108:109], off
	s_waitcnt lgkmcnt(8)
	v_mfma_f32_16x16x32_f16 v[32:35], v[200:203], v[192:195], v[32:35]
	v_mfma_f32_16x16x32_f16 v[28:31], v[204:207], v[192:195], v[28:31]
	v_mfma_f32_16x16x32_f16 v[24:27], v[208:211], v[192:195], v[24:27]
	v_mfma_f32_16x16x32_f16 v[20:23], v[212:215], v[192:195], v[20:23]
	ds_read_b128 v[192:195], v242 offset:34816
	ds_write_b128 v167, v[112:115] offset:8192
	v_add_co_u32_e32 v112, vcc, s72, v218
	s_nop 1
	v_addc_co_u32_e32 v113, vcc, 0, v219, vcc
	global_load_dwordx4 v[112:115], v[112:113], off
	s_waitcnt lgkmcnt(9)
	v_mfma_f32_16x16x32_f16 v[16:19], v[200:203], v[196:199], v[16:19]
	v_mfma_f32_16x16x32_f16 v[12:15], v[204:207], v[196:199], v[12:15]
	v_mfma_f32_16x16x32_f16 v[8:11], v[208:211], v[196:199], v[8:11]
	v_mfma_f32_16x16x32_f16 v[4:7], v[212:215], v[196:199], v[4:7]
	ds_read_b128 v[196:199], v242 offset:36864
	ds_read_b128 v[200:203], v242 offset:38912
	s_waitcnt vmcnt(14)
	ds_write_b128 v167, v[116:119] offset:12288
	v_add_co_u32_e32 v116, vcc, s73, v218
	s_nop 1
	v_addc_co_u32_e32 v117, vcc, 0, v219, vcc
	global_load_dwordx4 v[116:119], v[116:117], off
	s_waitcnt lgkmcnt(6)
	v_mfma_f32_16x16x32_f16 v[64:67], v[244:247], v[160:163], v[64:67]
	v_mfma_f32_16x16x32_f16 v[60:63], v[248:251], v[160:163], v[60:63]
	v_mfma_f32_16x16x32_f16 v[56:59], v[252:255], v[160:163], v[56:59]
	v_mfma_f32_16x16x32_f16 v[52:55], v[132:135], v[160:163], v[52:55]
	ds_write_b128 v167, v[104:107] offset:16384
	global_load_dwordx4 v[104:107], v[216:217], off
	s_waitcnt lgkmcnt(5)
	v_mfma_f32_16x16x32_f16 v[48:51], v[244:247], v[192:195], v[48:51]
	v_mfma_f32_16x16x32_f16 v[44:47], v[248:251], v[192:195], v[44:47]
	v_mfma_f32_16x16x32_f16 v[40:43], v[252:255], v[192:195], v[40:43]
	v_mfma_f32_16x16x32_f16 v[36:39], v[132:135], v[192:195], v[36:39]
	s_waitcnt vmcnt(15)
	ds_write_b128 v167, v[120:123] offset:20480
	v_add_co_u32_e32 v120, vcc, s94, v216
	s_nop 1
	v_addc_co_u32_e32 v121, vcc, 0, v217, vcc
	global_load_dwordx4 v[120:123], v[120:121], off
	s_waitcnt lgkmcnt(4)
	v_mfma_f32_16x16x32_f16 v[32:35], v[244:247], v[196:199], v[32:35]
	v_mfma_f32_16x16x32_f16 v[28:31], v[248:251], v[196:199], v[28:31]
	v_mfma_f32_16x16x32_f16 v[24:27], v[252:255], v[196:199], v[24:27]
	v_mfma_f32_16x16x32_f16 v[20:23], v[132:135], v[196:199], v[20:23]
	s_waitcnt vmcnt(15)
	ds_write_b128 v167, v[124:127] offset:24576
	v_add_co_u32_e32 v124, vcc, s72, v216
	s_nop 1
	v_addc_co_u32_e32 v125, vcc, 0, v217, vcc
	global_load_dwordx4 v[124:127], v[124:125], off
	s_waitcnt lgkmcnt(4)
	v_mfma_f32_16x16x32_f16 v[16:19], v[244:247], v[200:203], v[16:19]
	v_mfma_f32_16x16x32_f16 v[12:15], v[248:251], v[200:203], v[12:15]
	v_mfma_f32_16x16x32_f16 v[8:11], v[252:255], v[200:203], v[8:11]
	v_mfma_f32_16x16x32_f16 v[4:7], v[132:135], v[200:203], v[4:7]
	s_waitcnt vmcnt(15)
	ds_write_b128 v167, v[128:131] offset:28672
	v_add_co_u32_e32 v128, vcc, s73, v216
	s_nop 1
	v_addc_co_u32_e32 v129, vcc, 0, v217, vcc
	global_load_dwordx4 v[128:131], v[128:129], off
	s_waitcnt lgkmcnt(0)
	s_barrier
	s_cbranch_scc1 .LBB0_195
; template <int NJ>
; __device__ __forceinline__ void gemm_tile(const f16* __restrict__ A, int lda, const f16* __restrict__ Bt, int ldb,
;                                           int K, f32x4 (&acc)[4][NJ], f16* sA, f16* sB, const int tid) {
;     ...
;   G_LOAD(ra0, rb0, 0)
;   if (K > 64) G_LOAD(ra1, rb1, 64)
;   __syncthreads();
;   G_STORE(ra0, rb0, 0)
;   if (K > 128) G_LOAD(ra0, rb0, 128)
;   __syncthreads();
; #pragma unroll 1
;   for (int k0 = 0; k0 < K; k0 += 128) {
;     {
;       const int kof = (k0 + 192 < K) ? k0 + 192 : K - 64;
;       G_STEP(0, ra1, rb1, true, true, kof)
	ds_read_b128 v[204:207], v168 offset:16384
	ds_read_b128 v[208:211], v168 offset:18432
	ds_read_b128 v[212:215], v168 offset:20480
	ds_read_b128 v[216:219], v168 offset:22528
	s_add_i32 s7, s6, 0xc0
	ds_read_b128 v[192:195], v170
	ds_read_b128 v[196:199], v170 offset:2048
	s_cmpk_lt_u32 s6, 0x340
	s_cselect_b32 s42, s7, 0x3c0
	ds_read_b128 v[200:203], v170 offset:4096
	s_lshl_b64 s[8:9], s[42:43], 1
	v_lshl_add_u64 v[162:163], v[156:157], 0, s[8:9]
	ds_read_b128 v[132:135], v170 offset:6144
	ds_read_b128 v[244:247], v243 offset:16384
	ds_read_b128 v[248:251], v243 offset:18432
	ds_read_b128 v[252:255], v243 offset:20480
	s_waitcnt lgkmcnt(6)
	v_mfma_f32_16x16x32_f16 v[64:67], v[204:207], v[192:195], v[64:67]
	v_lshl_add_u64 v[160:161], v[158:159], 0, s[8:9]
	s_add_i32 s7, s6, 0x100
	s_cmpk_lt_u32 s6, 0x300
	v_mfma_f32_16x16x32_f16 v[60:63], v[208:211], v[192:195], v[60:63]
	s_cselect_b32 s42, s7, 0x3c0
	s_lshl_b64 s[8:9], s[42:43], 1
	s_add_i32 s7, s6, 0x80
	v_mfma_f32_16x16x32_f16 v[56:59], v[212:215], v[192:195], v[56:59]
	s_cmpk_lt_u32 s6, 0x380
	s_mov_b32 s6, s7
	v_mfma_f32_16x16x32_f16 v[52:55], v[216:219], v[192:195], v[52:55]
	ds_read_b128 v[192:195], v243 offset:22528
	s_waitcnt vmcnt(15)
	ds_write_b128 v167, v[68:71] offset:32768
	global_load_dwordx4 v[68:71], v[162:163], off
	s_waitcnt lgkmcnt(7)
	v_mfma_f32_16x16x32_f16 v[48:51], v[204:207], v[196:199], v[48:51]
	v_mfma_f32_16x16x32_f16 v[44:47], v[208:211], v[196:199], v[44:47]
	v_mfma_f32_16x16x32_f16 v[40:43], v[212:215], v[196:199], v[40:43]
	v_mfma_f32_16x16x32_f16 v[36:39], v[216:219], v[196:199], v[36:39]
	ds_read_b128 v[196:199], v242
	s_waitcnt vmcnt(15)
	ds_write_b128 v167, v[76:79] offset:36864
	v_add_co_u32_e32 v76, vcc, s94, v162
	s_nop 1
	v_addc_co_u32_e32 v77, vcc, 0, v163, vcc
	global_load_dwordx4 v[76:79], v[76:77], off
	s_waitcnt lgkmcnt(8)
	v_mfma_f32_16x16x32_f16 v[32:35], v[204:207], v[200:203], v[32:35]
	v_mfma_f32_16x16x32_f16 v[28:31], v[208:211], v[200:203], v[28:31]
	v_mfma_f32_16x16x32_f16 v[24:27], v[212:215], v[200:203], v[24:27]
	v_mfma_f32_16x16x32_f16 v[20:23], v[216:219], v[200:203], v[20:23]
	ds_read_b128 v[200:203], v242 offset:2048
	s_waitcnt vmcnt(15)
	ds_write_b128 v167, v[80:83] offset:40960
	v_add_co_u32_e32 v80, vcc, s72, v162
	s_nop 1
	v_addc_co_u32_e32 v81, vcc, 0, v163, vcc
	global_load_dwordx4 v[80:83], v[80:81], off
	s_waitcnt lgkmcnt(9)
	v_mfma_f32_16x16x32_f16 v[16:19], v[204:207], v[132:135], v[16:19]
	v_mfma_f32_16x16x32_f16 v[12:15], v[208:211], v[132:135], v[12:15]
	v_mfma_f32_16x16x32_f16 v[8:11], v[212:215], v[132:135], v[8:11]
	v_mfma_f32_16x16x32_f16 v[4:7], v[216:219], v[132:135], v[4:7]
	ds_read_b128 v[132:135], v242 offset:4096
	ds_read_b128 v[204:207], v242 offset:6144
	s_waitcnt vmcnt(15)
	ds_write_b128 v167, v[84:87] offset:45056
	v_add_co_u32_e32 v84, vcc, s73, v162
	s_nop 1
	v_addc_co_u32_e32 v85, vcc, 0, v163, vcc
	global_load_dwordx4 v[84:87], v[84:85], off
	s_waitcnt lgkmcnt(6)
	v_mfma_f32_16x16x32_f16 v[64:67], v[244:247], v[196:199], v[64:67]
	v_mfma_f32_16x16x32_f16 v[60:63], v[248:251], v[196:199], v[60:63]
	v_mfma_f32_16x16x32_f16 v[56:59], v[252:255], v[196:199], v[56:59]
	v_mfma_f32_16x16x32_f16 v[52:55], v[192:195], v[196:199], v[52:55]
	s_waitcnt vmcnt(15)
	ds_write_b128 v167, v[72:75] offset:49152
	global_load_dwordx4 v[72:75], v[160:161], off
	v_lshl_add_u64 v[218:219], v[156:157], 0, s[8:9]
	s_waitcnt lgkmcnt(5)
	v_mfma_f32_16x16x32_f16 v[48:51], v[244:247], v[200:203], v[48:51]
	v_lshl_add_u64 v[216:217], v[158:159], 0, s[8:9]
	v_mfma_f32_16x16x32_f16 v[44:47], v[248:251], v[200:203], v[44:47]
	v_mfma_f32_16x16x32_f16 v[40:43], v[252:255], v[200:203], v[40:43]
	v_mfma_f32_16x16x32_f16 v[36:39], v[192:195], v[200:203], v[36:39]
	s_waitcnt vmcnt(15)
	ds_write_b128 v167, v[88:91] offset:53248
	v_add_co_u32_e32 v88, vcc, s94, v160
	s_nop 1
	v_addc_co_u32_e32 v89, vcc, 0, v161, vcc
	global_load_dwordx4 v[88:91], v[88:89], off
	s_waitcnt lgkmcnt(4)
	v_mfma_f32_16x16x32_f16 v[32:35], v[244:247], v[132:135], v[32:35]
	v_mfma_f32_16x16x32_f16 v[28:31], v[248:251], v[132:135], v[28:31]
	v_mfma_f32_16x16x32_f16 v[24:27], v[252:255], v[132:135], v[24:27]
	v_mfma_f32_16x16x32_f16 v[20:23], v[192:195], v[132:135], v[20:23]
	s_waitcnt vmcnt(15)
	ds_write_b128 v167, v[96:99] offset:57344
	v_add_co_u32_e32 v96, vcc, s72, v160
	s_nop 1
	v_addc_co_u32_e32 v97, vcc, 0, v161, vcc
	global_load_dwordx4 v[96:99], v[96:97], off
	s_waitcnt lgkmcnt(4)
	v_mfma_f32_16x16x32_f16 v[16:19], v[244:247], v[204:207], v[16:19]
	v_mfma_f32_16x16x32_f16 v[12:15], v[248:251], v[204:207], v[12:15]
	v_mfma_f32_16x16x32_f16 v[8:11], v[252:255], v[204:207], v[8:11]
	v_mfma_f32_16x16x32_f16 v[4:7], v[192:195], v[204:207], v[4:7]
	s_waitcnt vmcnt(15)
	ds_write_b128 v167, v[100:103] offset:61440
	v_add_co_u32_e32 v100, vcc, s73, v160
	s_nop 1
	v_addc_co_u32_e32 v101, vcc, 0, v161, vcc
	global_load_dwordx4 v[100:103], v[100:101], off
	s_waitcnt lgkmcnt(0)
	s_barrier
; template <int NJ>
; __device__ __forceinline__ void gemm_tile(const f16* __restrict__ A, int lda, const f16* __restrict__ Bt, int ldb,
;                                           int K, f32x4 (&acc)[4][NJ], f16* sA, f16* sB, const int tid) {
;     ...
;   G_LOAD(ra0, rb0, 0)
;   if (K > 64) G_LOAD(ra1, rb1, 64)
;   __syncthreads();
;   G_STORE(ra0, rb0, 0)
;   if (K > 128) G_LOAD(ra0, rb0, 128)
;   __syncthreads();
; #pragma unroll 1
;   for (int k0 = 0; k0 < K; k0 += 128) {
;     {
;       const int kof = (k0 + 192 < K) ? k0 + 192 : K - 64;
;       G_STEP(0, ra1, rb1, true, true, kof)
;     }
;     __syncthreads();
;     if (k0 + 64 >= K) break;
;     {
;       const int kof = (k0 + 256 < K) ? k0 + 256 : K - 64;
;       G_STEP(1, ra0, rb0, true, true, kof)
;     }
;     __syncthreads();
	ds_read_b128 v[200:203], v168 offset:49152
	ds_read_b128 v[204:207], v168 offset:51200
	ds_read_b128 v[208:211], v168 offset:53248
	ds_read_b128 v[212:215], v168 offset:55296
	ds_read_b128 v[132:135], v170 offset:32768
	ds_read_b128 v[160:163], v170 offset:34816
	ds_read_b128 v[192:195], v170 offset:36864
	ds_read_b128 v[196:199], v170 offset:38912
	ds_read_b128 v[244:247], v243 offset:49152
	ds_read_b128 v[248:251], v243 offset:51200
	ds_read_b128 v[252:255], v243 offset:53248
	s_waitcnt lgkmcnt(6)
	v_mfma_f32_16x16x32_f16 v[64:67], v[200:203], v[132:135], v[64:67]
	v_mfma_f32_16x16x32_f16 v[60:63], v[204:207], v[132:135], v[60:63]
	v_mfma_f32_16x16x32_f16 v[56:59], v[208:211], v[132:135], v[56:59]
	v_mfma_f32_16x16x32_f16 v[52:55], v[212:215], v[132:135], v[52:55]
	ds_read_b128 v[132:135], v243 offset:55296
	s_waitcnt vmcnt(15)
	ds_write_b128 v167, v[92:95]
	s_waitcnt lgkmcnt(7)
	v_mfma_f32_16x16x32_f16 v[48:51], v[200:203], v[160:163], v[48:51]
	v_mfma_f32_16x16x32_f16 v[44:47], v[204:207], v[160:163], v[44:47]
	v_mfma_f32_16x16x32_f16 v[40:43], v[208:211], v[160:163], v[40:43]
	v_mfma_f32_16x16x32_f16 v[36:39], v[212:215], v[160:163], v[36:39]
	ds_read_b128 v[160:163], v242 offset:32768
	s_waitcnt vmcnt(14)
	ds_write_b128 v167, v[108:111] offset:4096
	s_waitcnt lgkmcnt(8)
	v_mfma_f32_16x16x32_f16 v[32:35], v[200:203], v[192:195], v[32:35]
	v_mfma_f32_16x16x32_f16 v[28:31], v[204:207], v[192:195], v[28:31]
	v_mfma_f32_16x16x32_f16 v[24:27], v[208:211], v[192:195], v[24:27]
	v_mfma_f32_16x16x32_f16 v[20:23], v[212:215], v[192:195], v[20:23]
	ds_read_b128 v[192:195], v242 offset:34816
	s_waitcnt vmcnt(13)
	ds_write_b128 v167, v[112:115] offset:8192
	s_waitcnt lgkmcnt(9)
	v_mfma_f32_16x16x32_f16 v[16:19], v[200:203], v[196:199], v[16:19]
	v_mfma_f32_16x16x32_f16 v[12:15], v[204:207], v[196:199], v[12:15]
	v_mfma_f32_16x16x32_f16 v[8:11], v[208:211], v[196:199], v[8:11]
	v_mfma_f32_16x16x32_f16 v[4:7], v[212:215], v[196:199], v[4:7]
	ds_read_b128 v[196:199], v242 offset:36864
	ds_read_b128 v[200:203], v242 offset:38912
	s_waitcnt vmcnt(12)
	ds_write_b128 v167, v[116:119] offset:12288
	s_waitcnt lgkmcnt(6)
	v_mfma_f32_16x16x32_f16 v[64:67], v[244:247], v[160:163], v[64:67]
	v_mfma_f32_16x16x32_f16 v[60:63], v[248:251], v[160:163], v[60:63]
	v_mfma_f32_16x16x32_f16 v[56:59], v[252:255], v[160:163], v[56:59]
	v_mfma_f32_16x16x32_f16 v[52:55], v[132:135], v[160:163], v[52:55]
	s_waitcnt vmcnt(11)
	ds_write_b128 v167, v[104:107] offset:16384
	s_waitcnt lgkmcnt(5)
	v_mfma_f32_16x16x32_f16 v[48:51], v[244:247], v[192:195], v[48:51]
	v_mfma_f32_16x16x32_f16 v[44:47], v[248:251], v[192:195], v[44:47]
	v_mfma_f32_16x16x32_f16 v[40:43], v[252:255], v[192:195], v[40:43]
	v_mfma_f32_16x16x32_f16 v[36:39], v[132:135], v[192:195], v[36:39]
	s_waitcnt vmcnt(10)
	ds_write_b128 v167, v[120:123] offset:20480
	s_waitcnt lgkmcnt(4)
	v_mfma_f32_16x16x32_f16 v[32:35], v[244:247], v[196:199], v[32:35]
	v_mfma_f32_16x16x32_f16 v[28:31], v[248:251], v[196:199], v[28:31]
	v_mfma_f32_16x16x32_f16 v[24:27], v[252:255], v[196:199], v[24:27]
	v_mfma_f32_16x16x32_f16 v[20:23], v[132:135], v[196:199], v[20:23]
	s_waitcnt vmcnt(9)
	ds_write_b128 v167, v[124:127] offset:24576
	s_waitcnt lgkmcnt(4)
	v_mfma_f32_16x16x32_f16 v[16:19], v[244:247], v[200:203], v[16:19]
	v_mfma_f32_16x16x32_f16 v[12:15], v[248:251], v[200:203], v[12:15]
	v_mfma_f32_16x16x32_f16 v[8:11], v[252:255], v[200:203], v[8:11]
	v_mfma_f32_16x16x32_f16 v[4:7], v[132:135], v[200:203], v[4:7]
	s_waitcnt vmcnt(8)
	ds_write_b128 v167, v[128:131] offset:28672
	s_waitcnt lgkmcnt(0)
	s_barrier
	ds_read_b128 v[204:207], v168 offset:16384
	ds_read_b128 v[208:211], v168 offset:18432
	ds_read_b128 v[212:215], v168 offset:20480
	ds_read_b128 v[216:219], v168 offset:22528
	s_add_i32 s7, s6, 0xc0
	ds_read_b128 v[192:195], v170
	ds_read_b128 v[196:199], v170 offset:2048
	s_cmpk_lt_u32 s6, 0x340
	s_cselect_b32 s42, s7, 0x3c0
	ds_read_b128 v[200:203], v170 offset:4096
	s_lshl_b64 s[8:9], s[42:43], 1
	v_lshl_add_u64 v[162:163], v[156:157], 0, s[8:9]
	ds_read_b128 v[132:135], v170 offset:6144
	ds_read_b128 v[244:247], v243 offset:16384
	ds_read_b128 v[248:251], v243 offset:18432
	ds_read_b128 v[252:255], v243 offset:20480
	s_waitcnt lgkmcnt(6)
	v_mfma_f32_16x16x32_f16 v[64:67], v[204:207], v[192:195], v[64:67]
	v_lshl_add_u64 v[160:161], v[158:159], 0, s[8:9]
	s_add_i32 s7, s6, 0x100
	s_cmpk_lt_u32 s6, 0x300
	v_mfma_f32_16x16x32_f16 v[60:63], v[208:211], v[192:195], v[60:63]
	s_cselect_b32 s42, s7, 0x3c0
	s_lshl_b64 s[8:9], s[42:43], 1
	s_add_i32 s7, s6, 0x80
	v_mfma_f32_16x16x32_f16 v[56:59], v[212:215], v[192:195], v[56:59]
	s_cmpk_lt_u32 s6, 0x380
	s_mov_b32 s6, s7
	v_mfma_f32_16x16x32_f16 v[52:55], v[216:219], v[192:195], v[52:55]
	ds_read_b128 v[192:195], v243 offset:22528
	s_waitcnt vmcnt(7)
	ds_write_b128 v167, v[68:71] offset:32768
	s_waitcnt lgkmcnt(7)
	v_mfma_f32_16x16x32_f16 v[48:51], v[204:207], v[196:199], v[48:51]
	v_mfma_f32_16x16x32_f16 v[44:47], v[208:211], v[196:199], v[44:47]
	v_mfma_f32_16x16x32_f16 v[40:43], v[212:215], v[196:199], v[40:43]
	v_mfma_f32_16x16x32_f16 v[36:39], v[216:219], v[196:199], v[36:39]
	ds_read_b128 v[196:199], v242
	s_waitcnt vmcnt(6)
	ds_write_b128 v167, v[76:79] offset:36864
	s_waitcnt lgkmcnt(8)
	v_mfma_f32_16x16x32_f16 v[32:35], v[204:207], v[200:203], v[32:35]
	v_mfma_f32_16x16x32_f16 v[28:31], v[208:211], v[200:203], v[28:31]
	v_mfma_f32_16x16x32_f16 v[24:27], v[212:215], v[200:203], v[24:27]
	v_mfma_f32_16x16x32_f16 v[20:23], v[216:219], v[200:203], v[20:23]
	ds_read_b128 v[200:203], v242 offset:2048
	s_waitcnt vmcnt(5)
; template <int NJ>
; __device__ __forceinline__ void gemm_tile(const f16* __restrict__ A, int lda, const f16* __restrict__ Bt, int ldb,
;                                           int K, f32x4 (&acc)[4][NJ], f16* sA, f16* sB, const int tid) {
;     ...
;   G_LOAD(ra0, rb0, 0)
;   if (K > 64) G_LOAD(ra1, rb1, 64)
;   __syncthreads();
;   G_STORE(ra0, rb0, 0)
;   if (K > 128) G_LOAD(ra0, rb0, 128)
;   __syncthreads();
; #pragma unroll 1
;   for (int k0 = 0; k0 < K; k0 += 128) {
;     {
;       const int kof = (k0 + 192 < K) ? k0 + 192 : K - 64;
;       G_STEP(0, ra1, rb1, true, true, kof)
;     }
;     __syncthreads();
;     if (k0 + 64 >= K) break;
;     {
;       const int kof = (k0 + 256 < K) ? k0 + 256 : K - 64;
;       G_STEP(1, ra0, rb0, true, true, kof)
;     }
;     __syncthreads();
; __device__ __forceinline__ void phase_g1(const Params& p, int l, f16* smem) {
;     ...
;     } else {
; #pragma unroll
;       for (int i = 0; i < 4; ++i) {
;         int m = m0 + wm * 64 + i * 16 + (lane & 15);
; #pragma unroll
;         for (int j = 0; j < 4; ++j) {
;           int n = n0 + wn * 64 + j * 16 + 4 * (lane >> 4);
;           if (n < N1) {
;             f16x4 o;
;             o[0] = (f16)acc[i][j][0];
;             o[1] = (f16)acc[i][j][1];
;             o[2] = (f16)acc[i][j][2];
;             o[3] = (f16)acc[i][j][3];
;             *(f16x4*)(proj + (size_t)m * PJ + (n - 384)) = o;
	ds_write_b128 v167, v[80:83] offset:40960
	s_waitcnt lgkmcnt(9)
	v_mfma_f32_16x16x32_f16 v[16:19], v[204:207], v[132:135], v[16:19]
	v_mfma_f32_16x16x32_f16 v[12:15], v[208:211], v[132:135], v[12:15]
	v_mfma_f32_16x16x32_f16 v[8:11], v[212:215], v[132:135], v[8:11]
	v_mfma_f32_16x16x32_f16 v[4:7], v[216:219], v[132:135], v[4:7]
	ds_read_b128 v[132:135], v242 offset:4096
	ds_read_b128 v[204:207], v242 offset:6144
	s_waitcnt vmcnt(4)
	ds_write_b128 v167, v[84:87] offset:45056
	s_waitcnt lgkmcnt(6)
	v_mfma_f32_16x16x32_f16 v[64:67], v[244:247], v[196:199], v[64:67]
	v_mfma_f32_16x16x32_f16 v[60:63], v[248:251], v[196:199], v[60:63]
	v_mfma_f32_16x16x32_f16 v[56:59], v[252:255], v[196:199], v[56:59]
	v_mfma_f32_16x16x32_f16 v[52:55], v[192:195], v[196:199], v[52:55]
	s_waitcnt vmcnt(3)
	ds_write_b128 v167, v[72:75] offset:49152
	v_lshl_add_u64 v[218:219], v[156:157], 0, s[8:9]
	s_waitcnt lgkmcnt(5)
	v_mfma_f32_16x16x32_f16 v[48:51], v[244:247], v[200:203], v[48:51]
	v_lshl_add_u64 v[216:217], v[158:159], 0, s[8:9]
	v_mfma_f32_16x16x32_f16 v[44:47], v[248:251], v[200:203], v[44:47]
	v_mfma_f32_16x16x32_f16 v[40:43], v[252:255], v[200:203], v[40:43]
	v_mfma_f32_16x16x32_f16 v[36:39], v[192:195], v[200:203], v[36:39]
	s_waitcnt vmcnt(2)
	ds_write_b128 v167, v[88:91] offset:53248
	s_waitcnt lgkmcnt(4)
	v_mfma_f32_16x16x32_f16 v[32:35], v[244:247], v[132:135], v[32:35]
	v_mfma_f32_16x16x32_f16 v[28:31], v[248:251], v[132:135], v[28:31]
	v_mfma_f32_16x16x32_f16 v[24:27], v[252:255], v[132:135], v[24:27]
	v_mfma_f32_16x16x32_f16 v[20:23], v[192:195], v[132:135], v[20:23]
	s_waitcnt vmcnt(1)
	ds_write_b128 v167, v[96:99] offset:57344
	s_waitcnt lgkmcnt(4)
	v_mfma_f32_16x16x32_f16 v[16:19], v[244:247], v[204:207], v[16:19]
	v_mfma_f32_16x16x32_f16 v[12:15], v[248:251], v[204:207], v[12:15]
	v_mfma_f32_16x16x32_f16 v[8:11], v[252:255], v[204:207], v[8:11]
	v_mfma_f32_16x16x32_f16 v[4:7], v[192:195], v[204:207], v[4:7]
	s_waitcnt vmcnt(0)
	ds_write_b128 v167, v[100:103] offset:61440
	s_waitcnt lgkmcnt(0)
	s_barrier
	ds_read_b128 v[200:203], v168 offset:49152
	ds_read_b128 v[204:207], v168 offset:51200
	ds_read_b128 v[208:211], v168 offset:53248
	ds_read_b128 v[212:215], v168 offset:55296
	ds_read_b128 v[132:135], v170 offset:32768
	ds_read_b128 v[160:163], v170 offset:34816
	ds_read_b128 v[192:195], v170 offset:36864
	ds_read_b128 v[196:199], v170 offset:38912
	ds_read_b128 v[244:247], v243 offset:49152
	ds_read_b128 v[248:251], v243 offset:51200
	ds_read_b128 v[252:255], v243 offset:53248
	s_waitcnt lgkmcnt(6)
	v_mfma_f32_16x16x32_f16 v[64:67], v[200:203], v[132:135], v[64:67]
	v_mfma_f32_16x16x32_f16 v[60:63], v[204:207], v[132:135], v[60:63]
	v_mfma_f32_16x16x32_f16 v[56:59], v[208:211], v[132:135], v[56:59]
	v_mfma_f32_16x16x32_f16 v[52:55], v[212:215], v[132:135], v[52:55]
	ds_read_b128 v[132:135], v243 offset:55296
	s_waitcnt lgkmcnt(6)
	v_mfma_f32_16x16x32_f16 v[48:51], v[200:203], v[160:163], v[48:51]
	v_mfma_f32_16x16x32_f16 v[44:47], v[204:207], v[160:163], v[44:47]
	v_mfma_f32_16x16x32_f16 v[40:43], v[208:211], v[160:163], v[40:43]
	v_mfma_f32_16x16x32_f16 v[36:39], v[212:215], v[160:163], v[36:39]
	ds_read_b128 v[160:163], v242 offset:32768
	s_waitcnt lgkmcnt(6)
	v_mfma_f32_16x16x32_f16 v[32:35], v[200:203], v[192:195], v[32:35]
	v_mfma_f32_16x16x32_f16 v[28:31], v[204:207], v[192:195], v[28:31]
	v_mfma_f32_16x16x32_f16 v[24:27], v[208:211], v[192:195], v[24:27]
	v_mfma_f32_16x16x32_f16 v[20:23], v[212:215], v[192:195], v[20:23]
	ds_read_b128 v[192:195], v242 offset:34816
	s_waitcnt lgkmcnt(6)
	v_mfma_f32_16x16x32_f16 v[16:19], v[200:203], v[196:199], v[16:19]
	v_mfma_f32_16x16x32_f16 v[12:15], v[204:207], v[196:199], v[12:15]
	v_mfma_f32_16x16x32_f16 v[8:11], v[208:211], v[196:199], v[8:11]
	v_mfma_f32_16x16x32_f16 v[4:7], v[212:215], v[196:199], v[4:7]
	ds_read_b128 v[196:199], v242 offset:36864
	ds_read_b128 v[200:203], v242 offset:38912
	s_waitcnt lgkmcnt(3)
	v_mfma_f32_16x16x32_f16 v[64:67], v[244:247], v[160:163], v[64:67]
	v_mfma_f32_16x16x32_f16 v[60:63], v[248:251], v[160:163], v[60:63]
	v_mfma_f32_16x16x32_f16 v[56:59], v[252:255], v[160:163], v[56:59]
	v_mfma_f32_16x16x32_f16 v[52:55], v[132:135], v[160:163], v[52:55]
	s_waitcnt lgkmcnt(2)
	v_mfma_f32_16x16x32_f16 v[48:51], v[244:247], v[192:195], v[48:51]
	v_mfma_f32_16x16x32_f16 v[44:47], v[248:251], v[192:195], v[44:47]
	v_mfma_f32_16x16x32_f16 v[40:43], v[252:255], v[192:195], v[40:43]
	v_mfma_f32_16x16x32_f16 v[36:39], v[132:135], v[192:195], v[36:39]
	s_waitcnt lgkmcnt(1)
	v_mfma_f32_16x16x32_f16 v[32:35], v[244:247], v[196:199], v[32:35]
	v_mfma_f32_16x16x32_f16 v[28:31], v[248:251], v[196:199], v[28:31]
	v_mfma_f32_16x16x32_f16 v[24:27], v[252:255], v[196:199], v[24:27]
	v_mfma_f32_16x16x32_f16 v[20:23], v[132:135], v[196:199], v[20:23]
	s_waitcnt lgkmcnt(0)
	v_mfma_f32_16x16x32_f16 v[16:19], v[244:247], v[200:203], v[16:19]
	v_mfma_f32_16x16x32_f16 v[12:15], v[248:251], v[200:203], v[12:15]
	v_mfma_f32_16x16x32_f16 v[8:11], v[252:255], v[200:203], v[8:11]
	v_mfma_f32_16x16x32_f16 v[4:7], v[132:135], v[200:203], v[4:7]
	s_waitcnt lgkmcnt(0)
	s_cmp_gt_i32 s21, 5
	s_mov_b64 s[6:7], -1
	s_cbranch_scc0 .LBB0_210
	s_cmp_lt_u32 s21, 9
	s_cbranch_scc1 .LBB0_232
	s_waitcnt vmcnt(15)
	v_add_u32_e32 v70, s14, v143
	v_or_b32_e32 v164, s16, v166
	v_mad_i64_i32 v[68:69], s[6:7], v70, s22, v[144:145]
	v_cmp_gt_i32_e32 vcc, s62, v164
	s_and_saveexec_b64 s[6:7], vcc
	s_cbranch_execz .LBB0_200
	s_waitcnt vmcnt(11)
	v_cvt_pk_f16_f32 v73, v66, v67
	v_cvt_pk_f16_f32 v72, v64, v65
	v_lshl_add_u64 v[74:75], v[164:165], 1, v[68:69]
	global_store_dwordx2 v[74:75], v[72:73], off offset:-768

; template <int NJ>
; __device__ __forceinline__ void gemm_tile(const f16* __restrict__ A, int lda, const f16* __restrict__ Bt, int ldb,
;                                           int K, f32x4 (&acc)[4][NJ], f16* sA, f16* sB, const int tid) {
;     ...
;   G_LOAD(ra0, rb0, 0)
;   if (K > 64) G_LOAD(ra1, rb1, 64)
;   __syncthreads();
;   G_STORE(ra0, rb0, 0)
;   if (K > 128) G_LOAD(ra0, rb0, 128)
;   __syncthreads();
; #pragma unroll 1
;   for (int k0 = 0; k0 < K; k0 += 128) {
;     {
;       const int kof = (k0 + 192 < K) ? k0 + 192 : K - 64;
;       G_STEP(0, ra1, rb1, true, true, kof)
.LBB0_1186:
	ds_read_b128 v[208:211], v192 offset:16384
	ds_read_b128 v[212:215], v192 offset:18432
	ds_read_b128 v[216:219], v192 offset:20480
	ds_read_b128 v[220:223], v192 offset:22528
	s_add_i32 s10, s9, 0xc0
	ds_read_b128 v[196:199], v170
	ds_read_b128 v[200:203], v170 offset:2048
	s_cmpk_lt_u32 s9, 0x340
	s_cselect_b32 s42, s10, 0x3c0
	ds_read_b128 v[204:207], v170 offset:4096
	s_lshl_b64 s[10:11], s[42:43], 1
	v_lshl_add_u64 v[160:161], v[154:155], 0, s[10:11]
	ds_read_b128 v[130:133], v170 offset:6144
	ds_read_b128 v[244:247], v243 offset:16384
	ds_read_b128 v[248:251], v243 offset:18432
	ds_read_b128 v[252:255], v243 offset:20480
	s_waitcnt lgkmcnt(6)
	v_mfma_f32_16x16x32_f16 v[126:129], v[208:211], v[196:199], v[126:129]
	v_lshl_add_u64 v[158:159], v[156:157], 0, s[10:11]
	s_add_i32 s10, s9, 0x100
	s_cmpk_lt_u32 s9, 0x300
	v_mfma_f32_16x16x32_f16 v[122:125], v[212:215], v[196:199], v[122:125]
	s_cselect_b32 s42, s10, 0x3c0
	s_lshl_b64 s[10:11], s[42:43], 1
	v_mfma_f32_16x16x32_f16 v[118:121], v[216:219], v[196:199], v[118:121]
	v_mfma_f32_16x16x32_f16 v[114:117], v[220:223], v[196:199], v[114:117]
	ds_read_b128 v[196:199], v243 offset:22528
	s_waitcnt vmcnt(15)
	ds_write_b128 v169, v[34:37] offset:32768
	global_load_dwordx4 v[34:37], v[160:161], off
	s_waitcnt lgkmcnt(7)
	v_mfma_f32_16x16x32_f16 v[110:113], v[208:211], v[200:203], v[110:113]
	v_mfma_f32_16x16x32_f16 v[106:109], v[212:215], v[200:203], v[106:109]
	v_mfma_f32_16x16x32_f16 v[102:105], v[216:219], v[200:203], v[102:105]
	v_mfma_f32_16x16x32_f16 v[98:101], v[220:223], v[200:203], v[98:101]
	ds_read_b128 v[200:203], v242
	s_waitcnt vmcnt(15)
	ds_write_b128 v169, v[42:45] offset:36864
	v_add_co_u32_e32 v42, vcc, s94, v160
	s_nop 1
	v_addc_co_u32_e32 v43, vcc, 0, v161, vcc
	global_load_dwordx4 v[42:45], v[42:43], off
	s_waitcnt lgkmcnt(8)
	v_mfma_f32_16x16x32_f16 v[30:33], v[208:211], v[204:207], v[30:33]
	v_mfma_f32_16x16x32_f16 v[26:29], v[212:215], v[204:207], v[26:29]
	v_mfma_f32_16x16x32_f16 v[22:25], v[216:219], v[204:207], v[22:25]
	v_mfma_f32_16x16x32_f16 v[18:21], v[220:223], v[204:207], v[18:21]
	ds_read_b128 v[204:207], v242 offset:2048
	s_waitcnt vmcnt(15)
	ds_write_b128 v169, v[46:49] offset:40960
	v_add_co_u32_e32 v46, vcc, s72, v160
	s_nop 1
	v_addc_co_u32_e32 v47, vcc, 0, v161, vcc
	global_load_dwordx4 v[46:49], v[46:47], off
	s_waitcnt lgkmcnt(9)
	v_mfma_f32_16x16x32_f16 v[14:17], v[208:211], v[130:133], v[14:17]
	v_mfma_f32_16x16x32_f16 v[10:13], v[212:215], v[130:133], v[10:13]
	v_mfma_f32_16x16x32_f16 v[6:9], v[216:219], v[130:133], v[6:9]
	v_mfma_f32_16x16x32_f16 v[2:5], v[220:223], v[130:133], v[2:5]
	ds_read_b128 v[130:133], v242 offset:4096
	ds_read_b128 v[208:211], v242 offset:6144
	s_waitcnt vmcnt(15)
	ds_write_b128 v169, v[50:53] offset:45056
	v_add_co_u32_e32 v50, vcc, s73, v160
	s_nop 1
	v_addc_co_u32_e32 v51, vcc, 0, v161, vcc
	global_load_dwordx4 v[50:53], v[50:51], off
	s_waitcnt lgkmcnt(6)
	v_mfma_f32_16x16x32_f16 v[126:129], v[244:247], v[200:203], v[126:129]
	v_mfma_f32_16x16x32_f16 v[122:125], v[248:251], v[200:203], v[122:125]
	v_mfma_f32_16x16x32_f16 v[118:121], v[252:255], v[200:203], v[118:121]
	v_mfma_f32_16x16x32_f16 v[114:117], v[196:199], v[200:203], v[114:117]
	s_waitcnt vmcnt(15)
	ds_write_b128 v169, v[38:41] offset:49152
	global_load_dwordx4 v[38:41], v[158:159], off
	v_lshl_add_u64 v[222:223], v[154:155], 0, s[10:11]
	s_waitcnt lgkmcnt(5)
	v_mfma_f32_16x16x32_f16 v[110:113], v[244:247], v[204:207], v[110:113]
	v_lshl_add_u64 v[220:221], v[156:157], 0, s[10:11]
	s_add_i32 s10, s9, 0x80
	s_cmpk_lt_u32 s9, 0x280
	v_mfma_f32_16x16x32_f16 v[106:109], v[248:251], v[204:207], v[106:109]
	s_mov_b32 s9, s10
	v_mfma_f32_16x16x32_f16 v[102:105], v[252:255], v[204:207], v[102:105]
	v_mfma_f32_16x16x32_f16 v[98:101], v[196:199], v[204:207], v[98:101]
	s_waitcnt vmcnt(15)
	ds_write_b128 v169, v[54:57] offset:53248
	v_add_co_u32_e32 v54, vcc, s94, v158
	s_nop 1
	v_addc_co_u32_e32 v55, vcc, 0, v159, vcc
	global_load_dwordx4 v[54:57], v[54:55], off
	s_waitcnt lgkmcnt(4)
	v_mfma_f32_16x16x32_f16 v[30:33], v[244:247], v[130:133], v[30:33]
	v_mfma_f32_16x16x32_f16 v[26:29], v[248:251], v[130:133], v[26:29]
	v_mfma_f32_16x16x32_f16 v[22:25], v[252:255], v[130:133], v[22:25]
	v_mfma_f32_16x16x32_f16 v[18:21], v[196:199], v[130:133], v[18:21]
	s_waitcnt vmcnt(15)
	ds_write_b128 v169, v[62:65] offset:57344
	v_add_co_u32_e32 v62, vcc, s72, v158
	s_nop 1
	v_addc_co_u32_e32 v63, vcc, 0, v159, vcc
	global_load_dwordx4 v[62:65], v[62:63], off
	s_waitcnt lgkmcnt(4)
	v_mfma_f32_16x16x32_f16 v[14:17], v[244:247], v[208:211], v[14:17]
	v_mfma_f32_16x16x32_f16 v[10:13], v[248:251], v[208:211], v[10:13]
	v_mfma_f32_16x16x32_f16 v[6:9], v[252:255], v[208:211], v[6:9]
	v_mfma_f32_16x16x32_f16 v[2:5], v[196:199], v[208:211], v[2:5]
	s_waitcnt vmcnt(15)
	ds_write_b128 v169, v[66:69] offset:61440
	v_add_co_u32_e32 v66, vcc, s73, v158
	s_nop 1
	v_addc_co_u32_e32 v67, vcc, 0, v159, vcc
	global_load_dwordx4 v[66:69], v[66:67], off
	s_waitcnt lgkmcnt(0)
	s_barrier
; template <int NJ>
; __device__ __forceinline__ void gemm_tile(const f16* __restrict__ A, int lda, const f16* __restrict__ Bt, int ldb,
;                                           int K, f32x4 (&acc)[4][NJ], f16* sA, f16* sB, const int tid) {
;     ...
;   G_LOAD(ra0, rb0, 0)
;   if (K > 64) G_LOAD(ra1, rb1, 64)
;   __syncthreads();
;   G_STORE(ra0, rb0, 0)
;   if (K > 128) G_LOAD(ra0, rb0, 128)
;   __syncthreads();
; #pragma unroll 1
;   for (int k0 = 0; k0 < K; k0 += 128) {
;     {
;       const int kof = (k0 + 192 < K) ? k0 + 192 : K - 64;
;       G_STEP(0, ra1, rb1, true, true, kof)
;     }
;     __syncthreads();
;     if (k0 + 64 >= K) break;
;     {
;       const int kof = (k0 + 256 < K) ? k0 + 256 : K - 64;
;       G_STEP(1, ra0, rb0, true, true, kof)
;     }
;     __syncthreads();
	ds_read_b128 v[204:207], v192 offset:49152
	ds_read_b128 v[208:211], v192 offset:51200
	ds_read_b128 v[212:215], v192 offset:53248
	ds_read_b128 v[216:219], v192 offset:55296
	ds_read_b128 v[130:133], v170 offset:32768
	ds_read_b128 v[158:161], v170 offset:34816
	ds_read_b128 v[196:199], v170 offset:36864
	ds_read_b128 v[200:203], v170 offset:38912
	ds_read_b128 v[244:247], v243 offset:49152
	ds_read_b128 v[248:251], v243 offset:51200
	ds_read_b128 v[252:255], v243 offset:53248
	s_waitcnt lgkmcnt(6)
	v_mfma_f32_16x16x32_f16 v[126:129], v[204:207], v[130:133], v[126:129]
	v_mfma_f32_16x16x32_f16 v[122:125], v[208:211], v[130:133], v[122:125]
	v_mfma_f32_16x16x32_f16 v[118:121], v[212:215], v[130:133], v[118:121]
	v_mfma_f32_16x16x32_f16 v[114:117], v[216:219], v[130:133], v[114:117]
	ds_read_b128 v[130:133], v243 offset:55296
	s_waitcnt vmcnt(13)
	ds_write_b128 v169, v[58:61]
	global_load_dwordx4 v[58:61], v[222:223], off
	s_waitcnt lgkmcnt(7)
	v_mfma_f32_16x16x32_f16 v[110:113], v[204:207], v[158:161], v[110:113]
	v_mfma_f32_16x16x32_f16 v[106:109], v[208:211], v[158:161], v[106:109]
	v_mfma_f32_16x16x32_f16 v[102:105], v[212:215], v[158:161], v[102:105]
	v_mfma_f32_16x16x32_f16 v[98:101], v[216:219], v[158:161], v[98:101]
	ds_read_b128 v[158:161], v242 offset:32768
	ds_write_b128 v169, v[74:77] offset:4096
	v_add_co_u32_e32 v74, vcc, s94, v222
	s_nop 1
	v_addc_co_u32_e32 v75, vcc, 0, v223, vcc
	global_load_dwordx4 v[74:77], v[74:75], off
	s_waitcnt lgkmcnt(8)
	v_mfma_f32_16x16x32_f16 v[30:33], v[204:207], v[196:199], v[30:33]
	v_mfma_f32_16x16x32_f16 v[26:29], v[208:211], v[196:199], v[26:29]
	v_mfma_f32_16x16x32_f16 v[22:25], v[212:215], v[196:199], v[22:25]
	v_mfma_f32_16x16x32_f16 v[18:21], v[216:219], v[196:199], v[18:21]
	ds_read_b128 v[196:199], v242 offset:34816
	ds_write_b128 v169, v[78:81] offset:8192
	v_add_co_u32_e32 v78, vcc, s72, v222
	s_nop 1
	v_addc_co_u32_e32 v79, vcc, 0, v223, vcc
	global_load_dwordx4 v[78:81], v[78:79], off
	s_waitcnt lgkmcnt(9)
	v_mfma_f32_16x16x32_f16 v[14:17], v[204:207], v[200:203], v[14:17]
	v_mfma_f32_16x16x32_f16 v[10:13], v[208:211], v[200:203], v[10:13]
	v_mfma_f32_16x16x32_f16 v[6:9], v[212:215], v[200:203], v[6:9]
	v_mfma_f32_16x16x32_f16 v[2:5], v[216:219], v[200:203], v[2:5]
	ds_read_b128 v[200:203], v242 offset:36864
	ds_read_b128 v[204:207], v242 offset:38912
	s_waitcnt vmcnt(14)
	ds_write_b128 v169, v[82:85] offset:12288
	v_add_co_u32_e32 v82, vcc, s73, v222
	s_nop 1
	v_addc_co_u32_e32 v83, vcc, 0, v223, vcc
	global_load_dwordx4 v[82:85], v[82:83], off
	s_waitcnt lgkmcnt(6)
	v_mfma_f32_16x16x32_f16 v[126:129], v[244:247], v[158:161], v[126:129]
	v_mfma_f32_16x16x32_f16 v[122:125], v[248:251], v[158:161], v[122:125]
	v_mfma_f32_16x16x32_f16 v[118:121], v[252:255], v[158:161], v[118:121]
	v_mfma_f32_16x16x32_f16 v[114:117], v[130:133], v[158:161], v[114:117]
	ds_write_b128 v169, v[70:73] offset:16384
	global_load_dwordx4 v[70:73], v[220:221], off
	s_waitcnt lgkmcnt(5)
	v_mfma_f32_16x16x32_f16 v[110:113], v[244:247], v[196:199], v[110:113]
	v_mfma_f32_16x16x32_f16 v[106:109], v[248:251], v[196:199], v[106:109]
	v_mfma_f32_16x16x32_f16 v[102:105], v[252:255], v[196:199], v[102:105]
	v_mfma_f32_16x16x32_f16 v[98:101], v[130:133], v[196:199], v[98:101]
	s_waitcnt vmcnt(15)
	ds_write_b128 v169, v[86:89] offset:20480
	v_add_co_u32_e32 v86, vcc, s94, v220
	s_nop 1
	v_addc_co_u32_e32 v87, vcc, 0, v221, vcc
	global_load_dwordx4 v[86:89], v[86:87], off
	s_waitcnt lgkmcnt(4)
	v_mfma_f32_16x16x32_f16 v[30:33], v[244:247], v[200:203], v[30:33]
	v_mfma_f32_16x16x32_f16 v[26:29], v[248:251], v[200:203], v[26:29]
	v_mfma_f32_16x16x32_f16 v[22:25], v[252:255], v[200:203], v[22:25]
	v_mfma_f32_16x16x32_f16 v[18:21], v[130:133], v[200:203], v[18:21]
	s_waitcnt vmcnt(15)
	ds_write_b128 v169, v[90:93] offset:24576
	v_add_co_u32_e32 v90, vcc, s72, v220
	s_nop 1
	v_addc_co_u32_e32 v91, vcc, 0, v221, vcc
	global_load_dwordx4 v[90:93], v[90:91], off
	s_waitcnt lgkmcnt(4)
	v_mfma_f32_16x16x32_f16 v[14:17], v[244:247], v[204:207], v[14:17]
	v_mfma_f32_16x16x32_f16 v[10:13], v[248:251], v[204:207], v[10:13]
	v_mfma_f32_16x16x32_f16 v[6:9], v[252:255], v[204:207], v[6:9]
	v_mfma_f32_16x16x32_f16 v[2:5], v[130:133], v[204:207], v[2:5]
	s_waitcnt vmcnt(15)
	ds_write_b128 v169, v[94:97] offset:28672
	v_add_co_u32_e32 v94, vcc, s73, v220
	s_nop 1
	v_addc_co_u32_e32 v95, vcc, 0, v221, vcc
	global_load_dwordx4 v[94:97], v[94:95], off
	s_waitcnt lgkmcnt(0)
	s_barrier
	s_cbranch_scc1 .LBB0_1186
; template <int NJ>
; __device__ __forceinline__ void gemm_tile(const f16* __restrict__ A, int lda, const f16* __restrict__ Bt, int ldb,
;                                           int K, f32x4 (&acc)[4][NJ], f16* sA, f16* sB, const int tid) {
;     ...
;   G_LOAD(ra0, rb0, 0)
;   if (K > 64) G_LOAD(ra1, rb1, 64)
;   __syncthreads();
;   G_STORE(ra0, rb0, 0)
;   if (K > 128) G_LOAD(ra0, rb0, 128)
;   __syncthreads();
; #pragma unroll 1
;   for (int k0 = 0; k0 < K; k0 += 128) {
;     {
;       const int kof = (k0 + 192 < K) ? k0 + 192 : K - 64;
;       G_STEP(0, ra1, rb1, true, true, kof)
	ds_read_b128 v[208:211], v192 offset:16384
	ds_read_b128 v[212:215], v192 offset:18432
	ds_read_b128 v[216:219], v192 offset:20480
	ds_read_b128 v[220:223], v192 offset:22528
	s_add_i32 s10, s9, 0xc0
	ds_read_b128 v[196:199], v170
	ds_read_b128 v[200:203], v170 offset:2048
	s_cmpk_lt_u32 s9, 0x340
	s_cselect_b32 s42, s10, 0x3c0
	ds_read_b128 v[204:207], v170 offset:4096
	s_lshl_b64 s[10:11], s[42:43], 1
	v_lshl_add_u64 v[160:161], v[154:155], 0, s[10:11]
	ds_read_b128 v[130:133], v170 offset:6144
	ds_read_b128 v[244:247], v243 offset:16384
	ds_read_b128 v[248:251], v243 offset:18432
	ds_read_b128 v[252:255], v243 offset:20480
	s_waitcnt lgkmcnt(6)
	v_mfma_f32_16x16x32_f16 v[126:129], v[208:211], v[196:199], v[126:129]
	v_lshl_add_u64 v[158:159], v[156:157], 0, s[10:11]
	s_add_i32 s10, s9, 0x100
	s_cmpk_lt_u32 s9, 0x300
	v_mfma_f32_16x16x32_f16 v[122:125], v[212:215], v[196:199], v[122:125]
	s_cselect_b32 s42, s10, 0x3c0
	s_lshl_b64 s[10:11], s[42:43], 1
	v_mfma_f32_16x16x32_f16 v[118:121], v[216:219], v[196:199], v[118:121]
	v_mfma_f32_16x16x32_f16 v[114:117], v[220:223], v[196:199], v[114:117]
	ds_read_b128 v[196:199], v243 offset:22528
	s_waitcnt vmcnt(15)
	ds_write_b128 v169, v[34:37] offset:32768
	global_load_dwordx4 v[34:37], v[160:161], off
	s_waitcnt lgkmcnt(7)
	v_mfma_f32_16x16x32_f16 v[110:113], v[208:211], v[200:203], v[110:113]
	v_mfma_f32_16x16x32_f16 v[106:109], v[212:215], v[200:203], v[106:109]
	v_mfma_f32_16x16x32_f16 v[102:105], v[216:219], v[200:203], v[102:105]
	v_mfma_f32_16x16x32_f16 v[98:101], v[220:223], v[200:203], v[98:101]
	ds_read_b128 v[200:203], v242
	s_waitcnt vmcnt(15)
	ds_write_b128 v169, v[42:45] offset:36864
	v_add_co_u32_e32 v42, vcc, s94, v160
	s_nop 1
	v_addc_co_u32_e32 v43, vcc, 0, v161, vcc
	global_load_dwordx4 v[42:45], v[42:43], off
	s_waitcnt lgkmcnt(8)
	v_mfma_f32_16x16x32_f16 v[30:33], v[208:211], v[204:207], v[30:33]
	v_mfma_f32_16x16x32_f16 v[26:29], v[212:215], v[204:207], v[26:29]
	v_mfma_f32_16x16x32_f16 v[22:25], v[216:219], v[204:207], v[22:25]
	v_mfma_f32_16x16x32_f16 v[18:21], v[220:223], v[204:207], v[18:21]
	ds_read_b128 v[204:207], v242 offset:2048
	s_waitcnt vmcnt(15)
	ds_write_b128 v169, v[46:49] offset:40960
	v_add_co_u32_e32 v46, vcc, s72, v160
	s_nop 1
	v_addc_co_u32_e32 v47, vcc, 0, v161, vcc
	global_load_dwordx4 v[46:49], v[46:47], off
	s_waitcnt lgkmcnt(9)
	v_mfma_f32_16x16x32_f16 v[14:17], v[208:211], v[130:133], v[14:17]
	v_mfma_f32_16x16x32_f16 v[10:13], v[212:215], v[130:133], v[10:13]
	v_mfma_f32_16x16x32_f16 v[6:9], v[216:219], v[130:133], v[6:9]
	v_mfma_f32_16x16x32_f16 v[2:5], v[220:223], v[130:133], v[2:5]
	ds_read_b128 v[130:133], v242 offset:4096
	ds_read_b128 v[208:211], v242 offset:6144
	s_waitcnt vmcnt(15)
	ds_write_b128 v169, v[50:53] offset:45056
	v_add_co_u32_e32 v50, vcc, s73, v160
	s_nop 1
	v_addc_co_u32_e32 v51, vcc, 0, v161, vcc
	global_load_dwordx4 v[50:53], v[50:51], off
	s_waitcnt lgkmcnt(6)
	v_mfma_f32_16x16x32_f16 v[126:129], v[244:247], v[200:203], v[126:129]
	v_mfma_f32_16x16x32_f16 v[122:125], v[248:251], v[200:203], v[122:125]
	v_mfma_f32_16x16x32_f16 v[118:121], v[252:255], v[200:203], v[118:121]
	v_mfma_f32_16x16x32_f16 v[114:117], v[196:199], v[200:203], v[114:117]
	s_waitcnt vmcnt(15)
	ds_write_b128 v169, v[38:41] offset:49152
	global_load_dwordx4 v[38:41], v[158:159], off
	v_lshl_add_u64 v[222:223], v[154:155], 0, s[10:11]
	s_waitcnt lgkmcnt(5)
	v_mfma_f32_16x16x32_f16 v[110:113], v[244:247], v[204:207], v[110:113]
	v_lshl_add_u64 v[220:221], v[156:157], 0, s[10:11]
	s_add_i32 s10, s9, 0x80
	s_cmpk_lt_u32 s9, 0x380
	v_mfma_f32_16x16x32_f16 v[106:109], v[248:251], v[204:207], v[106:109]
	s_mov_b32 s9, s10
	v_mfma_f32_16x16x32_f16 v[102:105], v[252:255], v[204:207], v[102:105]
	v_mfma_f32_16x16x32_f16 v[98:101], v[196:199], v[204:207], v[98:101]
	s_waitcnt vmcnt(15)
	ds_write_b128 v169, v[54:57] offset:53248
	v_add_co_u32_e32 v54, vcc, s94, v158
	s_nop 1
	v_addc_co_u32_e32 v55, vcc, 0, v159, vcc
	global_load_dwordx4 v[54:57], v[54:55], off
	s_waitcnt lgkmcnt(4)
	v_mfma_f32_16x16x32_f16 v[30:33], v[244:247], v[130:133], v[30:33]
	v_mfma_f32_16x16x32_f16 v[26:29], v[248:251], v[130:133], v[26:29]
	v_mfma_f32_16x16x32_f16 v[22:25], v[252:255], v[130:133], v[22:25]
	v_mfma_f32_16x16x32_f16 v[18:21], v[196:199], v[130:133], v[18:21]
	s_waitcnt vmcnt(15)
	ds_write_b128 v169, v[62:65] offset:57344
	v_add_co_u32_e32 v62, vcc, s72, v158
	s_nop 1
	v_addc_co_u32_e32 v63, vcc, 0, v159, vcc
	global_load_dwordx4 v[62:65], v[62:63], off
	s_waitcnt lgkmcnt(4)
	v_mfma_f32_16x16x32_f16 v[14:17], v[244:247], v[208:211], v[14:17]
	v_mfma_f32_16x16x32_f16 v[10:13], v[248:251], v[208:211], v[10:13]
	v_mfma_f32_16x16x32_f16 v[6:9], v[252:255], v[208:211], v[6:9]
	v_mfma_f32_16x16x32_f16 v[2:5], v[196:199], v[208:211], v[2:5]
	s_waitcnt vmcnt(15)
	ds_write_b128 v169, v[66:69] offset:61440
	v_add_co_u32_e32 v66, vcc, s73, v158
	s_nop 1
	v_addc_co_u32_e32 v67, vcc, 0, v159, vcc
	global_load_dwordx4 v[66:69], v[66:67], off
	s_waitcnt lgkmcnt(0)
	s_barrier
; template <int NJ>
; __device__ __forceinline__ void gemm_tile(const f16* __restrict__ A, int lda, const f16* __restrict__ Bt, int ldb,
;                                           int K, f32x4 (&acc)[4][NJ], f16* sA, f16* sB, const int tid) {
;     ...
;   G_LOAD(ra0, rb0, 0)
;   if (K > 64) G_LOAD(ra1, rb1, 64)
;   __syncthreads();
;   G_STORE(ra0, rb0, 0)
;   if (K > 128) G_LOAD(ra0, rb0, 128)
;   __syncthreads();
; #pragma unroll 1
;   for (int k0 = 0; k0 < K; k0 += 128) {
;     {
;       const int kof = (k0 + 192 < K) ? k0 + 192 : K - 64;
;       G_STEP(0, ra1, rb1, true, true, kof)
;     }
;     __syncthreads();
;     if (k0 + 64 >= K) break;
;     {
;       const int kof = (k0 + 256 < K) ? k0 + 256 : K - 64;
;       G_STEP(1, ra0, rb0, true, true, kof)
;     }
;     __syncthreads();
	ds_read_b128 v[204:207], v192 offset:49152
	ds_read_b128 v[208:211], v192 offset:51200
	ds_read_b128 v[212:215], v192 offset:53248
	ds_read_b128 v[216:219], v192 offset:55296
	ds_read_b128 v[130:133], v170 offset:32768
	ds_read_b128 v[158:161], v170 offset:34816
	ds_read_b128 v[196:199], v170 offset:36864
	ds_read_b128 v[200:203], v170 offset:38912
	ds_read_b128 v[244:247], v243 offset:49152
	ds_read_b128 v[248:251], v243 offset:51200
	ds_read_b128 v[252:255], v243 offset:53248
	s_waitcnt lgkmcnt(6)
	v_mfma_f32_16x16x32_f16 v[126:129], v[204:207], v[130:133], v[126:129]
	v_mfma_f32_16x16x32_f16 v[122:125], v[208:211], v[130:133], v[122:125]
	v_mfma_f32_16x16x32_f16 v[118:121], v[212:215], v[130:133], v[118:121]
	v_mfma_f32_16x16x32_f16 v[114:117], v[216:219], v[130:133], v[114:117]
	ds_read_b128 v[130:133], v243 offset:55296
	s_waitcnt vmcnt(15)
	ds_write_b128 v169, v[58:61]
	s_waitcnt lgkmcnt(7)
	v_mfma_f32_16x16x32_f16 v[110:113], v[204:207], v[158:161], v[110:113]
	v_mfma_f32_16x16x32_f16 v[106:109], v[208:211], v[158:161], v[106:109]
	v_mfma_f32_16x16x32_f16 v[102:105], v[212:215], v[158:161], v[102:105]
	v_mfma_f32_16x16x32_f16 v[98:101], v[216:219], v[158:161], v[98:101]
	ds_read_b128 v[158:161], v242 offset:32768
	s_waitcnt vmcnt(14)
	ds_write_b128 v169, v[74:77] offset:4096
	s_waitcnt lgkmcnt(8)
	v_mfma_f32_16x16x32_f16 v[30:33], v[204:207], v[196:199], v[30:33]
	v_mfma_f32_16x16x32_f16 v[26:29], v[208:211], v[196:199], v[26:29]
	v_mfma_f32_16x16x32_f16 v[22:25], v[212:215], v[196:199], v[22:25]
	v_mfma_f32_16x16x32_f16 v[18:21], v[216:219], v[196:199], v[18:21]
	ds_read_b128 v[196:199], v242 offset:34816
	s_waitcnt vmcnt(13)
	ds_write_b128 v169, v[78:81] offset:8192
	s_waitcnt lgkmcnt(9)
	v_mfma_f32_16x16x32_f16 v[14:17], v[204:207], v[200:203], v[14:17]
	v_mfma_f32_16x16x32_f16 v[10:13], v[208:211], v[200:203], v[10:13]
	v_mfma_f32_16x16x32_f16 v[6:9], v[212:215], v[200:203], v[6:9]
	v_mfma_f32_16x16x32_f16 v[2:5], v[216:219], v[200:203], v[2:5]
	ds_read_b128 v[200:203], v242 offset:36864
	ds_read_b128 v[204:207], v242 offset:38912
	s_waitcnt vmcnt(12)
	ds_write_b128 v169, v[82:85] offset:12288
	s_waitcnt lgkmcnt(6)
	v_mfma_f32_16x16x32_f16 v[126:129], v[244:247], v[158:161], v[126:129]
	v_mfma_f32_16x16x32_f16 v[122:125], v[248:251], v[158:161], v[122:125]
	v_mfma_f32_16x16x32_f16 v[118:121], v[252:255], v[158:161], v[118:121]
	v_mfma_f32_16x16x32_f16 v[114:117], v[130:133], v[158:161], v[114:117]
	s_waitcnt vmcnt(11)
	ds_write_b128 v169, v[70:73] offset:16384
	s_waitcnt lgkmcnt(5)
	v_mfma_f32_16x16x32_f16 v[110:113], v[244:247], v[196:199], v[110:113]
	v_mfma_f32_16x16x32_f16 v[106:109], v[248:251], v[196:199], v[106:109]
	v_mfma_f32_16x16x32_f16 v[102:105], v[252:255], v[196:199], v[102:105]
	v_mfma_f32_16x16x32_f16 v[98:101], v[130:133], v[196:199], v[98:101]
	s_waitcnt vmcnt(10)
	ds_write_b128 v169, v[86:89] offset:20480
	s_waitcnt lgkmcnt(4)
	v_mfma_f32_16x16x32_f16 v[30:33], v[244:247], v[200:203], v[30:33]
	v_mfma_f32_16x16x32_f16 v[26:29], v[248:251], v[200:203], v[26:29]
	v_mfma_f32_16x16x32_f16 v[22:25], v[252:255], v[200:203], v[22:25]
	v_mfma_f32_16x16x32_f16 v[18:21], v[130:133], v[200:203], v[18:21]
	s_waitcnt vmcnt(9)
	ds_write_b128 v169, v[90:93] offset:24576
	s_waitcnt lgkmcnt(4)
	v_mfma_f32_16x16x32_f16 v[14:17], v[244:247], v[204:207], v[14:17]
	v_mfma_f32_16x16x32_f16 v[10:13], v[248:251], v[204:207], v[10:13]
	v_mfma_f32_16x16x32_f16 v[6:9], v[252:255], v[204:207], v[6:9]
	v_mfma_f32_16x16x32_f16 v[2:5], v[130:133], v[204:207], v[2:5]
	s_waitcnt vmcnt(8)
	ds_write_b128 v169, v[94:97] offset:28672
	s_waitcnt lgkmcnt(0)
	s_barrier
	ds_read_b128 v[208:211], v192 offset:16384
	ds_read_b128 v[212:215], v192 offset:18432
	ds_read_b128 v[216:219], v192 offset:20480
	ds_read_b128 v[220:223], v192 offset:22528
	s_add_i32 s10, s9, 0xc0
	ds_read_b128 v[196:199], v170
	ds_read_b128 v[200:203], v170 offset:2048
	s_cmpk_lt_u32 s9, 0x340
	s_cselect_b32 s42, s10, 0x3c0
	ds_read_b128 v[204:207], v170 offset:4096
	s_lshl_b64 s[10:11], s[42:43], 1
	v_lshl_add_u64 v[160:161], v[154:155], 0, s[10:11]
	ds_read_b128 v[130:133], v170 offset:6144
	ds_read_b128 v[244:247], v243 offset:16384
	ds_read_b128 v[248:251], v243 offset:18432
	ds_read_b128 v[252:255], v243 offset:20480
	s_waitcnt lgkmcnt(6)
	v_mfma_f32_16x16x32_f16 v[126:129], v[208:211], v[196:199], v[126:129]
	v_lshl_add_u64 v[158:159], v[156:157], 0, s[10:11]
	s_add_i32 s10, s9, 0x100
	s_cmpk_lt_u32 s9, 0x300
	v_mfma_f32_16x16x32_f16 v[122:125], v[212:215], v[196:199], v[122:125]
	s_cselect_b32 s42, s10, 0x3c0
	s_lshl_b64 s[10:11], s[42:43], 1
	v_mfma_f32_16x16x32_f16 v[118:121], v[216:219], v[196:199], v[118:121]
	v_mfma_f32_16x16x32_f16 v[114:117], v[220:223], v[196:199], v[114:117]
	ds_read_b128 v[196:199], v243 offset:22528
	s_waitcnt vmcnt(7)
	ds_write_b128 v169, v[34:37] offset:32768
	s_waitcnt lgkmcnt(7)
	v_mfma_f32_16x16x32_f16 v[110:113], v[208:211], v[200:203], v[110:113]
	v_mfma_f32_16x16x32_f16 v[106:109], v[212:215], v[200:203], v[106:109]
	v_mfma_f32_16x16x32_f16 v[102:105], v[216:219], v[200:203], v[102:105]
	v_mfma_f32_16x16x32_f16 v[98:101], v[220:223], v[200:203], v[98:101]
	ds_read_b128 v[200:203], v242
	s_waitcnt vmcnt(6)
	ds_write_b128 v169, v[42:45] offset:36864
	s_waitcnt lgkmcnt(8)
	v_mfma_f32_16x16x32_f16 v[30:33], v[208:211], v[204:207], v[30:33]
	v_mfma_f32_16x16x32_f16 v[26:29], v[212:215], v[204:207], v[26:29]
	v_mfma_f32_16x16x32_f16 v[22:25], v[216:219], v[204:207], v[22:25]
	v_mfma_f32_16x16x32_f16 v[18:21], v[220:223], v[204:207], v[18:21]
	ds_read_b128 v[204:207], v242 offset:2048
	s_waitcnt vmcnt(5)
	ds_write_b128 v169, v[46:49] offset:40960
	s_waitcnt lgkmcnt(9)
; template <int NJ>
; __device__ __forceinline__ void gemm_tile(const f16* __restrict__ A, int lda, const f16* __restrict__ Bt, int ldb,
;                                           int K, f32x4 (&acc)[4][NJ], f16* sA, f16* sB, const int tid) {
;     ...
;   G_LOAD(ra0, rb0, 0)
;   if (K > 64) G_LOAD(ra1, rb1, 64)
;   __syncthreads();
;   G_STORE(ra0, rb0, 0)
;   if (K > 128) G_LOAD(ra0, rb0, 128)
;   __syncthreads();
; #pragma unroll 1
;   for (int k0 = 0; k0 < K; k0 += 128) {
;     {
;       const int kof = (k0 + 192 < K) ? k0 + 192 : K - 64;
;       G_STEP(0, ra1, rb1, true, true, kof)
;     }
;     __syncthreads();
;     if (k0 + 64 >= K) break;
;     {
;       const int kof = (k0 + 256 < K) ? k0 + 256 : K - 64;
;       G_STEP(1, ra0, rb0, true, true, kof)
;     }
;     __syncthreads();
; template <int NJ>
; __device__ __forceinline__ void gres_tile(const Params& p, const f16* A, int lda, const f16* W, int K, const float* mod,
;                                           bool first_in, f16* sA, f16* sB, int m0, int n0) {
;     ...
; #pragma unroll
;   for (int i = 0; i < 4; ++i) {
;     int m = m0 + wm * 64 + i * 16 + (lane & 15);
;     const float* xi = xrow_in(p, first_in ? 0 : 1, m);
;     float* xo = xrow_out(p, m);
;     const float* gt = mod + (size_t)modrow_of(m) * 6 * DM;
	v_mfma_f32_16x16x32_f16 v[14:17], v[208:211], v[130:133], v[14:17]
	v_mfma_f32_16x16x32_f16 v[10:13], v[212:215], v[130:133], v[10:13]
	v_mfma_f32_16x16x32_f16 v[6:9], v[216:219], v[130:133], v[6:9]
	v_mfma_f32_16x16x32_f16 v[2:5], v[220:223], v[130:133], v[2:5]
	ds_read_b128 v[130:133], v242 offset:4096
	ds_read_b128 v[208:211], v242 offset:6144
	s_waitcnt vmcnt(4)
	ds_write_b128 v169, v[50:53] offset:45056
	s_waitcnt lgkmcnt(6)
	v_mfma_f32_16x16x32_f16 v[126:129], v[244:247], v[200:203], v[126:129]
	v_mfma_f32_16x16x32_f16 v[122:125], v[248:251], v[200:203], v[122:125]
	v_mfma_f32_16x16x32_f16 v[118:121], v[252:255], v[200:203], v[118:121]
	v_mfma_f32_16x16x32_f16 v[114:117], v[196:199], v[200:203], v[114:117]
	s_waitcnt vmcnt(3)
	ds_write_b128 v169, v[38:41] offset:49152
	v_lshl_add_u64 v[222:223], v[154:155], 0, s[10:11]
	s_waitcnt lgkmcnt(5)
	v_mfma_f32_16x16x32_f16 v[110:113], v[244:247], v[204:207], v[110:113]
	v_lshl_add_u64 v[220:221], v[156:157], 0, s[10:11]
	s_add_i32 s10, s9, 0x80
	s_cmpk_lt_u32 s9, 0x380
	v_mfma_f32_16x16x32_f16 v[106:109], v[248:251], v[204:207], v[106:109]
	s_mov_b32 s9, s10
	v_mfma_f32_16x16x32_f16 v[102:105], v[252:255], v[204:207], v[102:105]
	v_mfma_f32_16x16x32_f16 v[98:101], v[196:199], v[204:207], v[98:101]
	s_waitcnt vmcnt(2)
	ds_write_b128 v169, v[54:57] offset:53248
	s_waitcnt lgkmcnt(4)
	v_mfma_f32_16x16x32_f16 v[30:33], v[244:247], v[130:133], v[30:33]
	v_mfma_f32_16x16x32_f16 v[26:29], v[248:251], v[130:133], v[26:29]
	v_mfma_f32_16x16x32_f16 v[22:25], v[252:255], v[130:133], v[22:25]
	v_mfma_f32_16x16x32_f16 v[18:21], v[196:199], v[130:133], v[18:21]
	s_waitcnt vmcnt(1)
	ds_write_b128 v169, v[62:65] offset:57344
	s_waitcnt lgkmcnt(4)
	v_mfma_f32_16x16x32_f16 v[14:17], v[244:247], v[208:211], v[14:17]
	v_mfma_f32_16x16x32_f16 v[10:13], v[248:251], v[208:211], v[10:13]
	v_mfma_f32_16x16x32_f16 v[6:9], v[252:255], v[208:211], v[6:9]
	v_mfma_f32_16x16x32_f16 v[2:5], v[196:199], v[208:211], v[2:5]
	s_waitcnt vmcnt(0)
	ds_write_b128 v169, v[66:69] offset:61440
	s_waitcnt lgkmcnt(0)
	s_barrier
	ds_read_b128 v[204:207], v192 offset:49152
	ds_read_b128 v[208:211], v192 offset:51200
	ds_read_b128 v[212:215], v192 offset:53248
	ds_read_b128 v[216:219], v192 offset:55296
	ds_read_b128 v[130:133], v170 offset:32768
	ds_read_b128 v[158:161], v170 offset:34816
	ds_read_b128 v[196:199], v170 offset:36864
	ds_read_b128 v[200:203], v170 offset:38912
	ds_read_b128 v[244:247], v243 offset:49152
	ds_read_b128 v[248:251], v243 offset:51200
	ds_read_b128 v[252:255], v243 offset:53248
	s_waitcnt lgkmcnt(6)
	v_mfma_f32_16x16x32_f16 v[126:129], v[204:207], v[130:133], v[126:129]
	v_mfma_f32_16x16x32_f16 v[122:125], v[208:211], v[130:133], v[122:125]
	v_mfma_f32_16x16x32_f16 v[118:121], v[212:215], v[130:133], v[118:121]
	v_mfma_f32_16x16x32_f16 v[114:117], v[216:219], v[130:133], v[114:117]
	ds_read_b128 v[130:133], v243 offset:55296
	s_waitcnt lgkmcnt(6)
	v_mfma_f32_16x16x32_f16 v[110:113], v[204:207], v[158:161], v[110:113]
	v_mfma_f32_16x16x32_f16 v[106:109], v[208:211], v[158:161], v[106:109]
	v_mfma_f32_16x16x32_f16 v[102:105], v[212:215], v[158:161], v[102:105]
	v_mfma_f32_16x16x32_f16 v[98:101], v[216:219], v[158:161], v[98:101]
	ds_read_b128 v[158:161], v242 offset:32768
	s_waitcnt lgkmcnt(6)
	v_mfma_f32_16x16x32_f16 v[30:33], v[204:207], v[196:199], v[30:33]
	v_mfma_f32_16x16x32_f16 v[26:29], v[208:211], v[196:199], v[26:29]
	v_mfma_f32_16x16x32_f16 v[22:25], v[212:215], v[196:199], v[22:25]
	v_mfma_f32_16x16x32_f16 v[18:21], v[216:219], v[196:199], v[18:21]
	ds_read_b128 v[196:199], v242 offset:34816
	s_waitcnt lgkmcnt(6)
	v_mfma_f32_16x16x32_f16 v[14:17], v[204:207], v[200:203], v[14:17]
	v_mfma_f32_16x16x32_f16 v[10:13], v[208:211], v[200:203], v[10:13]
	v_mfma_f32_16x16x32_f16 v[6:9], v[212:215], v[200:203], v[6:9]
	v_mfma_f32_16x16x32_f16 v[2:5], v[216:219], v[200:203], v[2:5]
	ds_read_b128 v[200:203], v242 offset:36864
	ds_read_b128 v[204:207], v242 offset:38912
	s_waitcnt lgkmcnt(3)
	v_mfma_f32_16x16x32_f16 v[126:129], v[244:247], v[158:161], v[126:129]
	v_mfma_f32_16x16x32_f16 v[122:125], v[248:251], v[158:161], v[122:125]
	v_mfma_f32_16x16x32_f16 v[118:121], v[252:255], v[158:161], v[118:121]
	v_mfma_f32_16x16x32_f16 v[114:117], v[130:133], v[158:161], v[114:117]
	s_waitcnt lgkmcnt(2)
	v_mfma_f32_16x16x32_f16 v[110:113], v[244:247], v[196:199], v[110:113]
	v_mfma_f32_16x16x32_f16 v[106:109], v[248:251], v[196:199], v[106:109]
	v_mfma_f32_16x16x32_f16 v[102:105], v[252:255], v[196:199], v[102:105]
	v_mfma_f32_16x16x32_f16 v[98:101], v[130:133], v[196:199], v[98:101]
	s_waitcnt lgkmcnt(1)
	v_mfma_f32_16x16x32_f16 v[30:33], v[244:247], v[200:203], v[30:33]
	v_mfma_f32_16x16x32_f16 v[26:29], v[248:251], v[200:203], v[26:29]
	v_mfma_f32_16x16x32_f16 v[22:25], v[252:255], v[200:203], v[22:25]
	v_mfma_f32_16x16x32_f16 v[18:21], v[130:133], v[200:203], v[18:21]
	s_waitcnt lgkmcnt(0)
	v_mfma_f32_16x16x32_f16 v[14:17], v[244:247], v[204:207], v[14:17]
	v_mfma_f32_16x16x32_f16 v[10:13], v[248:251], v[204:207], v[10:13]
	v_mfma_f32_16x16x32_f16 v[6:9], v[252:255], v[204:207], v[6:9]
	v_mfma_f32_16x16x32_f16 v[2:5], v[130:133], v[204:207], v[2:5]
	s_waitcnt lgkmcnt(0)
	s_waitcnt vmcnt(15)
	v_or_b32_e32 v34, s8, v162
	v_add_u32_e32 v34, v34, v147
	v_cmp_gt_i32_e64 s[8:9], s80, v34
	v_cmp_lt_i32_e64 s[10:11], s82, v34
	s_mov_b64 s[14:15], -1
	s_and_b64 vcc, exec, s[30:31]
	s_cbranch_vccz .LBB0_1193
	v_mov_b64_e32 v[36:37], v[0:1]
	s_and_saveexec_b64 s[14:15], s[10:11]
	s_xor_b64 s[14:15], exec, s[14:15]
	s_cbranch_execz .LBB0_1190
	v_add_u32_e32 v164, 0xffff8000, v34
	v_mov_b64_e32 v[36:37], v[152:153]
	s_waitcnt vmcnt(11)
	v_mov_b64_e32 v[38:39], v[164:165]

; template <int NJ>
; __device__ __forceinline__ void gemm_tile(const f16* __restrict__ A, int lda, const f16* __restrict__ Bt, int ldb,
;                                           int K, f32x4 (&acc)[4][NJ], f16* sA, f16* sB, const int tid) {
;     ...
;   G_LOAD(ra0, rb0, 0)
;   if (K > 64) G_LOAD(ra1, rb1, 64)
;   __syncthreads();
;   G_STORE(ra0, rb0, 0)
;   if (K > 128) G_LOAD(ra0, rb0, 128)
;   __syncthreads();
; #pragma unroll 1
;   for (int k0 = 0; k0 < K; k0 += 128) {
;     {
;       const int kof = (k0 + 192 < K) ? k0 + 192 : K - 64;
;       G_STEP(0, ra1, rb1, true, true, kof)
.LBB0_1398:
	ds_read_b128 v[166:169], v148 offset:16384
	ds_read_b128 v[192:195], v148 offset:18432
	ds_read_b128 v[196:199], v148 offset:20480
	ds_read_b128 v[200:203], v148 offset:22528
	s_add_i32 s13, s11, 0xc0
	ds_read_b128 v[152:155], v150
	ds_read_b128 v[156:159], v150 offset:2048
	s_cmpk_lt_u32 s11, 0x340
	s_cselect_b32 s42, s13, 0x3c0
	ds_read_b128 v[160:163], v150 offset:4096
	s_lshl_b64 s[14:15], s[42:43], 1
	v_lshl_add_u64 v[144:145], v[138:139], 0, s[14:15]
	ds_read_b128 v[128:131], v150 offset:6144
	ds_read_b128 v[244:247], v243 offset:16384
	ds_read_b128 v[248:251], v243 offset:18432
	ds_read_b128 v[252:255], v243 offset:20480
	s_waitcnt lgkmcnt(6)
	v_mfma_f32_16x16x32_f16 v[124:127], v[166:169], v[152:155], v[124:127]
	v_lshl_add_u64 v[142:143], v[140:141], 0, s[14:15]
	s_add_i32 s13, s11, 0x100
	s_cmpk_lt_u32 s11, 0x300
	v_mfma_f32_16x16x32_f16 v[116:119], v[192:195], v[152:155], v[116:119]
	s_cselect_b32 s42, s13, 0x3c0
	s_lshl_b64 s[14:15], s[42:43], 1
	s_add_i32 s13, s11, 0x80
	v_mfma_f32_16x16x32_f16 v[120:123], v[196:199], v[152:155], v[120:123]
	s_cmpk_lt_u32 s11, 0x280
	s_mov_b32 s11, s13
	v_mfma_f32_16x16x32_f16 v[112:115], v[200:203], v[152:155], v[112:115]
	ds_read_b128 v[152:155], v243 offset:22528
	s_waitcnt vmcnt(15)
	ds_write_b128 v147, v[40:43] offset:32768
	global_load_dwordx4 v[40:43], v[144:145], off
	s_waitcnt lgkmcnt(7)
	v_mfma_f32_16x16x32_f16 v[108:111], v[166:169], v[156:159], v[108:111]
	v_mfma_f32_16x16x32_f16 v[36:39], v[192:195], v[156:159], v[36:39]
	v_mfma_f32_16x16x32_f16 v[104:107], v[196:199], v[156:159], v[104:107]
	v_mfma_f32_16x16x32_f16 v[32:35], v[200:203], v[156:159], v[32:35]
	ds_read_b128 v[156:159], v242
	s_waitcnt vmcnt(14)
	ds_write_b128 v147, v[48:51] offset:36864
	v_add_co_u32_e32 v48, vcc, s94, v144
	s_nop 1
	v_addc_co_u32_e32 v49, vcc, 0, v145, vcc
	global_load_dwordx4 v[48:51], v[48:49], off
	s_waitcnt lgkmcnt(8)
	v_mfma_f32_16x16x32_f16 v[28:31], v[166:169], v[160:163], v[28:31]
	v_mfma_f32_16x16x32_f16 v[20:23], v[192:195], v[160:163], v[20:23]
	v_mfma_f32_16x16x32_f16 v[24:27], v[196:199], v[160:163], v[24:27]
	v_mfma_f32_16x16x32_f16 v[16:19], v[200:203], v[160:163], v[16:19]
	ds_read_b128 v[160:163], v242 offset:2048
	s_waitcnt vmcnt(14)
	ds_write_b128 v147, v[52:55] offset:40960
	v_add_co_u32_e32 v52, vcc, s72, v144
	s_nop 1
	v_addc_co_u32_e32 v53, vcc, 0, v145, vcc
	global_load_dwordx4 v[52:55], v[52:53], off
	s_waitcnt lgkmcnt(9)
	v_mfma_f32_16x16x32_f16 v[12:15], v[166:169], v[128:131], v[12:15]
	v_mfma_f32_16x16x32_f16 v[4:7], v[192:195], v[128:131], v[4:7]
	v_mfma_f32_16x16x32_f16 v[8:11], v[196:199], v[128:131], v[8:11]
	v_mfma_f32_16x16x32_f16 v[0:3], v[200:203], v[128:131], v[0:3]
	ds_read_b128 v[128:131], v242 offset:4096
	ds_read_b128 v[166:169], v242 offset:6144
	s_waitcnt vmcnt(14)
	ds_write_b128 v147, v[56:59] offset:45056
	v_add_co_u32_e32 v56, vcc, s73, v144
	s_nop 1
	v_addc_co_u32_e32 v57, vcc, 0, v145, vcc
	global_load_dwordx4 v[56:59], v[56:57], off
	s_waitcnt lgkmcnt(6)
	v_mfma_f32_16x16x32_f16 v[124:127], v[244:247], v[156:159], v[124:127]
	v_mfma_f32_16x16x32_f16 v[116:119], v[248:251], v[156:159], v[116:119]
	v_mfma_f32_16x16x32_f16 v[120:123], v[252:255], v[156:159], v[120:123]
	v_mfma_f32_16x16x32_f16 v[112:115], v[152:155], v[156:159], v[112:115]
	ds_write_b128 v147, v[44:47] offset:49152
	global_load_dwordx4 v[44:47], v[142:143], off
	v_lshl_add_u64 v[202:203], v[138:139], 0, s[14:15]
	s_waitcnt lgkmcnt(5)
	v_mfma_f32_16x16x32_f16 v[108:111], v[244:247], v[160:163], v[108:111]
	v_lshl_add_u64 v[200:201], v[140:141], 0, s[14:15]
	v_mfma_f32_16x16x32_f16 v[36:39], v[248:251], v[160:163], v[36:39]
	v_mfma_f32_16x16x32_f16 v[104:107], v[252:255], v[160:163], v[104:107]
	v_mfma_f32_16x16x32_f16 v[32:35], v[152:155], v[160:163], v[32:35]
	s_waitcnt vmcnt(15)
	ds_write_b128 v147, v[60:63] offset:53248
	v_add_co_u32_e32 v60, vcc, s94, v142
	s_nop 1
	v_addc_co_u32_e32 v61, vcc, 0, v143, vcc
	global_load_dwordx4 v[60:63], v[60:61], off
	s_waitcnt lgkmcnt(4)
	v_mfma_f32_16x16x32_f16 v[28:31], v[244:247], v[128:131], v[28:31]
	v_mfma_f32_16x16x32_f16 v[20:23], v[248:251], v[128:131], v[20:23]
	v_mfma_f32_16x16x32_f16 v[24:27], v[252:255], v[128:131], v[24:27]
	v_mfma_f32_16x16x32_f16 v[16:19], v[152:155], v[128:131], v[16:19]
	s_waitcnt vmcnt(15)
	ds_write_b128 v147, v[68:71] offset:57344
	v_add_co_u32_e32 v68, vcc, s72, v142
	s_nop 1
	v_addc_co_u32_e32 v69, vcc, 0, v143, vcc
	global_load_dwordx4 v[68:71], v[68:69], off
	s_waitcnt lgkmcnt(4)
	v_mfma_f32_16x16x32_f16 v[12:15], v[244:247], v[166:169], v[12:15]
	v_mfma_f32_16x16x32_f16 v[4:7], v[248:251], v[166:169], v[4:7]
	v_mfma_f32_16x16x32_f16 v[8:11], v[252:255], v[166:169], v[8:11]
	v_mfma_f32_16x16x32_f16 v[0:3], v[152:155], v[166:169], v[0:3]
	s_waitcnt vmcnt(15)
	ds_write_b128 v147, v[72:75] offset:61440
	v_add_co_u32_e32 v72, vcc, s73, v142
	s_nop 1
	v_addc_co_u32_e32 v73, vcc, 0, v143, vcc
	global_load_dwordx4 v[72:75], v[72:73], off
	s_waitcnt lgkmcnt(0)
	s_barrier
; template <int NJ>
; __device__ __forceinline__ void gemm_tile(const f16* __restrict__ A, int lda, const f16* __restrict__ Bt, int ldb,
;                                           int K, f32x4 (&acc)[4][NJ], f16* sA, f16* sB, const int tid) {
;     ...
;   G_LOAD(ra0, rb0, 0)
;   if (K > 64) G_LOAD(ra1, rb1, 64)
;   __syncthreads();
;   G_STORE(ra0, rb0, 0)
;   if (K > 128) G_LOAD(ra0, rb0, 128)
;   __syncthreads();
; #pragma unroll 1
;   for (int k0 = 0; k0 < K; k0 += 128) {
;     {
;       const int kof = (k0 + 192 < K) ? k0 + 192 : K - 64;
;       G_STEP(0, ra1, rb1, true, true, kof)
;     }
;     __syncthreads();
;     if (k0 + 64 >= K) break;
;     {
;       const int kof = (k0 + 256 < K) ? k0 + 256 : K - 64;
;       G_STEP(1, ra0, rb0, true, true, kof)
;     }
;     __syncthreads();
	ds_read_b128 v[160:163], v148 offset:49152
	ds_read_b128 v[166:169], v148 offset:51200
	ds_read_b128 v[192:195], v148 offset:53248
	ds_read_b128 v[196:199], v148 offset:55296
	ds_read_b128 v[128:131], v150 offset:32768
	ds_read_b128 v[142:145], v150 offset:34816
	ds_read_b128 v[152:155], v150 offset:36864
	ds_read_b128 v[156:159], v150 offset:38912
	ds_read_b128 v[244:247], v243 offset:49152
	ds_read_b128 v[248:251], v243 offset:51200
	ds_read_b128 v[252:255], v243 offset:53248
	s_waitcnt lgkmcnt(6)
	v_mfma_f32_16x16x32_f16 v[124:127], v[160:163], v[128:131], v[124:127]
	v_mfma_f32_16x16x32_f16 v[116:119], v[166:169], v[128:131], v[116:119]
	v_mfma_f32_16x16x32_f16 v[120:123], v[192:195], v[128:131], v[120:123]
	v_mfma_f32_16x16x32_f16 v[112:115], v[196:199], v[128:131], v[112:115]
	ds_read_b128 v[128:131], v243 offset:55296
	s_waitcnt vmcnt(13)
	ds_write_b128 v147, v[64:67]
	global_load_dwordx4 v[64:67], v[202:203], off
	s_waitcnt lgkmcnt(7)
	v_mfma_f32_16x16x32_f16 v[108:111], v[160:163], v[142:145], v[108:111]
	v_mfma_f32_16x16x32_f16 v[36:39], v[166:169], v[142:145], v[36:39]
	v_mfma_f32_16x16x32_f16 v[104:107], v[192:195], v[142:145], v[104:107]
	v_mfma_f32_16x16x32_f16 v[32:35], v[196:199], v[142:145], v[32:35]
	ds_read_b128 v[142:145], v242 offset:32768
	ds_write_b128 v147, v[80:83] offset:4096
	v_add_co_u32_e32 v80, vcc, s94, v202
	s_nop 1
	v_addc_co_u32_e32 v81, vcc, 0, v203, vcc
	global_load_dwordx4 v[80:83], v[80:81], off
	s_waitcnt lgkmcnt(8)
	v_mfma_f32_16x16x32_f16 v[28:31], v[160:163], v[152:155], v[28:31]
	v_mfma_f32_16x16x32_f16 v[20:23], v[166:169], v[152:155], v[20:23]
	v_mfma_f32_16x16x32_f16 v[24:27], v[192:195], v[152:155], v[24:27]
	v_mfma_f32_16x16x32_f16 v[16:19], v[196:199], v[152:155], v[16:19]
	ds_read_b128 v[152:155], v242 offset:34816
	ds_write_b128 v147, v[84:87] offset:8192
	v_add_co_u32_e32 v84, vcc, s72, v202
	s_nop 1
	v_addc_co_u32_e32 v85, vcc, 0, v203, vcc
	global_load_dwordx4 v[84:87], v[84:85], off
	s_waitcnt lgkmcnt(9)
	v_mfma_f32_16x16x32_f16 v[12:15], v[160:163], v[156:159], v[12:15]
	v_mfma_f32_16x16x32_f16 v[4:7], v[166:169], v[156:159], v[4:7]
	v_mfma_f32_16x16x32_f16 v[8:11], v[192:195], v[156:159], v[8:11]
	v_mfma_f32_16x16x32_f16 v[0:3], v[196:199], v[156:159], v[0:3]
	ds_read_b128 v[156:159], v242 offset:36864
	ds_read_b128 v[160:163], v242 offset:38912
	s_waitcnt vmcnt(14)
	ds_write_b128 v147, v[88:91] offset:12288
	v_add_co_u32_e32 v88, vcc, s73, v202
	s_nop 1
	v_addc_co_u32_e32 v89, vcc, 0, v203, vcc
	global_load_dwordx4 v[88:91], v[88:89], off
	s_waitcnt lgkmcnt(6)
	v_mfma_f32_16x16x32_f16 v[124:127], v[244:247], v[142:145], v[124:127]
	v_mfma_f32_16x16x32_f16 v[116:119], v[248:251], v[142:145], v[116:119]
	v_mfma_f32_16x16x32_f16 v[120:123], v[252:255], v[142:145], v[120:123]
	v_mfma_f32_16x16x32_f16 v[112:115], v[128:131], v[142:145], v[112:115]
	ds_write_b128 v147, v[76:79] offset:16384
	global_load_dwordx4 v[76:79], v[200:201], off
	s_waitcnt lgkmcnt(5)
	v_mfma_f32_16x16x32_f16 v[108:111], v[244:247], v[152:155], v[108:111]
	v_mfma_f32_16x16x32_f16 v[36:39], v[248:251], v[152:155], v[36:39]
	v_mfma_f32_16x16x32_f16 v[104:107], v[252:255], v[152:155], v[104:107]
	v_mfma_f32_16x16x32_f16 v[32:35], v[128:131], v[152:155], v[32:35]
	s_waitcnt vmcnt(15)
	ds_write_b128 v147, v[92:95] offset:20480
	v_add_co_u32_e32 v92, vcc, s94, v200
	s_nop 1
	v_addc_co_u32_e32 v93, vcc, 0, v201, vcc
	global_load_dwordx4 v[92:95], v[92:93], off
	s_waitcnt lgkmcnt(4)
	v_mfma_f32_16x16x32_f16 v[28:31], v[244:247], v[156:159], v[28:31]
	v_mfma_f32_16x16x32_f16 v[20:23], v[248:251], v[156:159], v[20:23]
	v_mfma_f32_16x16x32_f16 v[24:27], v[252:255], v[156:159], v[24:27]
	v_mfma_f32_16x16x32_f16 v[16:19], v[128:131], v[156:159], v[16:19]
	s_waitcnt vmcnt(15)
	ds_write_b128 v147, v[96:99] offset:24576
	v_add_co_u32_e32 v96, vcc, s72, v200
	s_nop 1
	v_addc_co_u32_e32 v97, vcc, 0, v201, vcc
	global_load_dwordx4 v[96:99], v[96:97], off
	s_waitcnt lgkmcnt(4)
	v_mfma_f32_16x16x32_f16 v[12:15], v[244:247], v[160:163], v[12:15]
	v_mfma_f32_16x16x32_f16 v[4:7], v[248:251], v[160:163], v[4:7]
	v_mfma_f32_16x16x32_f16 v[8:11], v[252:255], v[160:163], v[8:11]
	v_mfma_f32_16x16x32_f16 v[0:3], v[128:131], v[160:163], v[0:3]
	s_waitcnt vmcnt(15)
	ds_write_b128 v147, v[100:103] offset:28672
	v_add_co_u32_e32 v100, vcc, s73, v200
	s_nop 1
	v_addc_co_u32_e32 v101, vcc, 0, v201, vcc
	global_load_dwordx4 v[100:103], v[100:101], off
	s_waitcnt lgkmcnt(0)
	s_barrier
	s_cbranch_scc1 .LBB0_1398
; template <int NJ>
; __device__ __forceinline__ void gemm_tile(const f16* __restrict__ A, int lda, const f16* __restrict__ Bt, int ldb,
;                                           int K, f32x4 (&acc)[4][NJ], f16* sA, f16* sB, const int tid) {
;     ...
;   G_LOAD(ra0, rb0, 0)
;   if (K > 64) G_LOAD(ra1, rb1, 64)
;   __syncthreads();
;   G_STORE(ra0, rb0, 0)
;   if (K > 128) G_LOAD(ra0, rb0, 128)
;   __syncthreads();
; #pragma unroll 1
;   for (int k0 = 0; k0 < K; k0 += 128) {
;     {
;       const int kof = (k0 + 192 < K) ? k0 + 192 : K - 64;
;       G_STEP(0, ra1, rb1, true, true, kof)
	ds_read_b128 v[166:169], v148 offset:16384
	ds_read_b128 v[192:195], v148 offset:18432
	ds_read_b128 v[196:199], v148 offset:20480
	ds_read_b128 v[200:203], v148 offset:22528
	s_add_i32 s13, s11, 0xc0
	ds_read_b128 v[152:155], v150
	ds_read_b128 v[156:159], v150 offset:2048
	s_cmpk_lt_u32 s11, 0x340
	s_cselect_b32 s42, s13, 0x3c0
	ds_read_b128 v[160:163], v150 offset:4096
	s_lshl_b64 s[14:15], s[42:43], 1
	v_lshl_add_u64 v[144:145], v[138:139], 0, s[14:15]
	ds_read_b128 v[128:131], v150 offset:6144
	ds_read_b128 v[244:247], v243 offset:16384
	ds_read_b128 v[248:251], v243 offset:18432
	ds_read_b128 v[252:255], v243 offset:20480
	s_waitcnt lgkmcnt(6)
	v_mfma_f32_16x16x32_f16 v[124:127], v[166:169], v[152:155], v[124:127]
	v_lshl_add_u64 v[142:143], v[140:141], 0, s[14:15]
	s_add_i32 s13, s11, 0x100
	s_cmpk_lt_u32 s11, 0x300
	v_mfma_f32_16x16x32_f16 v[116:119], v[192:195], v[152:155], v[116:119]
	s_cselect_b32 s42, s13, 0x3c0
	s_lshl_b64 s[14:15], s[42:43], 1
	s_add_i32 s13, s11, 0x80
	v_mfma_f32_16x16x32_f16 v[120:123], v[196:199], v[152:155], v[120:123]
	s_cmpk_lt_u32 s11, 0x380
	s_mov_b32 s11, s13
	v_mfma_f32_16x16x32_f16 v[112:115], v[200:203], v[152:155], v[112:115]
	ds_read_b128 v[152:155], v243 offset:22528
	s_waitcnt vmcnt(15)
	ds_write_b128 v147, v[40:43] offset:32768
	global_load_dwordx4 v[40:43], v[144:145], off
	s_waitcnt lgkmcnt(7)
	v_mfma_f32_16x16x32_f16 v[108:111], v[166:169], v[156:159], v[108:111]
	v_mfma_f32_16x16x32_f16 v[36:39], v[192:195], v[156:159], v[36:39]
	v_mfma_f32_16x16x32_f16 v[104:107], v[196:199], v[156:159], v[104:107]
	v_mfma_f32_16x16x32_f16 v[32:35], v[200:203], v[156:159], v[32:35]
	ds_read_b128 v[156:159], v242
	s_waitcnt vmcnt(15)
	ds_write_b128 v147, v[48:51] offset:36864
	v_add_co_u32_e32 v48, vcc, s94, v144
	s_nop 1
	v_addc_co_u32_e32 v49, vcc, 0, v145, vcc
	global_load_dwordx4 v[48:51], v[48:49], off
	s_waitcnt lgkmcnt(8)
	v_mfma_f32_16x16x32_f16 v[28:31], v[166:169], v[160:163], v[28:31]
	v_mfma_f32_16x16x32_f16 v[20:23], v[192:195], v[160:163], v[20:23]
	v_mfma_f32_16x16x32_f16 v[24:27], v[196:199], v[160:163], v[24:27]
	v_mfma_f32_16x16x32_f16 v[16:19], v[200:203], v[160:163], v[16:19]
	ds_read_b128 v[160:163], v242 offset:2048
	s_waitcnt vmcnt(15)
	ds_write_b128 v147, v[52:55] offset:40960
	v_add_co_u32_e32 v52, vcc, s72, v144
	s_nop 1
	v_addc_co_u32_e32 v53, vcc, 0, v145, vcc
	global_load_dwordx4 v[52:55], v[52:53], off
	s_waitcnt lgkmcnt(9)
	v_mfma_f32_16x16x32_f16 v[12:15], v[166:169], v[128:131], v[12:15]
	v_mfma_f32_16x16x32_f16 v[4:7], v[192:195], v[128:131], v[4:7]
	v_mfma_f32_16x16x32_f16 v[8:11], v[196:199], v[128:131], v[8:11]
	v_mfma_f32_16x16x32_f16 v[0:3], v[200:203], v[128:131], v[0:3]
	ds_read_b128 v[128:131], v242 offset:4096
	ds_read_b128 v[166:169], v242 offset:6144
	s_waitcnt vmcnt(15)
	ds_write_b128 v147, v[56:59] offset:45056
	v_add_co_u32_e32 v56, vcc, s73, v144
	s_nop 1
	v_addc_co_u32_e32 v57, vcc, 0, v145, vcc
	global_load_dwordx4 v[56:59], v[56:57], off
	s_waitcnt lgkmcnt(6)
	v_mfma_f32_16x16x32_f16 v[124:127], v[244:247], v[156:159], v[124:127]
	v_mfma_f32_16x16x32_f16 v[116:119], v[248:251], v[156:159], v[116:119]
	v_mfma_f32_16x16x32_f16 v[120:123], v[252:255], v[156:159], v[120:123]
	v_mfma_f32_16x16x32_f16 v[112:115], v[152:155], v[156:159], v[112:115]
	s_waitcnt vmcnt(15)
	ds_write_b128 v147, v[44:47] offset:49152
	global_load_dwordx4 v[44:47], v[142:143], off
	v_lshl_add_u64 v[202:203], v[138:139], 0, s[14:15]
	s_waitcnt lgkmcnt(5)
	v_mfma_f32_16x16x32_f16 v[108:111], v[244:247], v[160:163], v[108:111]
	v_lshl_add_u64 v[200:201], v[140:141], 0, s[14:15]
	v_mfma_f32_16x16x32_f16 v[36:39], v[248:251], v[160:163], v[36:39]
	v_mfma_f32_16x16x32_f16 v[104:107], v[252:255], v[160:163], v[104:107]
	v_mfma_f32_16x16x32_f16 v[32:35], v[152:155], v[160:163], v[32:35]
	s_waitcnt vmcnt(15)
	ds_write_b128 v147, v[60:63] offset:53248
	v_add_co_u32_e32 v60, vcc, s94, v142
	s_nop 1
	v_addc_co_u32_e32 v61, vcc, 0, v143, vcc
	global_load_dwordx4 v[60:63], v[60:61], off
	s_waitcnt lgkmcnt(4)
	v_mfma_f32_16x16x32_f16 v[28:31], v[244:247], v[128:131], v[28:31]
	v_mfma_f32_16x16x32_f16 v[20:23], v[248:251], v[128:131], v[20:23]
	v_mfma_f32_16x16x32_f16 v[24:27], v[252:255], v[128:131], v[24:27]
	v_mfma_f32_16x16x32_f16 v[16:19], v[152:155], v[128:131], v[16:19]
	s_waitcnt vmcnt(15)
	ds_write_b128 v147, v[68:71] offset:57344
	v_add_co_u32_e32 v68, vcc, s72, v142
	s_nop 1
	v_addc_co_u32_e32 v69, vcc, 0, v143, vcc
	global_load_dwordx4 v[68:71], v[68:69], off
	s_waitcnt lgkmcnt(4)
	v_mfma_f32_16x16x32_f16 v[12:15], v[244:247], v[166:169], v[12:15]
	v_mfma_f32_16x16x32_f16 v[4:7], v[248:251], v[166:169], v[4:7]
	v_mfma_f32_16x16x32_f16 v[8:11], v[252:255], v[166:169], v[8:11]
	v_mfma_f32_16x16x32_f16 v[0:3], v[152:155], v[166:169], v[0:3]
	s_waitcnt vmcnt(15)
	ds_write_b128 v147, v[72:75] offset:61440
	v_add_co_u32_e32 v72, vcc, s73, v142
	s_nop 1
	v_addc_co_u32_e32 v73, vcc, 0, v143, vcc
	global_load_dwordx4 v[72:75], v[72:73], off
	s_waitcnt lgkmcnt(0)
	s_barrier
; template <int NJ>
; __device__ __forceinline__ void gemm_tile(const f16* __restrict__ A, int lda, const f16* __restrict__ Bt, int ldb,
;                                           int K, f32x4 (&acc)[4][NJ], f16* sA, f16* sB, const int tid) {
;     ...
;   G_LOAD(ra0, rb0, 0)
;   if (K > 64) G_LOAD(ra1, rb1, 64)
;   __syncthreads();
;   G_STORE(ra0, rb0, 0)
;   if (K > 128) G_LOAD(ra0, rb0, 128)
;   __syncthreads();
; #pragma unroll 1
;   for (int k0 = 0; k0 < K; k0 += 128) {
;     {
;       const int kof = (k0 + 192 < K) ? k0 + 192 : K - 64;
;       G_STEP(0, ra1, rb1, true, true, kof)
;     }
;     __syncthreads();
;     if (k0 + 64 >= K) break;
;     {
;       const int kof = (k0 + 256 < K) ? k0 + 256 : K - 64;
;       G_STEP(1, ra0, rb0, true, true, kof)
;     }
;     __syncthreads();
	ds_read_b128 v[160:163], v148 offset:49152
	ds_read_b128 v[166:169], v148 offset:51200
	ds_read_b128 v[192:195], v148 offset:53248
	ds_read_b128 v[196:199], v148 offset:55296
	ds_read_b128 v[128:131], v150 offset:32768
	ds_read_b128 v[142:145], v150 offset:34816
	ds_read_b128 v[152:155], v150 offset:36864
	ds_read_b128 v[156:159], v150 offset:38912
	ds_read_b128 v[244:247], v243 offset:49152
	ds_read_b128 v[248:251], v243 offset:51200
	ds_read_b128 v[252:255], v243 offset:53248
	s_waitcnt lgkmcnt(6)
	v_mfma_f32_16x16x32_f16 v[124:127], v[160:163], v[128:131], v[124:127]
	v_mfma_f32_16x16x32_f16 v[116:119], v[166:169], v[128:131], v[116:119]
	v_mfma_f32_16x16x32_f16 v[120:123], v[192:195], v[128:131], v[120:123]
	v_mfma_f32_16x16x32_f16 v[112:115], v[196:199], v[128:131], v[112:115]
	ds_read_b128 v[128:131], v243 offset:55296
	s_waitcnt vmcnt(15)
	ds_write_b128 v147, v[64:67]
	s_waitcnt lgkmcnt(7)
	v_mfma_f32_16x16x32_f16 v[108:111], v[160:163], v[142:145], v[108:111]
	v_mfma_f32_16x16x32_f16 v[36:39], v[166:169], v[142:145], v[36:39]
	v_mfma_f32_16x16x32_f16 v[104:107], v[192:195], v[142:145], v[104:107]
	v_mfma_f32_16x16x32_f16 v[32:35], v[196:199], v[142:145], v[32:35]
	ds_read_b128 v[142:145], v242 offset:32768
	s_waitcnt vmcnt(14)
	ds_write_b128 v147, v[80:83] offset:4096
	s_waitcnt lgkmcnt(8)
	v_mfma_f32_16x16x32_f16 v[28:31], v[160:163], v[152:155], v[28:31]
	v_mfma_f32_16x16x32_f16 v[20:23], v[166:169], v[152:155], v[20:23]
	v_mfma_f32_16x16x32_f16 v[24:27], v[192:195], v[152:155], v[24:27]
	v_mfma_f32_16x16x32_f16 v[16:19], v[196:199], v[152:155], v[16:19]
	ds_read_b128 v[152:155], v242 offset:34816
	s_waitcnt vmcnt(13)
	ds_write_b128 v147, v[84:87] offset:8192
	s_waitcnt lgkmcnt(9)
	v_mfma_f32_16x16x32_f16 v[12:15], v[160:163], v[156:159], v[12:15]
	v_mfma_f32_16x16x32_f16 v[4:7], v[166:169], v[156:159], v[4:7]
	v_mfma_f32_16x16x32_f16 v[8:11], v[192:195], v[156:159], v[8:11]
	v_mfma_f32_16x16x32_f16 v[0:3], v[196:199], v[156:159], v[0:3]
	ds_read_b128 v[156:159], v242 offset:36864
	ds_read_b128 v[160:163], v242 offset:38912
	s_waitcnt vmcnt(12)
	ds_write_b128 v147, v[88:91] offset:12288
	s_waitcnt lgkmcnt(6)
	v_mfma_f32_16x16x32_f16 v[124:127], v[244:247], v[142:145], v[124:127]
	v_mfma_f32_16x16x32_f16 v[116:119], v[248:251], v[142:145], v[116:119]
	v_mfma_f32_16x16x32_f16 v[120:123], v[252:255], v[142:145], v[120:123]
	v_mfma_f32_16x16x32_f16 v[112:115], v[128:131], v[142:145], v[112:115]
	s_waitcnt vmcnt(11)
	ds_write_b128 v147, v[76:79] offset:16384
	s_waitcnt lgkmcnt(5)
	v_mfma_f32_16x16x32_f16 v[108:111], v[244:247], v[152:155], v[108:111]
	v_mfma_f32_16x16x32_f16 v[36:39], v[248:251], v[152:155], v[36:39]
	v_mfma_f32_16x16x32_f16 v[104:107], v[252:255], v[152:155], v[104:107]
	v_mfma_f32_16x16x32_f16 v[32:35], v[128:131], v[152:155], v[32:35]
	s_waitcnt vmcnt(10)
	ds_write_b128 v147, v[92:95] offset:20480
	s_waitcnt lgkmcnt(4)
	v_mfma_f32_16x16x32_f16 v[28:31], v[244:247], v[156:159], v[28:31]
	v_mfma_f32_16x16x32_f16 v[20:23], v[248:251], v[156:159], v[20:23]
	v_mfma_f32_16x16x32_f16 v[24:27], v[252:255], v[156:159], v[24:27]
	v_mfma_f32_16x16x32_f16 v[16:19], v[128:131], v[156:159], v[16:19]
	s_waitcnt vmcnt(9)
	ds_write_b128 v147, v[96:99] offset:24576
	s_waitcnt lgkmcnt(4)
	v_mfma_f32_16x16x32_f16 v[12:15], v[244:247], v[160:163], v[12:15]
	v_mfma_f32_16x16x32_f16 v[4:7], v[248:251], v[160:163], v[4:7]
	v_mfma_f32_16x16x32_f16 v[8:11], v[252:255], v[160:163], v[8:11]
	v_mfma_f32_16x16x32_f16 v[0:3], v[128:131], v[160:163], v[0:3]
	s_waitcnt vmcnt(8)
	ds_write_b128 v147, v[100:103] offset:28672
	s_waitcnt lgkmcnt(0)
	s_barrier
	ds_read_b128 v[166:169], v148 offset:16384
	ds_read_b128 v[192:195], v148 offset:18432
	ds_read_b128 v[196:199], v148 offset:20480
	ds_read_b128 v[200:203], v148 offset:22528
	s_add_i32 s13, s11, 0xc0
	ds_read_b128 v[152:155], v150
	ds_read_b128 v[156:159], v150 offset:2048
	s_cmpk_lt_u32 s11, 0x340
	s_cselect_b32 s42, s13, 0x3c0
	ds_read_b128 v[160:163], v150 offset:4096
	s_lshl_b64 s[14:15], s[42:43], 1
	v_lshl_add_u64 v[144:145], v[138:139], 0, s[14:15]
	ds_read_b128 v[128:131], v150 offset:6144
	ds_read_b128 v[244:247], v243 offset:16384
	ds_read_b128 v[248:251], v243 offset:18432
	ds_read_b128 v[252:255], v243 offset:20480
	s_waitcnt lgkmcnt(6)
	v_mfma_f32_16x16x32_f16 v[124:127], v[166:169], v[152:155], v[124:127]
	v_lshl_add_u64 v[142:143], v[140:141], 0, s[14:15]
	s_add_i32 s13, s11, 0x100
	s_cmpk_lt_u32 s11, 0x300
	v_mfma_f32_16x16x32_f16 v[116:119], v[192:195], v[152:155], v[116:119]
	s_cselect_b32 s42, s13, 0x3c0
	s_lshl_b64 s[14:15], s[42:43], 1
	s_add_i32 s13, s11, 0x80
	v_mfma_f32_16x16x32_f16 v[120:123], v[196:199], v[152:155], v[120:123]
	s_cmpk_lt_u32 s11, 0x380
	s_mov_b32 s11, s13
	v_mfma_f32_16x16x32_f16 v[112:115], v[200:203], v[152:155], v[112:115]
	ds_read_b128 v[152:155], v243 offset:22528
	s_waitcnt vmcnt(7)
	ds_write_b128 v147, v[40:43] offset:32768
	s_waitcnt lgkmcnt(7)
	v_mfma_f32_16x16x32_f16 v[108:111], v[166:169], v[156:159], v[108:111]
	v_mfma_f32_16x16x32_f16 v[36:39], v[192:195], v[156:159], v[36:39]
	v_mfma_f32_16x16x32_f16 v[104:107], v[196:199], v[156:159], v[104:107]
	v_mfma_f32_16x16x32_f16 v[32:35], v[200:203], v[156:159], v[32:35]
	ds_read_b128 v[156:159], v242
	s_waitcnt vmcnt(6)
	ds_write_b128 v147, v[48:51] offset:36864
	s_waitcnt lgkmcnt(8)
	v_mfma_f32_16x16x32_f16 v[28:31], v[166:169], v[160:163], v[28:31]
	v_mfma_f32_16x16x32_f16 v[20:23], v[192:195], v[160:163], v[20:23]
	v_mfma_f32_16x16x32_f16 v[24:27], v[196:199], v[160:163], v[24:27]
	v_mfma_f32_16x16x32_f16 v[16:19], v[200:203], v[160:163], v[16:19]
	ds_read_b128 v[160:163], v242 offset:2048
	s_waitcnt vmcnt(5)
; __device__ __forceinline__ float siluf_(float x) { return x / (1.0f + __expf(-x)); }
; template <int NJ>
; __device__ __forceinline__ void gemm_tile(const f16* __restrict__ A, int lda, const f16* __restrict__ Bt, int ldb,
;                                           int K, f32x4 (&acc)[4][NJ], f16* sA, f16* sB, const int tid) {
;     ...
;   G_LOAD(ra0, rb0, 0)
;   if (K > 64) G_LOAD(ra1, rb1, 64)
;   __syncthreads();
;   G_STORE(ra0, rb0, 0)
;   if (K > 128) G_LOAD(ra0, rb0, 128)
;   __syncthreads();
; #pragma unroll 1
;   for (int k0 = 0; k0 < K; k0 += 128) {
;     {
;       const int kof = (k0 + 192 < K) ? k0 + 192 : K - 64;
;       G_STEP(0, ra1, rb1, true, true, kof)
;     }
;     __syncthreads();
;     if (k0 + 64 >= K) break;
;     {
;       const int kof = (k0 + 256 < K) ? k0 + 256 : K - 64;
;       G_STEP(1, ra0, rb0, true, true, kof)
;     }
;     __syncthreads();
; __device__ __forceinline__ void phase_g4(const Params& p, f16* smem) {
;     ...
; #pragma unroll
;     for (int i = 0; i < 4; ++i) {
;       int m = m0 + wm * 64 + i * 16 + (lane & 15);
; #pragma unroll
;       for (int jj = 0; jj < 2; ++jj) {
;         int u = nt * 64 + wn * 32 + jj * 16 + 4 * (lane >> 4);
;         f16x4 o;
; #pragma unroll
;         for (int r = 0; r < 4; ++r) o[r] = (f16)(siluf_(acc[i][jj][r]) * acc[i][jj + 2][r]);
	ds_write_b128 v147, v[52:55] offset:40960
	s_waitcnt lgkmcnt(9)
	v_mfma_f32_16x16x32_f16 v[12:15], v[166:169], v[128:131], v[12:15]
	v_mfma_f32_16x16x32_f16 v[4:7], v[192:195], v[128:131], v[4:7]
	v_mfma_f32_16x16x32_f16 v[8:11], v[196:199], v[128:131], v[8:11]
	v_mfma_f32_16x16x32_f16 v[0:3], v[200:203], v[128:131], v[0:3]
	ds_read_b128 v[128:131], v242 offset:4096
	ds_read_b128 v[166:169], v242 offset:6144
	s_waitcnt vmcnt(4)
	ds_write_b128 v147, v[56:59] offset:45056
	s_waitcnt lgkmcnt(6)
	v_mfma_f32_16x16x32_f16 v[124:127], v[244:247], v[156:159], v[124:127]
	v_mfma_f32_16x16x32_f16 v[116:119], v[248:251], v[156:159], v[116:119]
	v_mfma_f32_16x16x32_f16 v[120:123], v[252:255], v[156:159], v[120:123]
	v_mfma_f32_16x16x32_f16 v[112:115], v[152:155], v[156:159], v[112:115]
	s_waitcnt vmcnt(3)
	ds_write_b128 v147, v[44:47] offset:49152
	v_lshl_add_u64 v[202:203], v[138:139], 0, s[14:15]
	s_waitcnt lgkmcnt(5)
	v_mfma_f32_16x16x32_f16 v[108:111], v[244:247], v[160:163], v[108:111]
	v_lshl_add_u64 v[200:201], v[140:141], 0, s[14:15]
	v_mfma_f32_16x16x32_f16 v[36:39], v[248:251], v[160:163], v[36:39]
	v_mfma_f32_16x16x32_f16 v[104:107], v[252:255], v[160:163], v[104:107]
	v_mfma_f32_16x16x32_f16 v[32:35], v[152:155], v[160:163], v[32:35]
	s_waitcnt vmcnt(2)
	ds_write_b128 v147, v[60:63] offset:53248
	s_waitcnt lgkmcnt(4)
	v_mfma_f32_16x16x32_f16 v[28:31], v[244:247], v[128:131], v[28:31]
	v_mfma_f32_16x16x32_f16 v[20:23], v[248:251], v[128:131], v[20:23]
	v_mfma_f32_16x16x32_f16 v[24:27], v[252:255], v[128:131], v[24:27]
	v_mfma_f32_16x16x32_f16 v[16:19], v[152:155], v[128:131], v[16:19]
	s_waitcnt vmcnt(1)
	ds_write_b128 v147, v[68:71] offset:57344
	s_waitcnt lgkmcnt(4)
	v_mfma_f32_16x16x32_f16 v[12:15], v[244:247], v[166:169], v[12:15]
	v_mfma_f32_16x16x32_f16 v[4:7], v[248:251], v[166:169], v[4:7]
	v_mfma_f32_16x16x32_f16 v[8:11], v[252:255], v[166:169], v[8:11]
	v_mfma_f32_16x16x32_f16 v[0:3], v[152:155], v[166:169], v[0:3]
	s_waitcnt vmcnt(0)
	ds_write_b128 v147, v[72:75] offset:61440
	s_waitcnt lgkmcnt(0)
	s_barrier
	ds_read_b128 v[160:163], v148 offset:49152
	ds_read_b128 v[166:169], v148 offset:51200
	ds_read_b128 v[192:195], v148 offset:53248
	ds_read_b128 v[196:199], v148 offset:55296
	ds_read_b128 v[128:131], v150 offset:32768
	ds_read_b128 v[142:145], v150 offset:34816
	ds_read_b128 v[152:155], v150 offset:36864
	ds_read_b128 v[156:159], v150 offset:38912
	ds_read_b128 v[244:247], v243 offset:49152
	ds_read_b128 v[248:251], v243 offset:51200
	ds_read_b128 v[252:255], v243 offset:53248
	s_waitcnt lgkmcnt(6)
	v_mfma_f32_16x16x32_f16 v[124:127], v[160:163], v[128:131], v[124:127]
	v_mfma_f32_16x16x32_f16 v[116:119], v[166:169], v[128:131], v[116:119]
	v_mfma_f32_16x16x32_f16 v[120:123], v[192:195], v[128:131], v[120:123]
	v_mfma_f32_16x16x32_f16 v[112:115], v[196:199], v[128:131], v[112:115]
	ds_read_b128 v[128:131], v243 offset:55296
	s_waitcnt lgkmcnt(6)
	v_mfma_f32_16x16x32_f16 v[108:111], v[160:163], v[142:145], v[108:111]
	v_mfma_f32_16x16x32_f16 v[36:39], v[166:169], v[142:145], v[36:39]
	v_mfma_f32_16x16x32_f16 v[104:107], v[192:195], v[142:145], v[104:107]
	v_mfma_f32_16x16x32_f16 v[32:35], v[196:199], v[142:145], v[32:35]
	ds_read_b128 v[142:145], v242 offset:32768
	s_waitcnt lgkmcnt(6)
	v_mfma_f32_16x16x32_f16 v[28:31], v[160:163], v[152:155], v[28:31]
	v_mfma_f32_16x16x32_f16 v[20:23], v[166:169], v[152:155], v[20:23]
	v_mfma_f32_16x16x32_f16 v[24:27], v[192:195], v[152:155], v[24:27]
	v_mfma_f32_16x16x32_f16 v[16:19], v[196:199], v[152:155], v[16:19]
	ds_read_b128 v[152:155], v242 offset:34816
	s_waitcnt lgkmcnt(6)
	v_mfma_f32_16x16x32_f16 v[12:15], v[160:163], v[156:159], v[12:15]
	v_mfma_f32_16x16x32_f16 v[4:7], v[166:169], v[156:159], v[4:7]
	v_mfma_f32_16x16x32_f16 v[8:11], v[192:195], v[156:159], v[8:11]
	v_mfma_f32_16x16x32_f16 v[0:3], v[196:199], v[156:159], v[0:3]
	ds_read_b128 v[156:159], v242 offset:36864
	ds_read_b128 v[160:163], v242 offset:38912
	s_waitcnt lgkmcnt(3)
	v_mfma_f32_16x16x32_f16 v[124:127], v[244:247], v[142:145], v[124:127]
	v_mfma_f32_16x16x32_f16 v[116:119], v[248:251], v[142:145], v[116:119]
	v_mfma_f32_16x16x32_f16 v[120:123], v[252:255], v[142:145], v[120:123]
	v_mfma_f32_16x16x32_f16 v[112:115], v[128:131], v[142:145], v[112:115]
	s_waitcnt lgkmcnt(2)
	v_mfma_f32_16x16x32_f16 v[108:111], v[244:247], v[152:155], v[108:111]
	v_mfma_f32_16x16x32_f16 v[36:39], v[248:251], v[152:155], v[36:39]
	v_mfma_f32_16x16x32_f16 v[104:107], v[252:255], v[152:155], v[104:107]
	v_mfma_f32_16x16x32_f16 v[32:35], v[128:131], v[152:155], v[32:35]
	s_waitcnt lgkmcnt(1)
	v_mfma_f32_16x16x32_f16 v[28:31], v[244:247], v[156:159], v[28:31]
	v_mfma_f32_16x16x32_f16 v[20:23], v[248:251], v[156:159], v[20:23]
	v_mfma_f32_16x16x32_f16 v[24:27], v[252:255], v[156:159], v[24:27]
	v_mfma_f32_16x16x32_f16 v[16:19], v[128:131], v[156:159], v[16:19]
	s_waitcnt lgkmcnt(0)
	v_mfma_f32_16x16x32_f16 v[12:15], v[244:247], v[160:163], v[12:15]
	v_mfma_f32_16x16x32_f16 v[4:7], v[248:251], v[160:163], v[4:7]
	v_mfma_f32_16x16x32_f16 v[8:11], v[252:255], v[160:163], v[8:11]
	v_mfma_f32_16x16x32_f16 v[0:3], v[128:131], v[160:163], v[0:3]
	s_waitcnt lgkmcnt(0)
	s_waitcnt vmcnt(15)
	v_mul_f32_e32 v41, 0xbfb8aa3b, v124
	s_waitcnt vmcnt(11)
; __device__ __forceinline__ float siluf_(float x) { return x / (1.0f + __expf(-x)); }
; __device__ __forceinline__ void phase_g4(const Params& p, f16* smem) {
;     ...
; #pragma unroll
;     for (int i = 0; i < 4; ++i) {
;       int m = m0 + wm * 64 + i * 16 + (lane & 15);
; #pragma unroll
;       for (int jj = 0; jj < 2; ++jj) {
;         int u = nt * 64 + wn * 32 + jj * 16 + 4 * (lane >> 4);
;         f16x4 o;
; #pragma unroll
;         for (int r = 0; r < 4; ++r) o[r] = (f16)(siluf_(acc[i][jj][r]) * acc[i][jj + 2][r]);
;         *(f16x4*)(hid + (size_t)m * FF + u) = o;
;       }
;     }
	v_exp_f32_e32 v46, v41
	v_mul_f32_e32 v41, 0xbfb8aa3b, v125
	v_exp_f32_e32 v47, v41
	v_add_u32_e32 v42, s10, v146
	v_lshl_or_b32 v40, s12, 6, v149
	v_mad_i64_i32 v[44:45], s[10:11], v42, s96, v[132:133]
	v_pk_add_f32 v[46:47], v[46:47], 1.0 op_sel_hi:[1,0]
	s_add_i32 s5, s5, s26
	s_movk_i32 s14, 0x2cb0
	s_cmp_eq_u32 s4, 3
	s_cselect_b32 s14, 0x2c00, s14
	s_cmp_lt_i32 s5, s14
	v_rcp_f32_e32 v43, v47
	s_nop 0
	v_mul_f32_e32 v41, v125, v43
	v_mov_b32_e32 v47, v41
	s_nop 0
	v_rcp_f32_e32 v43, v46
	s_nop 0
	v_mul_f32_e32 v41, v124, v43
	v_mov_b32_e32 v46, v41
	v_mul_f32_e32 v41, 0xbfb8aa3b, v126
	v_exp_f32_e32 v48, v41
	v_mul_f32_e32 v41, 0xbfb8aa3b, v127
	v_exp_f32_e32 v49, v41
	v_pk_mul_f32 v[46:47], v[120:121], v[46:47]
	v_pk_add_f32 v[48:49], v[48:49], 1.0 op_sel_hi:[1,0]
	s_nop 0
	v_cvt_pk_f16_f32 v46, v46, v47
	v_rcp_f32_e32 v43, v49
	s_nop 0
	v_mul_f32_e32 v41, v127, v43
	v_mov_b32_e32 v49, v41
	s_nop 0
	v_rcp_f32_e32 v43, v48
	s_nop 0
	v_mul_f32_e32 v41, v126, v43
	v_mov_b32_e32 v48, v41
	v_ashrrev_i32_e32 v41, 31, v40
	v_pk_mul_f32 v[48:49], v[122:123], v[48:49]
	v_lshlrev_b64 v[40:41], 1, v[40:41]
	v_cvt_pk_f16_f32 v47, v48, v49
	v_lshl_add_u64 v[44:45], v[44:45], 0, v[40:41]
	v_mul_f32_e32 v43, 0xbfb8aa3b, v116
	global_store_dwordx2 v[44:45], v[46:47], off
	v_exp_f32_e32 v46, v43
	v_mul_f32_e32 v43, 0xbfb8aa3b, v117
	v_exp_f32_e32 v47, v43
	s_nop 0
	v_pk_add_f32 v[46:47], v[46:47], 1.0 op_sel_hi:[1,0]
	s_nop 0
	s_nop 0
	v_rcp_f32_e32 v48, v47
	s_nop 0
	v_mul_f32_e32 v43, v117, v48
	v_mov_b32_e32 v47, v43
	s_nop 0
	v_rcp_f32_e32 v48, v46
	s_nop 0
	v_mul_f32_e32 v43, v116, v48
	v_mov_b32_e32 v46, v43
	v_mul_f32_e32 v43, 0xbfb8aa3b, v118
	v_exp_f32_e32 v48, v43
	v_mul_f32_e32 v43, 0xbfb8aa3b, v119
	v_exp_f32_e32 v49, v43
	v_pk_mul_f32 v[46:47], v[112:113], v[46:47]
	v_pk_add_f32 v[48:49], v[48:49], 1.0 op_sel_hi:[1,0]
	s_nop 0
	v_cvt_pk_f16_f32 v46, v46, v47
	s_nop 0
	v_rcp_f32_e32 v47, v49
	s_nop 0
	v_mul_f32_e32 v43, v119, v47
	v_mov_b32_e32 v49, v43
	s_nop 0
	v_rcp_f32_e32 v47, v48
	s_nop 0
	v_mul_f32_e32 v43, v118, v47
	v_mov_b32_e32 v48, v43
	v_pk_mul_f32 v[48:49], v[114:115], v[48:49]
	v_or_b32_e32 v43, 16, v42
	v_cvt_pk_f16_f32 v47, v48, v49
	global_store_dwordx2 v[44:45], v[46:47], off offset:32
	v_mad_i64_i32 v[44:45], s[10:11], v43, s96, v[132:133]
	v_mul_f32_e32 v43, 0xbfb8aa3b, v108
	v_exp_f32_e32 v46, v43
	v_mul_f32_e32 v43, 0xbfb8aa3b, v109
	v_exp_f32_e32 v47, v43
	v_lshl_add_u64 v[44:45], v[44:45], 0, v[40:41]
	v_pk_add_f32 v[46:47], v[46:47], 1.0 op_sel_hi:[1,0]
	s_nop 0
	s_nop 0
	v_rcp_f32_e32 v48, v47
	s_nop 0
	v_mul_f32_e32 v43, v109, v48
	v_mov_b32_e32 v47, v43
	s_nop 0
	v_rcp_f32_e32 v48, v46
	s_nop 0
	v_mul_f32_e32 v43, v108, v48
	v_mov_b32_e32 v46, v43
	v_mul_f32_e32 v43, 0xbfb8aa3b, v110
	v_exp_f32_e32 v48, v43
	v_mul_f32_e32 v43, 0xbfb8aa3b, v111
	v_exp_f32_e32 v49, v43
	v_pk_mul_f32 v[46:47], v[104:105], v[46:47]
	v_pk_add_f32 v[48:49], v[48:49], 1.0 op_sel_hi:[1,0]
	s_nop 0
	v_cvt_pk_f16_f32 v46, v46, v47
	s_nop 0
	v_rcp_f32_e32 v47, v49
	s_nop 0
	v_mul_f32_e32 v43, v111, v47
	v_mov_b32_e32 v49, v43
	s_nop 0
	v_rcp_f32_e32 v47, v48
	s_nop 0
	v_mul_f32_e32 v43, v110, v47
	v_mov_b32_e32 v48, v43
	v_pk_mul_f32 v[48:49], v[106:107], v[48:49]
	v_mul_f32_e32 v43, 0xbfb8aa3b, v36
	v_cvt_pk_f16_f32 v47, v48, v49
	global_store_dwordx2 v[44:45], v[46:47], off
	v_exp_f32_e32 v46, v43
	v_mul_f32_e32 v43, 0xbfb8aa3b, v37
	v_exp_f32_e32 v47, v43
	s_nop 0
	v_pk_add_f32 v[46:47], v[46:47], 1.0 op_sel_hi:[1,0]
	s_nop 0
	s_nop 0
	v_rcp_f32_e32 v48, v47
	s_nop 0
	v_mul_f32_e32 v43, v37, v48
	v_mov_b32_e32 v37, v43
	s_nop 0
	v_rcp_f32_e32 v47, v46
	s_nop 0
	v_mul_f32_e32 v43, v36, v47
	v_mov_b32_e32 v36, v43
	v_pk_mul_f32 v[32:33], v[32:33], v[36:37]
	s_nop 0
	v_cvt_pk_f16_f32 v32, v32, v33
	v_mul_f32_e32 v33, 0xbfb8aa3b, v38
	v_exp_f32_e32 v36, v33
	v_mul_f32_e32 v33, 0xbfb8aa3b, v39
	v_exp_f32_e32 v37, v33
	s_nop 0
	v_pk_add_f32 v[36:37], v[36:37], 1.0 op_sel_hi:[1,0]
	s_nop 0
	s_nop 0
	v_rcp_f32_e32 v43, v37
	s_nop 0
	v_mul_f32_e32 v33, v39, v43
	v_mov_b32_e32 v37, v33
	s_nop 0
	v_rcp_f32_e32 v39, v36
	s_nop 0
	v_mul_f32_e32 v33, v38, v39
	v_mov_b32_e32 v36, v33
	v_pk_mul_f32 v[34:35], v[34:35], v[36:37]
	s_nop 0
; __device__ __forceinline__ float siluf_(float x) { return x / (1.0f + __expf(-x)); }
; __device__ __forceinline__ void phase_g4(const Params& p, f16* smem) {
;     ...
; #pragma unroll
;     for (int i = 0; i < 4; ++i) {
;       int m = m0 + wm * 64 + i * 16 + (lane & 15);
; #pragma unroll
;       for (int jj = 0; jj < 2; ++jj) {
;         int u = nt * 64 + wn * 32 + jj * 16 + 4 * (lane >> 4);
;         f16x4 o;
; #pragma unroll
;         for (int r = 0; r < 4; ++r) o[r] = (f16)(siluf_(acc[i][jj][r]) * acc[i][jj + 2][r]);
;         *(f16x4*)(hid + (size_t)m * FF + u) = o;
;       }
;     }
;   }
	v_cvt_pk_f16_f32 v33, v34, v35
	v_mul_f32_e32 v34, 0xbfb8aa3b, v28
	v_mul_f32_e32 v35, 0xbfb8aa3b, v29
	v_exp_f32_e32 v34, v34
	v_exp_f32_e32 v35, v35
	global_store_dwordx2 v[44:45], v[32:33], off offset:32
	v_or_b32_e32 v32, 32, v42
	v_mad_i64_i32 v[32:33], s[10:11], v32, s96, v[132:133]
	v_pk_add_f32 v[34:35], v[34:35], 1.0 op_sel_hi:[1,0]
	s_nop 0
	s_nop 0
	v_rcp_f32_e32 v37, v35
	s_nop 0
	v_mul_f32_e32 v36, v29, v37
	v_mov_b32_e32 v29, v36
	s_nop 0
	v_rcp_f32_e32 v36, v34
	s_nop 0
	v_mul_f32_e32 v35, v28, v36
	v_mov_b32_e32 v28, v35
	v_pk_mul_f32 v[24:25], v[24:25], v[28:29]
	s_nop 0
	v_cvt_pk_f16_f32 v24, v24, v25
	v_mul_f32_e32 v25, 0xbfb8aa3b, v30
	v_exp_f32_e32 v28, v25
	v_mul_f32_e32 v25, 0xbfb8aa3b, v31
	v_exp_f32_e32 v29, v25
	s_nop 0
	v_pk_add_f32 v[28:29], v[28:29], 1.0 op_sel_hi:[1,0]
	s_nop 0
	s_nop 0
	v_rcp_f32_e32 v34, v29
	s_nop 0
	v_mul_f32_e32 v25, v31, v34
	v_mov_b32_e32 v29, v25
	s_nop 0
	v_rcp_f32_e32 v31, v28
	s_nop 0
	v_mul_f32_e32 v25, v30, v31
	v_mov_b32_e32 v28, v25
	v_pk_mul_f32 v[26:27], v[26:27], v[28:29]
	s_nop 0
	v_cvt_pk_f16_f32 v25, v26, v27
	v_lshl_add_u64 v[26:27], v[32:33], 0, v[40:41]
	global_store_dwordx2 v[26:27], v[24:25], off
	v_mul_f32_e32 v24, 0xbfb8aa3b, v20
	v_mul_f32_e32 v25, 0xbfb8aa3b, v21
	v_exp_f32_e32 v24, v24
	v_exp_f32_e32 v25, v25
	s_nop 0
	v_pk_add_f32 v[24:25], v[24:25], 1.0 op_sel_hi:[1,0]
	s_nop 0
	s_nop 0
	v_rcp_f32_e32 v29, v25
	s_nop 0
	v_mul_f32_e32 v28, v21, v29
	v_mov_b32_e32 v21, v28
	s_nop 0
	v_rcp_f32_e32 v28, v24
	s_nop 0
	v_mul_f32_e32 v25, v20, v28
	v_mov_b32_e32 v20, v25
	v_pk_mul_f32 v[16:17], v[16:17], v[20:21]
	s_nop 0
	v_cvt_pk_f16_f32 v16, v16, v17
	v_mul_f32_e32 v17, 0xbfb8aa3b, v22
	v_exp_f32_e32 v20, v17
	v_mul_f32_e32 v17, 0xbfb8aa3b, v23
	v_exp_f32_e32 v21, v17
	s_nop 0
	v_pk_add_f32 v[20:21], v[20:21], 1.0 op_sel_hi:[1,0]
	s_nop 0
	s_nop 0
	v_rcp_f32_e32 v24, v21
	s_nop 0
	v_mul_f32_e32 v17, v23, v24
	v_mov_b32_e32 v21, v17
	s_nop 0
	v_rcp_f32_e32 v23, v20
	s_nop 0
	v_mul_f32_e32 v17, v22, v23
	v_mov_b32_e32 v20, v17
	v_pk_mul_f32 v[18:19], v[18:19], v[20:21]
	s_nop 0
	v_cvt_pk_f16_f32 v17, v18, v19
	v_mul_f32_e32 v18, 0xbfb8aa3b, v12
	v_mul_f32_e32 v19, 0xbfb8aa3b, v13
	v_exp_f32_e32 v18, v18
	v_exp_f32_e32 v19, v19
	global_store_dwordx2 v[26:27], v[16:17], off offset:32
	v_or_b32_e32 v16, 48, v42
	v_mad_i64_i32 v[16:17], s[10:11], v16, s96, v[132:133]
	v_pk_add_f32 v[18:19], v[18:19], 1.0 op_sel_hi:[1,0]
	s_nop 0
	s_nop 0
	v_rcp_f32_e32 v21, v19
	s_nop 0
	v_mul_f32_e32 v20, v13, v21
	v_mov_b32_e32 v13, v20
	s_nop 0
	v_rcp_f32_e32 v20, v18
	s_nop 0
	v_mul_f32_e32 v19, v12, v20
	v_mov_b32_e32 v12, v19
	v_pk_mul_f32 v[8:9], v[8:9], v[12:13]
	s_nop 0
	v_cvt_pk_f16_f32 v8, v8, v9
	v_mul_f32_e32 v9, 0xbfb8aa3b, v14
	v_exp_f32_e32 v12, v9
	v_mul_f32_e32 v9, 0xbfb8aa3b, v15
	v_exp_f32_e32 v13, v9
	s_nop 0
	v_pk_add_f32 v[12:13], v[12:13], 1.0 op_sel_hi:[1,0]
	s_nop 0
	s_nop 0
	v_rcp_f32_e32 v18, v13
	s_nop 0
	v_mul_f32_e32 v9, v15, v18
	v_mov_b32_e32 v13, v9
	s_nop 0
	v_rcp_f32_e32 v15, v12
	s_nop 0
	v_mul_f32_e32 v9, v14, v15
	v_mov_b32_e32 v12, v9
	v_pk_mul_f32 v[10:11], v[10:11], v[12:13]
	s_nop 0
	v_cvt_pk_f16_f32 v9, v10, v11
	v_lshl_add_u64 v[10:11], v[16:17], 0, v[40:41]
	global_store_dwordx2 v[10:11], v[8:9], off
	v_mul_f32_e32 v8, 0xbfb8aa3b, v4
	v_mul_f32_e32 v9, 0xbfb8aa3b, v5
	v_exp_f32_e32 v8, v8
	v_exp_f32_e32 v9, v9
	s_nop 0
	v_pk_add_f32 v[8:9], v[8:9], 1.0 op_sel_hi:[1,0]
	s_nop 0
	s_nop 0
	v_rcp_f32_e32 v13, v9
	s_nop 0
	v_mul_f32_e32 v12, v5, v13
	v_mov_b32_e32 v5, v12
	s_nop 0
	v_rcp_f32_e32 v12, v8
	s_nop 0
	v_mul_f32_e32 v9, v4, v12
	v_mov_b32_e32 v4, v9
	v_pk_mul_f32 v[0:1], v[0:1], v[4:5]
	s_nop 0
	v_cvt_pk_f16_f32 v0, v0, v1
	v_mul_f32_e32 v1, 0xbfb8aa3b, v6
	v_exp_f32_e32 v4, v1
	v_mul_f32_e32 v1, 0xbfb8aa3b, v7
	v_exp_f32_e32 v5, v1
	s_nop 0
	v_pk_add_f32 v[4:5], v[4:5], 1.0 op_sel_hi:[1,0]
	s_nop 0
	s_nop 0
	v_rcp_f32_e32 v8, v5
	s_nop 0
	v_mul_f32_e32 v1, v7, v8
	v_mov_b32_e32 v5, v1
	s_nop 0
	v_rcp_f32_e32 v7, v4
	s_nop 0
	v_mul_f32_e32 v1, v6, v7
	v_mov_b32_e32 v4, v1
	v_pk_mul_f32 v[2:3], v[2:3], v[4:5]
	s_nop 0
	v_cvt_pk_f16_f32 v1, v2, v3
	global_store_dwordx2 v[10:11], v[0:1], off offset:32
	s_cbranch_scc1 .LBB0_1397

; template <int NJ>
; __device__ __forceinline__ void gemm_tile(const f16* __restrict__ A, int lda, const f16* __restrict__ Bt, int ldb,
;                                           int K, f32x4 (&acc)[4][NJ], f16* sA, f16* sB, const int tid) {
;     ...
;   G_LOAD(ra0, rb0, 0)
;   if (K > 64) G_LOAD(ra1, rb1, 64)
;   __syncthreads();
;   G_STORE(ra0, rb0, 0)
;   if (K > 128) G_LOAD(ra0, rb0, 128)
;   __syncthreads();
; #pragma unroll 1
;   for (int k0 = 0; k0 < K; k0 += 128) {
;     {
;       const int kof = (k0 + 192 < K) ? k0 + 192 : K - 64;
;       G_STEP(0, ra1, rb1, true, true, kof)
.LBB0_1457:
	ds_read_b128 v[204:207], v163 offset:16384
	ds_read_b128 v[208:211], v163 offset:18432
	ds_read_b128 v[212:215], v163 offset:20480
	ds_read_b128 v[216:219], v163 offset:22528
	s_add_i32 s11, s10, 0xc0
	ds_read_b128 v[192:195], v162
	ds_read_b128 v[196:199], v162 offset:2048
	s_cmpk_lt_u32 s10, 0xa40
	s_cselect_b32 s42, s11, 0xac0
	ds_read_b128 v[200:203], v162 offset:4096
	s_lshl_b64 s[12:13], s[42:43], 1
	v_lshl_add_u64 v[152:153], v[146:147], 0, s[12:13]
	ds_read_b128 v[130:133], v162 offset:6144
	ds_read_b128 v[244:247], v243 offset:16384
	ds_read_b128 v[248:251], v243 offset:18432
	ds_read_b128 v[252:255], v243 offset:20480
	s_waitcnt lgkmcnt(6)
	v_mfma_f32_16x16x32_f16 v[126:129], v[204:207], v[192:195], v[126:129]
	v_lshl_add_u64 v[150:151], v[148:149], 0, s[12:13]
	s_add_i32 s11, s10, 0x100
	s_cmpk_lt_u32 s10, 0xa00
	v_mfma_f32_16x16x32_f16 v[122:125], v[208:211], v[192:195], v[122:125]
	s_cselect_b32 s42, s11, 0xac0
	s_lshl_b64 s[12:13], s[42:43], 1
	v_lshl_add_u64 v[168:169], v[148:149], 0, s[12:13]
	v_mfma_f32_16x16x32_f16 v[118:121], v[212:215], v[192:195], v[118:121]
	s_add_i32 s11, s10, 0x80
	s_cmpk_lt_u32 s10, 0x980
	s_mov_b32 s10, s11
	v_mfma_f32_16x16x32_f16 v[114:117], v[216:219], v[192:195], v[114:117]
	ds_read_b128 v[192:195], v243 offset:22528
	s_waitcnt vmcnt(15)
	ds_write_b128 v161, v[18:21] offset:32768
	global_load_dwordx4 v[18:21], v[152:153], off
	s_waitcnt lgkmcnt(7)
	v_mfma_f32_16x16x32_f16 v[110:113], v[204:207], v[196:199], v[110:113]
	v_mfma_f32_16x16x32_f16 v[106:109], v[208:211], v[196:199], v[106:109]
	v_mfma_f32_16x16x32_f16 v[102:105], v[212:215], v[196:199], v[102:105]
	v_mfma_f32_16x16x32_f16 v[98:101], v[216:219], v[196:199], v[98:101]
	ds_read_b128 v[196:199], v242
	s_waitcnt vmcnt(15)
	ds_write_b128 v161, v[26:29] offset:36864
	v_add_co_u32_e32 v26, vcc, s81, v152
	s_nop 1
	v_addc_co_u32_e32 v27, vcc, 0, v153, vcc
	global_load_dwordx4 v[26:29], v[26:27], off
	s_waitcnt lgkmcnt(8)
	v_mfma_f32_16x16x32_f16 v[94:97], v[204:207], v[200:203], v[94:97]
	v_mfma_f32_16x16x32_f16 v[90:93], v[208:211], v[200:203], v[90:93]
	v_mfma_f32_16x16x32_f16 v[86:89], v[212:215], v[200:203], v[86:89]
	v_mfma_f32_16x16x32_f16 v[82:85], v[216:219], v[200:203], v[82:85]
	ds_read_b128 v[200:203], v242 offset:2048
	s_waitcnt vmcnt(14)
	ds_write_b128 v161, v[30:33] offset:40960
	v_add_co_u32_e32 v30, vcc, s97, v152
	s_nop 1
	v_addc_co_u32_e32 v31, vcc, 0, v153, vcc
	global_load_dwordx4 v[30:33], v[30:31], off
	s_waitcnt lgkmcnt(9)
	v_mfma_f32_16x16x32_f16 v[14:17], v[204:207], v[130:133], v[14:17]
	v_mfma_f32_16x16x32_f16 v[10:13], v[208:211], v[130:133], v[10:13]
	v_mfma_f32_16x16x32_f16 v[6:9], v[212:215], v[130:133], v[6:9]
	v_mfma_f32_16x16x32_f16 v[2:5], v[216:219], v[130:133], v[2:5]
	ds_read_b128 v[130:133], v242 offset:4096
	ds_read_b128 v[204:207], v242 offset:6144
	s_waitcnt vmcnt(14)
	ds_write_b128 v161, v[34:37] offset:45056
	v_add_co_u32_e32 v34, vcc, s27, v152
	s_nop 1
	v_addc_co_u32_e32 v35, vcc, 0, v153, vcc
	global_load_dwordx4 v[34:37], v[34:35], off
	s_waitcnt lgkmcnt(6)
	v_mfma_f32_16x16x32_f16 v[126:129], v[244:247], v[196:199], v[126:129]
	v_mfma_f32_16x16x32_f16 v[122:125], v[248:251], v[196:199], v[122:125]
	v_mfma_f32_16x16x32_f16 v[118:121], v[252:255], v[196:199], v[118:121]
	v_mfma_f32_16x16x32_f16 v[114:117], v[192:195], v[196:199], v[114:117]
	ds_write_b128 v161, v[22:25] offset:49152
	global_load_dwordx4 v[22:25], v[150:151], off
	v_lshl_add_u64 v[216:217], v[146:147], 0, s[12:13]
	s_waitcnt lgkmcnt(5)
	v_mfma_f32_16x16x32_f16 v[110:113], v[244:247], v[200:203], v[110:113]
	v_mfma_f32_16x16x32_f16 v[106:109], v[248:251], v[200:203], v[106:109]
	v_mfma_f32_16x16x32_f16 v[102:105], v[252:255], v[200:203], v[102:105]
	v_mfma_f32_16x16x32_f16 v[98:101], v[192:195], v[200:203], v[98:101]
	s_waitcnt vmcnt(15)
	ds_write_b128 v161, v[38:41] offset:53248
	v_add_co_u32_e32 v38, vcc, s81, v150
	s_nop 1
	v_addc_co_u32_e32 v39, vcc, 0, v151, vcc
	global_load_dwordx4 v[38:41], v[38:39], off
	s_waitcnt lgkmcnt(4)
	v_mfma_f32_16x16x32_f16 v[94:97], v[244:247], v[130:133], v[94:97]
	v_mfma_f32_16x16x32_f16 v[90:93], v[248:251], v[130:133], v[90:93]
	v_mfma_f32_16x16x32_f16 v[86:89], v[252:255], v[130:133], v[86:89]
	v_mfma_f32_16x16x32_f16 v[82:85], v[192:195], v[130:133], v[82:85]
	s_waitcnt vmcnt(15)
	ds_write_b128 v161, v[46:49] offset:57344
	v_add_co_u32_e32 v46, vcc, s97, v150
	s_nop 1
	v_addc_co_u32_e32 v47, vcc, 0, v151, vcc
	global_load_dwordx4 v[46:49], v[46:47], off
	s_waitcnt lgkmcnt(4)
	v_mfma_f32_16x16x32_f16 v[14:17], v[244:247], v[204:207], v[14:17]
	v_mfma_f32_16x16x32_f16 v[10:13], v[248:251], v[204:207], v[10:13]
	v_mfma_f32_16x16x32_f16 v[6:9], v[252:255], v[204:207], v[6:9]
	v_mfma_f32_16x16x32_f16 v[2:5], v[192:195], v[204:207], v[2:5]
	s_waitcnt vmcnt(15)
	ds_write_b128 v161, v[50:53] offset:61440
	v_add_co_u32_e32 v50, vcc, s27, v150
	s_nop 1
	v_addc_co_u32_e32 v51, vcc, 0, v151, vcc
	global_load_dwordx4 v[50:53], v[50:51], off
	s_waitcnt lgkmcnt(0)
	s_barrier
; template <int NJ>
; __device__ __forceinline__ void gemm_tile(const f16* __restrict__ A, int lda, const f16* __restrict__ Bt, int ldb,
;                                           int K, f32x4 (&acc)[4][NJ], f16* sA, f16* sB, const int tid) {
;     ...
;   G_LOAD(ra0, rb0, 0)
;   if (K > 64) G_LOAD(ra1, rb1, 64)
;   __syncthreads();
;   G_STORE(ra0, rb0, 0)
;   if (K > 128) G_LOAD(ra0, rb0, 128)
;   __syncthreads();
; #pragma unroll 1
;   for (int k0 = 0; k0 < K; k0 += 128) {
;     {
;       const int kof = (k0 + 192 < K) ? k0 + 192 : K - 64;
;       G_STEP(0, ra1, rb1, true, true, kof)
;     }
;     __syncthreads();
;     if (k0 + 64 >= K) break;
;     {
;       const int kof = (k0 + 256 < K) ? k0 + 256 : K - 64;
;       G_STEP(1, ra0, rb0, true, true, kof)
;     }
;     __syncthreads();
	ds_read_b128 v[200:203], v163 offset:49152
	ds_read_b128 v[204:207], v163 offset:51200
	ds_read_b128 v[208:211], v163 offset:53248
	ds_read_b128 v[212:215], v163 offset:55296
	ds_read_b128 v[130:133], v162 offset:32768
	ds_read_b128 v[150:153], v162 offset:34816
	ds_read_b128 v[192:195], v162 offset:36864
	ds_read_b128 v[196:199], v162 offset:38912
	ds_read_b128 v[244:247], v243 offset:49152
	ds_read_b128 v[248:251], v243 offset:51200
	ds_read_b128 v[252:255], v243 offset:53248
	s_waitcnt lgkmcnt(6)
	v_mfma_f32_16x16x32_f16 v[126:129], v[200:203], v[130:133], v[126:129]
	v_mfma_f32_16x16x32_f16 v[122:125], v[204:207], v[130:133], v[122:125]
	v_mfma_f32_16x16x32_f16 v[118:121], v[208:211], v[130:133], v[118:121]
	v_mfma_f32_16x16x32_f16 v[114:117], v[212:215], v[130:133], v[114:117]
	ds_read_b128 v[130:133], v243 offset:55296
	s_waitcnt vmcnt(13)
	ds_write_b128 v161, v[42:45]
	global_load_dwordx4 v[42:45], v[216:217], off
	s_waitcnt lgkmcnt(7)
	v_mfma_f32_16x16x32_f16 v[110:113], v[200:203], v[150:153], v[110:113]
	v_mfma_f32_16x16x32_f16 v[106:109], v[204:207], v[150:153], v[106:109]
	v_mfma_f32_16x16x32_f16 v[102:105], v[208:211], v[150:153], v[102:105]
	v_mfma_f32_16x16x32_f16 v[98:101], v[212:215], v[150:153], v[98:101]
	ds_read_b128 v[150:153], v242 offset:32768
	ds_write_b128 v161, v[58:61] offset:4096
	v_add_co_u32_e32 v58, vcc, s81, v216
	s_nop 1
	v_addc_co_u32_e32 v59, vcc, 0, v217, vcc
	global_load_dwordx4 v[58:61], v[58:59], off
	s_waitcnt lgkmcnt(8)
	v_mfma_f32_16x16x32_f16 v[94:97], v[200:203], v[192:195], v[94:97]
	v_mfma_f32_16x16x32_f16 v[90:93], v[204:207], v[192:195], v[90:93]
	v_mfma_f32_16x16x32_f16 v[86:89], v[208:211], v[192:195], v[86:89]
	v_mfma_f32_16x16x32_f16 v[82:85], v[212:215], v[192:195], v[82:85]
	ds_read_b128 v[192:195], v242 offset:34816
	ds_write_b128 v161, v[62:65] offset:8192
	v_add_co_u32_e32 v62, vcc, s97, v216
	s_nop 1
	v_addc_co_u32_e32 v63, vcc, 0, v217, vcc
	global_load_dwordx4 v[62:65], v[62:63], off
	s_waitcnt lgkmcnt(9)
	v_mfma_f32_16x16x32_f16 v[14:17], v[200:203], v[196:199], v[14:17]
	v_mfma_f32_16x16x32_f16 v[10:13], v[204:207], v[196:199], v[10:13]
	v_mfma_f32_16x16x32_f16 v[6:9], v[208:211], v[196:199], v[6:9]
	v_mfma_f32_16x16x32_f16 v[2:5], v[212:215], v[196:199], v[2:5]
	ds_read_b128 v[196:199], v242 offset:36864
	ds_read_b128 v[200:203], v242 offset:38912
	s_waitcnt vmcnt(14)
	ds_write_b128 v161, v[66:69] offset:12288
	v_add_co_u32_e32 v66, vcc, s27, v216
	s_nop 1
	v_addc_co_u32_e32 v67, vcc, 0, v217, vcc
	global_load_dwordx4 v[66:69], v[66:67], off
	s_waitcnt lgkmcnt(6)
	v_mfma_f32_16x16x32_f16 v[126:129], v[244:247], v[150:153], v[126:129]
	v_mfma_f32_16x16x32_f16 v[122:125], v[248:251], v[150:153], v[122:125]
	v_mfma_f32_16x16x32_f16 v[118:121], v[252:255], v[150:153], v[118:121]
	v_mfma_f32_16x16x32_f16 v[114:117], v[130:133], v[150:153], v[114:117]
	ds_write_b128 v161, v[54:57] offset:16384
	global_load_dwordx4 v[54:57], v[168:169], off
	s_waitcnt lgkmcnt(5)
	v_mfma_f32_16x16x32_f16 v[110:113], v[244:247], v[192:195], v[110:113]
	v_mfma_f32_16x16x32_f16 v[106:109], v[248:251], v[192:195], v[106:109]
	v_mfma_f32_16x16x32_f16 v[102:105], v[252:255], v[192:195], v[102:105]
	v_mfma_f32_16x16x32_f16 v[98:101], v[130:133], v[192:195], v[98:101]
	s_waitcnt vmcnt(15)
	ds_write_b128 v161, v[70:73] offset:20480
	v_add_co_u32_e32 v70, vcc, s81, v168
	s_nop 1
	v_addc_co_u32_e32 v71, vcc, 0, v169, vcc
	global_load_dwordx4 v[70:73], v[70:71], off
	s_waitcnt lgkmcnt(4)
	v_mfma_f32_16x16x32_f16 v[94:97], v[244:247], v[196:199], v[94:97]
	v_mfma_f32_16x16x32_f16 v[90:93], v[248:251], v[196:199], v[90:93]
	v_mfma_f32_16x16x32_f16 v[86:89], v[252:255], v[196:199], v[86:89]
	v_mfma_f32_16x16x32_f16 v[82:85], v[130:133], v[196:199], v[82:85]
	s_waitcnt vmcnt(15)
	ds_write_b128 v161, v[74:77] offset:24576
	v_add_co_u32_e32 v74, vcc, s97, v168
	s_nop 1
	v_addc_co_u32_e32 v75, vcc, 0, v169, vcc
	global_load_dwordx4 v[74:77], v[74:75], off
	s_waitcnt lgkmcnt(4)
	v_mfma_f32_16x16x32_f16 v[14:17], v[244:247], v[200:203], v[14:17]
	v_mfma_f32_16x16x32_f16 v[10:13], v[248:251], v[200:203], v[10:13]
	v_mfma_f32_16x16x32_f16 v[6:9], v[252:255], v[200:203], v[6:9]
	v_mfma_f32_16x16x32_f16 v[2:5], v[130:133], v[200:203], v[2:5]
	s_waitcnt vmcnt(15)
	ds_write_b128 v161, v[78:81] offset:28672
	v_add_co_u32_e32 v78, vcc, s27, v168
	s_nop 1
	v_addc_co_u32_e32 v79, vcc, 0, v169, vcc
	global_load_dwordx4 v[78:81], v[78:79], off
	s_waitcnt lgkmcnt(0)
	s_barrier
	s_cbranch_scc1 .LBB0_1457
; template <int NJ>
; __device__ __forceinline__ void gemm_tile(const f16* __restrict__ A, int lda, const f16* __restrict__ Bt, int ldb,
;                                           int K, f32x4 (&acc)[4][NJ], f16* sA, f16* sB, const int tid) {
;     ...
;   G_LOAD(ra0, rb0, 0)
;   if (K > 64) G_LOAD(ra1, rb1, 64)
;   __syncthreads();
;   G_STORE(ra0, rb0, 0)
;   if (K > 128) G_LOAD(ra0, rb0, 128)
;   __syncthreads();
; #pragma unroll 1
;   for (int k0 = 0; k0 < K; k0 += 128) {
;     {
;       const int kof = (k0 + 192 < K) ? k0 + 192 : K - 64;
;       G_STEP(0, ra1, rb1, true, true, kof)
	ds_read_b128 v[204:207], v163 offset:16384
	ds_read_b128 v[208:211], v163 offset:18432
	ds_read_b128 v[212:215], v163 offset:20480
	ds_read_b128 v[216:219], v163 offset:22528
	s_add_i32 s11, s10, 0xc0
	ds_read_b128 v[192:195], v162
	ds_read_b128 v[196:199], v162 offset:2048
	s_cmpk_lt_u32 s10, 0xa40
	s_cselect_b32 s42, s11, 0xac0
	ds_read_b128 v[200:203], v162 offset:4096
	s_lshl_b64 s[12:13], s[42:43], 1
	v_lshl_add_u64 v[152:153], v[146:147], 0, s[12:13]
	ds_read_b128 v[130:133], v162 offset:6144
	ds_read_b128 v[244:247], v243 offset:16384
	ds_read_b128 v[248:251], v243 offset:18432
	ds_read_b128 v[252:255], v243 offset:20480
	s_waitcnt lgkmcnt(6)
	v_mfma_f32_16x16x32_f16 v[126:129], v[204:207], v[192:195], v[126:129]
	v_lshl_add_u64 v[150:151], v[148:149], 0, s[12:13]
	s_add_i32 s11, s10, 0x100
	s_cmpk_lt_u32 s10, 0xa00
	v_mfma_f32_16x16x32_f16 v[122:125], v[208:211], v[192:195], v[122:125]
	s_cselect_b32 s42, s11, 0xac0
	s_lshl_b64 s[12:13], s[42:43], 1
	v_lshl_add_u64 v[168:169], v[148:149], 0, s[12:13]
	v_mfma_f32_16x16x32_f16 v[118:121], v[212:215], v[192:195], v[118:121]
	s_add_i32 s11, s10, 0x80
	s_cmpk_lt_u32 s10, 0xa80
	s_mov_b32 s10, s11
	v_mfma_f32_16x16x32_f16 v[114:117], v[216:219], v[192:195], v[114:117]
	ds_read_b128 v[192:195], v243 offset:22528
	s_waitcnt vmcnt(15)
	ds_write_b128 v161, v[18:21] offset:32768
	global_load_dwordx4 v[18:21], v[152:153], off
	s_waitcnt lgkmcnt(7)
	v_mfma_f32_16x16x32_f16 v[110:113], v[204:207], v[196:199], v[110:113]
	v_mfma_f32_16x16x32_f16 v[106:109], v[208:211], v[196:199], v[106:109]
	v_mfma_f32_16x16x32_f16 v[102:105], v[212:215], v[196:199], v[102:105]
	v_mfma_f32_16x16x32_f16 v[98:101], v[216:219], v[196:199], v[98:101]
	ds_read_b128 v[196:199], v242
	s_waitcnt vmcnt(15)
	ds_write_b128 v161, v[26:29] offset:36864
	v_add_co_u32_e32 v26, vcc, s81, v152
	s_nop 1
	v_addc_co_u32_e32 v27, vcc, 0, v153, vcc
	global_load_dwordx4 v[26:29], v[26:27], off
	s_waitcnt lgkmcnt(8)
	v_mfma_f32_16x16x32_f16 v[94:97], v[204:207], v[200:203], v[94:97]
	v_mfma_f32_16x16x32_f16 v[90:93], v[208:211], v[200:203], v[90:93]
	v_mfma_f32_16x16x32_f16 v[86:89], v[212:215], v[200:203], v[86:89]
	v_mfma_f32_16x16x32_f16 v[82:85], v[216:219], v[200:203], v[82:85]
	ds_read_b128 v[200:203], v242 offset:2048
	s_waitcnt vmcnt(15)
	ds_write_b128 v161, v[30:33] offset:40960
	v_add_co_u32_e32 v30, vcc, s97, v152
	s_nop 1
	v_addc_co_u32_e32 v31, vcc, 0, v153, vcc
	global_load_dwordx4 v[30:33], v[30:31], off
	s_waitcnt lgkmcnt(9)
	v_mfma_f32_16x16x32_f16 v[14:17], v[204:207], v[130:133], v[14:17]
	v_mfma_f32_16x16x32_f16 v[10:13], v[208:211], v[130:133], v[10:13]
	v_mfma_f32_16x16x32_f16 v[6:9], v[212:215], v[130:133], v[6:9]
	v_mfma_f32_16x16x32_f16 v[2:5], v[216:219], v[130:133], v[2:5]
	ds_read_b128 v[130:133], v242 offset:4096
	ds_read_b128 v[204:207], v242 offset:6144
	s_waitcnt vmcnt(15)
	ds_write_b128 v161, v[34:37] offset:45056
	v_add_co_u32_e32 v34, vcc, s27, v152
	s_nop 1
	v_addc_co_u32_e32 v35, vcc, 0, v153, vcc
	global_load_dwordx4 v[34:37], v[34:35], off
	s_waitcnt lgkmcnt(6)
	v_mfma_f32_16x16x32_f16 v[126:129], v[244:247], v[196:199], v[126:129]
	v_mfma_f32_16x16x32_f16 v[122:125], v[248:251], v[196:199], v[122:125]
	v_mfma_f32_16x16x32_f16 v[118:121], v[252:255], v[196:199], v[118:121]
	v_mfma_f32_16x16x32_f16 v[114:117], v[192:195], v[196:199], v[114:117]
	s_waitcnt vmcnt(15)
	ds_write_b128 v161, v[22:25] offset:49152
	global_load_dwordx4 v[22:25], v[150:151], off
	v_lshl_add_u64 v[216:217], v[146:147], 0, s[12:13]
	s_waitcnt lgkmcnt(5)
	v_mfma_f32_16x16x32_f16 v[110:113], v[244:247], v[200:203], v[110:113]
	v_mfma_f32_16x16x32_f16 v[106:109], v[248:251], v[200:203], v[106:109]
	v_mfma_f32_16x16x32_f16 v[102:105], v[252:255], v[200:203], v[102:105]
	v_mfma_f32_16x16x32_f16 v[98:101], v[192:195], v[200:203], v[98:101]
	s_waitcnt vmcnt(15)
	ds_write_b128 v161, v[38:41] offset:53248
	v_add_co_u32_e32 v38, vcc, s81, v150
	s_nop 1
	v_addc_co_u32_e32 v39, vcc, 0, v151, vcc
	global_load_dwordx4 v[38:41], v[38:39], off
	s_waitcnt lgkmcnt(4)
	v_mfma_f32_16x16x32_f16 v[94:97], v[244:247], v[130:133], v[94:97]
	v_mfma_f32_16x16x32_f16 v[90:93], v[248:251], v[130:133], v[90:93]
	v_mfma_f32_16x16x32_f16 v[86:89], v[252:255], v[130:133], v[86:89]
	v_mfma_f32_16x16x32_f16 v[82:85], v[192:195], v[130:133], v[82:85]
	s_waitcnt vmcnt(15)
	ds_write_b128 v161, v[46:49] offset:57344
	v_add_co_u32_e32 v46, vcc, s97, v150
	s_nop 1
	v_addc_co_u32_e32 v47, vcc, 0, v151, vcc
	global_load_dwordx4 v[46:49], v[46:47], off
	s_waitcnt lgkmcnt(4)
	v_mfma_f32_16x16x32_f16 v[14:17], v[244:247], v[204:207], v[14:17]
	v_mfma_f32_16x16x32_f16 v[10:13], v[248:251], v[204:207], v[10:13]
	v_mfma_f32_16x16x32_f16 v[6:9], v[252:255], v[204:207], v[6:9]
	v_mfma_f32_16x16x32_f16 v[2:5], v[192:195], v[204:207], v[2:5]
	s_waitcnt vmcnt(15)
	ds_write_b128 v161, v[50:53] offset:61440
	v_add_co_u32_e32 v50, vcc, s27, v150
	s_nop 1
	v_addc_co_u32_e32 v51, vcc, 0, v151, vcc
	global_load_dwordx4 v[50:53], v[50:51], off
	s_waitcnt lgkmcnt(0)
	s_barrier
; template <int NJ>
; __device__ __forceinline__ void gemm_tile(const f16* __restrict__ A, int lda, const f16* __restrict__ Bt, int ldb,
;                                           int K, f32x4 (&acc)[4][NJ], f16* sA, f16* sB, const int tid) {
;     ...
;   G_LOAD(ra0, rb0, 0)
;   if (K > 64) G_LOAD(ra1, rb1, 64)
;   __syncthreads();
;   G_STORE(ra0, rb0, 0)
;   if (K > 128) G_LOAD(ra0, rb0, 128)
;   __syncthreads();
; #pragma unroll 1
;   for (int k0 = 0; k0 < K; k0 += 128) {
;     {
;       const int kof = (k0 + 192 < K) ? k0 + 192 : K - 64;
;       G_STEP(0, ra1, rb1, true, true, kof)
;     }
;     __syncthreads();
;     if (k0 + 64 >= K) break;
;     {
;       const int kof = (k0 + 256 < K) ? k0 + 256 : K - 64;
;       G_STEP(1, ra0, rb0, true, true, kof)
;     }
;     __syncthreads();
	ds_read_b128 v[200:203], v163 offset:49152
	ds_read_b128 v[204:207], v163 offset:51200
	ds_read_b128 v[208:211], v163 offset:53248
	ds_read_b128 v[212:215], v163 offset:55296
	ds_read_b128 v[130:133], v162 offset:32768
	ds_read_b128 v[150:153], v162 offset:34816
	ds_read_b128 v[192:195], v162 offset:36864
	ds_read_b128 v[196:199], v162 offset:38912
	ds_read_b128 v[244:247], v243 offset:49152
	ds_read_b128 v[248:251], v243 offset:51200
	ds_read_b128 v[252:255], v243 offset:53248
	s_waitcnt lgkmcnt(6)
	v_mfma_f32_16x16x32_f16 v[126:129], v[200:203], v[130:133], v[126:129]
	v_mfma_f32_16x16x32_f16 v[122:125], v[204:207], v[130:133], v[122:125]
	v_mfma_f32_16x16x32_f16 v[118:121], v[208:211], v[130:133], v[118:121]
	v_mfma_f32_16x16x32_f16 v[114:117], v[212:215], v[130:133], v[114:117]
	ds_read_b128 v[130:133], v243 offset:55296
	s_waitcnt vmcnt(15)
	ds_write_b128 v161, v[42:45]
	s_waitcnt lgkmcnt(7)
	v_mfma_f32_16x16x32_f16 v[110:113], v[200:203], v[150:153], v[110:113]
	v_mfma_f32_16x16x32_f16 v[106:109], v[204:207], v[150:153], v[106:109]
	v_mfma_f32_16x16x32_f16 v[102:105], v[208:211], v[150:153], v[102:105]
	v_mfma_f32_16x16x32_f16 v[98:101], v[212:215], v[150:153], v[98:101]
	ds_read_b128 v[150:153], v242 offset:32768
	s_waitcnt vmcnt(14)
	ds_write_b128 v161, v[58:61] offset:4096
	s_waitcnt lgkmcnt(8)
	v_mfma_f32_16x16x32_f16 v[94:97], v[200:203], v[192:195], v[94:97]
	v_mfma_f32_16x16x32_f16 v[90:93], v[204:207], v[192:195], v[90:93]
	v_mfma_f32_16x16x32_f16 v[86:89], v[208:211], v[192:195], v[86:89]
	v_mfma_f32_16x16x32_f16 v[82:85], v[212:215], v[192:195], v[82:85]
	ds_read_b128 v[192:195], v242 offset:34816
	s_waitcnt vmcnt(13)
	ds_write_b128 v161, v[62:65] offset:8192
	s_waitcnt lgkmcnt(9)
	v_mfma_f32_16x16x32_f16 v[14:17], v[200:203], v[196:199], v[14:17]
	v_mfma_f32_16x16x32_f16 v[10:13], v[204:207], v[196:199], v[10:13]
	v_mfma_f32_16x16x32_f16 v[6:9], v[208:211], v[196:199], v[6:9]
	v_mfma_f32_16x16x32_f16 v[2:5], v[212:215], v[196:199], v[2:5]
	ds_read_b128 v[196:199], v242 offset:36864
	ds_read_b128 v[200:203], v242 offset:38912
	s_waitcnt vmcnt(12)
	ds_write_b128 v161, v[66:69] offset:12288
	s_waitcnt lgkmcnt(6)
	v_mfma_f32_16x16x32_f16 v[126:129], v[244:247], v[150:153], v[126:129]
	v_mfma_f32_16x16x32_f16 v[122:125], v[248:251], v[150:153], v[122:125]
	v_mfma_f32_16x16x32_f16 v[118:121], v[252:255], v[150:153], v[118:121]
	v_mfma_f32_16x16x32_f16 v[114:117], v[130:133], v[150:153], v[114:117]
	s_waitcnt vmcnt(11)
	ds_write_b128 v161, v[54:57] offset:16384
	s_waitcnt lgkmcnt(5)
	v_mfma_f32_16x16x32_f16 v[110:113], v[244:247], v[192:195], v[110:113]
	v_mfma_f32_16x16x32_f16 v[106:109], v[248:251], v[192:195], v[106:109]
	v_mfma_f32_16x16x32_f16 v[102:105], v[252:255], v[192:195], v[102:105]
	v_mfma_f32_16x16x32_f16 v[98:101], v[130:133], v[192:195], v[98:101]
	s_waitcnt vmcnt(10)
	ds_write_b128 v161, v[70:73] offset:20480
	s_waitcnt lgkmcnt(4)
	v_mfma_f32_16x16x32_f16 v[94:97], v[244:247], v[196:199], v[94:97]
	v_mfma_f32_16x16x32_f16 v[90:93], v[248:251], v[196:199], v[90:93]
	v_mfma_f32_16x16x32_f16 v[86:89], v[252:255], v[196:199], v[86:89]
	v_mfma_f32_16x16x32_f16 v[82:85], v[130:133], v[196:199], v[82:85]
	s_waitcnt vmcnt(9)
	ds_write_b128 v161, v[74:77] offset:24576
	s_waitcnt lgkmcnt(4)
	v_mfma_f32_16x16x32_f16 v[14:17], v[244:247], v[200:203], v[14:17]
	v_mfma_f32_16x16x32_f16 v[10:13], v[248:251], v[200:203], v[10:13]
	v_mfma_f32_16x16x32_f16 v[6:9], v[252:255], v[200:203], v[6:9]
	v_mfma_f32_16x16x32_f16 v[2:5], v[130:133], v[200:203], v[2:5]
	s_waitcnt vmcnt(8)
	ds_write_b128 v161, v[78:81] offset:28672
	s_waitcnt lgkmcnt(0)
	s_barrier
	ds_read_b128 v[204:207], v163 offset:16384
	ds_read_b128 v[208:211], v163 offset:18432
	ds_read_b128 v[212:215], v163 offset:20480
	ds_read_b128 v[216:219], v163 offset:22528
	s_add_i32 s11, s10, 0xc0
	ds_read_b128 v[192:195], v162
	ds_read_b128 v[196:199], v162 offset:2048
	s_cmpk_lt_u32 s10, 0xa40
	s_cselect_b32 s42, s11, 0xac0
	ds_read_b128 v[200:203], v162 offset:4096
	s_lshl_b64 s[12:13], s[42:43], 1
	v_lshl_add_u64 v[152:153], v[146:147], 0, s[12:13]
	ds_read_b128 v[130:133], v162 offset:6144
	ds_read_b128 v[244:247], v243 offset:16384
	ds_read_b128 v[248:251], v243 offset:18432
	ds_read_b128 v[252:255], v243 offset:20480
	s_waitcnt lgkmcnt(6)
	v_mfma_f32_16x16x32_f16 v[126:129], v[204:207], v[192:195], v[126:129]
	v_lshl_add_u64 v[150:151], v[148:149], 0, s[12:13]
	s_add_i32 s11, s10, 0x100
	s_cmpk_lt_u32 s10, 0xa00
	v_mfma_f32_16x16x32_f16 v[122:125], v[208:211], v[192:195], v[122:125]
	s_cselect_b32 s42, s11, 0xac0
	s_lshl_b64 s[12:13], s[42:43], 1
	v_lshl_add_u64 v[168:169], v[148:149], 0, s[12:13]
	v_mfma_f32_16x16x32_f16 v[118:121], v[212:215], v[192:195], v[118:121]
	s_add_i32 s11, s10, 0x80
	s_cmpk_lt_u32 s10, 0xa80
	s_mov_b32 s10, s11
	v_mfma_f32_16x16x32_f16 v[114:117], v[216:219], v[192:195], v[114:117]
	ds_read_b128 v[192:195], v243 offset:22528
	s_waitcnt vmcnt(7)
	ds_write_b128 v161, v[18:21] offset:32768
	s_waitcnt lgkmcnt(7)
	v_mfma_f32_16x16x32_f16 v[110:113], v[204:207], v[196:199], v[110:113]
	v_mfma_f32_16x16x32_f16 v[106:109], v[208:211], v[196:199], v[106:109]
	v_mfma_f32_16x16x32_f16 v[102:105], v[212:215], v[196:199], v[102:105]
	v_mfma_f32_16x16x32_f16 v[98:101], v[216:219], v[196:199], v[98:101]
	ds_read_b128 v[196:199], v242
	s_waitcnt vmcnt(6)
	ds_write_b128 v161, v[26:29] offset:36864
	s_waitcnt lgkmcnt(8)
	v_mfma_f32_16x16x32_f16 v[94:97], v[204:207], v[200:203], v[94:97]
	v_mfma_f32_16x16x32_f16 v[90:93], v[208:211], v[200:203], v[90:93]
	v_mfma_f32_16x16x32_f16 v[86:89], v[212:215], v[200:203], v[86:89]
	v_mfma_f32_16x16x32_f16 v[82:85], v[216:219], v[200:203], v[82:85]
	ds_read_b128 v[200:203], v242 offset:2048
	s_waitcnt vmcnt(5)
; template <int NJ>
; __device__ __forceinline__ void gemm_tile(const f16* __restrict__ A, int lda, const f16* __restrict__ Bt, int ldb,
;                                           int K, f32x4 (&acc)[4][NJ], f16* sA, f16* sB, const int tid) {
;     ...
;   G_LOAD(ra0, rb0, 0)
;   if (K > 64) G_LOAD(ra1, rb1, 64)
;   __syncthreads();
;   G_STORE(ra0, rb0, 0)
;   if (K > 128) G_LOAD(ra0, rb0, 128)
;   __syncthreads();
; #pragma unroll 1
;   for (int k0 = 0; k0 < K; k0 += 128) {
;     {
;       const int kof = (k0 + 192 < K) ? k0 + 192 : K - 64;
;       G_STEP(0, ra1, rb1, true, true, kof)
;     }
;     __syncthreads();
;     if (k0 + 64 >= K) break;
;     {
;       const int kof = (k0 + 256 < K) ? k0 + 256 : K - 64;
;       G_STEP(1, ra0, rb0, true, true, kof)
;     }
;     __syncthreads();
; template <int NJ>
; __device__ __forceinline__ void gres_tile(const Params& p, const f16* A, int lda, const f16* W, int K, const float* mod,
;                                           bool first_in, f16* sA, f16* sB, int m0, int n0) {
;     ...
; #pragma unroll
;   for (int i = 0; i < 4; ++i) {
;     int m = m0 + wm * 64 + i * 16 + (lane & 15);
;     const float* xi = xrow_in(p, first_in ? 0 : 1, m);
;     float* xo = xrow_out(p, m);
;     const float* gt = mod + (size_t)modrow_of(m) * 6 * DM;
	ds_write_b128 v161, v[30:33] offset:40960
	s_waitcnt lgkmcnt(9)
	v_mfma_f32_16x16x32_f16 v[14:17], v[204:207], v[130:133], v[14:17]
	v_mfma_f32_16x16x32_f16 v[10:13], v[208:211], v[130:133], v[10:13]
	v_mfma_f32_16x16x32_f16 v[6:9], v[212:215], v[130:133], v[6:9]
	v_mfma_f32_16x16x32_f16 v[2:5], v[216:219], v[130:133], v[2:5]
	ds_read_b128 v[130:133], v242 offset:4096
	ds_read_b128 v[204:207], v242 offset:6144
	s_waitcnt vmcnt(4)
	ds_write_b128 v161, v[34:37] offset:45056
	s_waitcnt lgkmcnt(6)
	v_mfma_f32_16x16x32_f16 v[126:129], v[244:247], v[196:199], v[126:129]
	v_mfma_f32_16x16x32_f16 v[122:125], v[248:251], v[196:199], v[122:125]
	v_mfma_f32_16x16x32_f16 v[118:121], v[252:255], v[196:199], v[118:121]
	v_mfma_f32_16x16x32_f16 v[114:117], v[192:195], v[196:199], v[114:117]
	s_waitcnt vmcnt(3)
	ds_write_b128 v161, v[22:25] offset:49152
	v_lshl_add_u64 v[216:217], v[146:147], 0, s[12:13]
	s_waitcnt lgkmcnt(5)
	v_mfma_f32_16x16x32_f16 v[110:113], v[244:247], v[200:203], v[110:113]
	v_mfma_f32_16x16x32_f16 v[106:109], v[248:251], v[200:203], v[106:109]
	v_mfma_f32_16x16x32_f16 v[102:105], v[252:255], v[200:203], v[102:105]
	v_mfma_f32_16x16x32_f16 v[98:101], v[192:195], v[200:203], v[98:101]
	s_waitcnt vmcnt(2)
	ds_write_b128 v161, v[38:41] offset:53248
	s_waitcnt lgkmcnt(4)
	v_mfma_f32_16x16x32_f16 v[94:97], v[244:247], v[130:133], v[94:97]
	v_mfma_f32_16x16x32_f16 v[90:93], v[248:251], v[130:133], v[90:93]
	v_mfma_f32_16x16x32_f16 v[86:89], v[252:255], v[130:133], v[86:89]
	v_mfma_f32_16x16x32_f16 v[82:85], v[192:195], v[130:133], v[82:85]
	s_waitcnt vmcnt(1)
	ds_write_b128 v161, v[46:49] offset:57344
	s_waitcnt lgkmcnt(4)
	v_mfma_f32_16x16x32_f16 v[14:17], v[244:247], v[204:207], v[14:17]
	v_mfma_f32_16x16x32_f16 v[10:13], v[248:251], v[204:207], v[10:13]
	v_mfma_f32_16x16x32_f16 v[6:9], v[252:255], v[204:207], v[6:9]
	v_mfma_f32_16x16x32_f16 v[2:5], v[192:195], v[204:207], v[2:5]
	s_waitcnt vmcnt(0)
	ds_write_b128 v161, v[50:53] offset:61440
	s_waitcnt lgkmcnt(0)
	s_barrier
	ds_read_b128 v[200:203], v163 offset:49152
	ds_read_b128 v[204:207], v163 offset:51200
	ds_read_b128 v[208:211], v163 offset:53248
	ds_read_b128 v[212:215], v163 offset:55296
	ds_read_b128 v[130:133], v162 offset:32768
	ds_read_b128 v[150:153], v162 offset:34816
	ds_read_b128 v[192:195], v162 offset:36864
	ds_read_b128 v[196:199], v162 offset:38912
	ds_read_b128 v[244:247], v243 offset:49152
	ds_read_b128 v[248:251], v243 offset:51200
	ds_read_b128 v[252:255], v243 offset:53248
	s_waitcnt lgkmcnt(6)
	v_mfma_f32_16x16x32_f16 v[126:129], v[200:203], v[130:133], v[126:129]
	v_mfma_f32_16x16x32_f16 v[122:125], v[204:207], v[130:133], v[122:125]
	v_mfma_f32_16x16x32_f16 v[118:121], v[208:211], v[130:133], v[118:121]
	v_mfma_f32_16x16x32_f16 v[114:117], v[212:215], v[130:133], v[114:117]
	ds_read_b128 v[130:133], v243 offset:55296
	s_waitcnt lgkmcnt(6)
	v_mfma_f32_16x16x32_f16 v[110:113], v[200:203], v[150:153], v[110:113]
	v_mfma_f32_16x16x32_f16 v[106:109], v[204:207], v[150:153], v[106:109]
	v_mfma_f32_16x16x32_f16 v[102:105], v[208:211], v[150:153], v[102:105]
	v_mfma_f32_16x16x32_f16 v[98:101], v[212:215], v[150:153], v[98:101]
	ds_read_b128 v[150:153], v242 offset:32768
	s_waitcnt lgkmcnt(6)
	v_mfma_f32_16x16x32_f16 v[94:97], v[200:203], v[192:195], v[94:97]
	v_mfma_f32_16x16x32_f16 v[90:93], v[204:207], v[192:195], v[90:93]
	v_mfma_f32_16x16x32_f16 v[86:89], v[208:211], v[192:195], v[86:89]
	v_mfma_f32_16x16x32_f16 v[82:85], v[212:215], v[192:195], v[82:85]
	ds_read_b128 v[192:195], v242 offset:34816
	s_waitcnt lgkmcnt(6)
	v_mfma_f32_16x16x32_f16 v[14:17], v[200:203], v[196:199], v[14:17]
	v_mfma_f32_16x16x32_f16 v[10:13], v[204:207], v[196:199], v[10:13]
	v_mfma_f32_16x16x32_f16 v[6:9], v[208:211], v[196:199], v[6:9]
	v_mfma_f32_16x16x32_f16 v[2:5], v[212:215], v[196:199], v[2:5]
	ds_read_b128 v[196:199], v242 offset:36864
	ds_read_b128 v[200:203], v242 offset:38912
	s_waitcnt lgkmcnt(3)
	v_mfma_f32_16x16x32_f16 v[126:129], v[244:247], v[150:153], v[126:129]
	v_mfma_f32_16x16x32_f16 v[122:125], v[248:251], v[150:153], v[122:125]
	v_mfma_f32_16x16x32_f16 v[118:121], v[252:255], v[150:153], v[118:121]
	v_mfma_f32_16x16x32_f16 v[114:117], v[130:133], v[150:153], v[114:117]
	s_waitcnt lgkmcnt(2)
	v_mfma_f32_16x16x32_f16 v[110:113], v[244:247], v[192:195], v[110:113]
	v_mfma_f32_16x16x32_f16 v[106:109], v[248:251], v[192:195], v[106:109]
	v_mfma_f32_16x16x32_f16 v[102:105], v[252:255], v[192:195], v[102:105]
	v_mfma_f32_16x16x32_f16 v[98:101], v[130:133], v[192:195], v[98:101]
	s_waitcnt lgkmcnt(1)
	v_mfma_f32_16x16x32_f16 v[94:97], v[244:247], v[196:199], v[94:97]
	v_mfma_f32_16x16x32_f16 v[90:93], v[248:251], v[196:199], v[90:93]
	v_mfma_f32_16x16x32_f16 v[86:89], v[252:255], v[196:199], v[86:89]
	v_mfma_f32_16x16x32_f16 v[82:85], v[130:133], v[196:199], v[82:85]
	s_waitcnt lgkmcnt(0)
	v_mfma_f32_16x16x32_f16 v[14:17], v[244:247], v[200:203], v[14:17]
	v_mfma_f32_16x16x32_f16 v[10:13], v[248:251], v[200:203], v[10:13]
	v_mfma_f32_16x16x32_f16 v[6:9], v[252:255], v[200:203], v[6:9]
	v_mfma_f32_16x16x32_f16 v[2:5], v[130:133], v[200:203], v[2:5]
	s_waitcnt lgkmcnt(0)
	s_waitcnt vmcnt(15)
	v_or_b32_e32 v18, s6, v154
	v_add_u32_e32 v21, v18, v160
	v_cmp_gt_i32_e32 vcc, s80, v21
	v_ashrrev_i32_e32 v20, 31, v21
	s_waitcnt vmcnt(11)
; __device__ __forceinline__ const float* xrow_in(const Params& p, int layer, int row) {
;   if (layer == 0) return row < NLAT ? p.in[I_X] + (size_t)row * DM : p.in[I_CTX] + (size_t)(row - NLAT) * DM;
;   return row < NLAT ? p.out + (size_t)row * DM : (const float*)(p.ws + XCTX_OFF) + (size_t)(row - NLAT) * DM;
; }
; template <int NJ>
; __device__ __forceinline__ void gres_tile(const Params& p, const f16* A, int lda, const f16* W, int K, const float* mod,
;                                           bool first_in, f16* sA, f16* sB, int m0, int n0) {
;     ...
; #pragma unroll
;   for (int i = 0; i < 4; ++i) {
;     int m = m0 + wm * 64 + i * 16 + (lane & 15);
;     const float* xi = xrow_in(p, first_in ? 0 : 1, m);
;     float* xo = xrow_out(p, m);
;     const float* gt = mod + (size_t)modrow_of(m) * 6 * DM;
; #pragma unroll
;     for (int j = 0; j < NJ; ++j) {
;       int n = n0 + wn * (NJ * 16) + j * 16 + 4 * (lane >> 4);
;       float4 xv = *(const float4*)(xi + n);
;       float4 gv = *(const float4*)(gt + n);
;       float4 o;
;       o.x = xv.x + gv.x * acc[i][j][0];
;       o.y = xv.y + gv.y * acc[i][j][1];
;       o.z = xv.z + gv.z * acc[i][j][2];
;       o.w = xv.w + gv.w * acc[i][j][3];
;       *(float4*)(xo + n) = o;
;     }
;   }
	v_add_u32_e32 v22, 0xffff8000, v21
	v_cndmask_b32_e32 v23, 0, v20, vcc
	v_cndmask_b32_e32 v22, v22, v21, vcc
	v_cndmask_b32_e32 v25, v137, v1, vcc
	v_cndmask_b32_e32 v24, v136, v0, vcc
	v_lshlrev_b64 v[22:23], 12, v[22:23]
	v_lshrrev_b32_e32 v20, 18, v20
	v_lshl_add_u64 v[22:23], v[24:25], 0, v[22:23]
	v_add_u32_e32 v24, v21, v20
	v_lshl_or_b32 v18, s7, 7, v166
	v_ashrrev_i32_e32 v24, 14, v24
	v_ashrrev_i32_e32 v19, 31, v18
	v_cndmask_b32_e32 v24, 2, v24, vcc
	v_mul_hi_i32_i24_e32 v25, 0x6000, v24
	v_mul_i32_i24_e32 v24, 0x6000, v24
	v_lshlrev_b64 v[18:19], 2, v[18:19]
	v_lshl_add_u64 v[24:25], v[134:135], 0, v[24:25]
	v_lshl_add_u64 v[30:31], v[22:23], 0, v[18:19]
	v_lshl_add_u64 v[32:33], v[24:25], 0, v[18:19]
	global_load_dwordx4 v[22:25], v[30:31], off
	global_load_dwordx4 v[26:29], v[32:33], off
	s_add_i32 s5, s5, s26
	s_cmp_ge_i32 s5, s74
	s_waitcnt vmcnt(0)
	v_pk_fma_f32 v[22:23], v[126:127], v[26:27], v[22:23]
	v_pk_fma_f32 v[24:25], v[128:129], v[28:29], v[24:25]
	global_store_dwordx4 v[30:31], v[22:25], off
	global_load_dwordx4 v[22:25], v[30:31], off offset:64
	s_nop 0
	global_load_dwordx4 v[26:29], v[32:33], off offset:64
	s_waitcnt vmcnt(0)
	v_pk_fma_f32 v[22:23], v[122:123], v[26:27], v[22:23]
	v_pk_fma_f32 v[24:25], v[124:125], v[28:29], v[24:25]
	global_store_dwordx4 v[30:31], v[22:25], off offset:64
	global_load_dwordx4 v[22:25], v[30:31], off offset:128
	s_nop 0
	global_load_dwordx4 v[26:29], v[32:33], off offset:128
	s_waitcnt vmcnt(0)
	v_pk_fma_f32 v[22:23], v[118:119], v[26:27], v[22:23]
	v_pk_fma_f32 v[24:25], v[120:121], v[28:29], v[24:25]
	global_store_dwordx4 v[30:31], v[22:25], off offset:128
	global_load_dwordx4 v[22:25], v[30:31], off offset:192
	s_nop 0
	global_load_dwordx4 v[26:29], v[32:33], off offset:192
	s_waitcnt vmcnt(0)
	v_pk_fma_f32 v[22:23], v[114:115], v[26:27], v[22:23]
	v_pk_fma_f32 v[24:25], v[116:117], v[28:29], v[24:25]
	v_or_b32_e32 v26, 16, v21
	global_store_dwordx4 v[30:31], v[22:25], off offset:192
	v_cmp_gt_i32_e32 vcc, s80, v26
	s_nop 0
	v_ashrrev_i32_e32 v22, 31, v26
	v_add_u32_e32 v24, 0xffff8010, v21
	v_cndmask_b32_e32 v23, 0, v22, vcc
	v_cndmask_b32_e32 v22, v24, v26, vcc
	v_cndmask_b32_e32 v25, v137, v1, vcc
	v_cndmask_b32_e32 v24, v136, v0, vcc
	v_lshlrev_b64 v[22:23], 12, v[22:23]
	v_lshl_add_u64 v[22:23], v[24:25], 0, v[22:23]
	v_add_u32_e32 v24, v26, v20
	v_ashrrev_i32_e32 v24, 14, v24
	v_cndmask_b32_e32 v24, 2, v24, vcc
	v_mul_hi_i32_i24_e32 v25, 0x6000, v24
	v_mul_i32_i24_e32 v24, 0x6000, v24
	v_lshl_add_u64 v[24:25], v[134:135], 0, v[24:25]
	v_lshl_add_u64 v[30:31], v[22:23], 0, v[18:19]
	v_lshl_add_u64 v[32:33], v[24:25], 0, v[18:19]
	global_load_dwordx4 v[22:25], v[30:31], off
	global_load_dwordx4 v[26:29], v[32:33], off
	s_waitcnt vmcnt(0)
	v_pk_fma_f32 v[22:23], v[110:111], v[26:27], v[22:23]
	v_pk_fma_f32 v[24:25], v[112:113], v[28:29], v[24:25]
	global_store_dwordx4 v[30:31], v[22:25], off
	global_load_dwordx4 v[22:25], v[30:31], off offset:64
	s_nop 0
	global_load_dwordx4 v[26:29], v[32:33], off offset:64
	s_waitcnt vmcnt(0)
	v_pk_fma_f32 v[22:23], v[106:107], v[26:27], v[22:23]
	v_pk_fma_f32 v[24:25], v[108:109], v[28:29], v[24:25]
	global_store_dwordx4 v[30:31], v[22:25], off offset:64
	global_load_dwordx4 v[22:25], v[30:31], off offset:128
	s_nop 0
	global_load_dwordx4 v[26:29], v[32:33], off offset:128
	s_waitcnt vmcnt(0)
	v_pk_fma_f32 v[22:23], v[102:103], v[26:27], v[22:23]
	v_pk_fma_f32 v[24:25], v[104:105], v[28:29], v[24:25]
	global_store_dwordx4 v[30:31], v[22:25], off offset:128
	global_load_dwordx4 v[22:25], v[30:31], off offset:192
	s_nop 0
	global_load_dwordx4 v[26:29], v[32:33], off offset:192
	s_waitcnt vmcnt(0)
; template <int NJ>
; __device__ __forceinline__ void gres_tile(const Params& p, const f16* A, int lda, const f16* W, int K, const float* mod,
;                                           bool first_in, f16* sA, f16* sB, int m0, int n0) {
;     ...
; #pragma unroll
;   for (int i = 0; i < 4; ++i) {
;     int m = m0 + wm * 64 + i * 16 + (lane & 15);
;     const float* xi = xrow_in(p, first_in ? 0 : 1, m);
;     float* xo = xrow_out(p, m);
;     const float* gt = mod + (size_t)modrow_of(m) * 6 * DM;
; #pragma unroll
;     for (int j = 0; j < NJ; ++j) {
;       int n = n0 + wn * (NJ * 16) + j * 16 + 4 * (lane >> 4);
;       float4 xv = *(const float4*)(xi + n);
;       float4 gv = *(const float4*)(gt + n);
;       float4 o;
;       o.x = xv.x + gv.x * acc[i][j][0];
;       o.y = xv.y + gv.y * acc[i][j][1];
;       o.z = xv.z + gv.z * acc[i][j][2];
;       o.w = xv.w + gv.w * acc[i][j][3];
;       *(float4*)(xo + n) = o;
;     }
;   }
	v_pk_fma_f32 v[22:23], v[98:99], v[26:27], v[22:23]
	v_pk_fma_f32 v[24:25], v[100:101], v[28:29], v[24:25]
	v_or_b32_e32 v26, 32, v21
	global_store_dwordx4 v[30:31], v[22:25], off offset:192
	v_cmp_gt_i32_e32 vcc, s80, v26
	s_nop 0
	v_ashrrev_i32_e32 v22, 31, v26
	v_add_u32_e32 v24, 0xffff8020, v21
	v_cndmask_b32_e32 v23, 0, v22, vcc
	v_cndmask_b32_e32 v22, v24, v26, vcc
	v_cndmask_b32_e32 v25, v137, v1, vcc
	v_cndmask_b32_e32 v24, v136, v0, vcc
	v_lshlrev_b64 v[22:23], 12, v[22:23]
	v_lshl_add_u64 v[22:23], v[24:25], 0, v[22:23]
	v_add_u32_e32 v24, v26, v20
	v_ashrrev_i32_e32 v24, 14, v24
	v_cndmask_b32_e32 v24, 2, v24, vcc
	v_mul_hi_i32_i24_e32 v25, 0x6000, v24
	v_mul_i32_i24_e32 v24, 0x6000, v24
	v_lshl_add_u64 v[24:25], v[134:135], 0, v[24:25]
	v_lshl_add_u64 v[30:31], v[22:23], 0, v[18:19]
	v_lshl_add_u64 v[32:33], v[24:25], 0, v[18:19]
	global_load_dwordx4 v[22:25], v[30:31], off
	global_load_dwordx4 v[26:29], v[32:33], off
	s_waitcnt vmcnt(0)
	v_pk_fma_f32 v[22:23], v[94:95], v[26:27], v[22:23]
	v_pk_fma_f32 v[24:25], v[96:97], v[28:29], v[24:25]
	global_store_dwordx4 v[30:31], v[22:25], off
	global_load_dwordx4 v[22:25], v[30:31], off offset:64
	s_nop 0
	global_load_dwordx4 v[26:29], v[32:33], off offset:64
	s_waitcnt vmcnt(0)
	v_pk_fma_f32 v[22:23], v[90:91], v[26:27], v[22:23]
	v_pk_fma_f32 v[24:25], v[92:93], v[28:29], v[24:25]
	global_store_dwordx4 v[30:31], v[22:25], off offset:64
	global_load_dwordx4 v[22:25], v[30:31], off offset:128
	s_nop 0
	global_load_dwordx4 v[26:29], v[32:33], off offset:128
	s_waitcnt vmcnt(0)
	v_pk_fma_f32 v[22:23], v[86:87], v[26:27], v[22:23]
	v_pk_fma_f32 v[24:25], v[88:89], v[28:29], v[24:25]
	global_store_dwordx4 v[30:31], v[22:25], off offset:128
	global_load_dwordx4 v[22:25], v[30:31], off offset:192
	s_nop 0
	global_load_dwordx4 v[26:29], v[32:33], off offset:192
	s_waitcnt vmcnt(0)
	v_pk_fma_f32 v[22:23], v[82:83], v[26:27], v[22:23]
	v_pk_fma_f32 v[24:25], v[84:85], v[28:29], v[24:25]
	v_or_b32_e32 v26, 48, v21
	global_store_dwordx4 v[30:31], v[22:25], off offset:192
	v_cmp_gt_i32_e32 vcc, s80, v26
	v_add_u32_e32 v21, 0xffff8030, v21
	v_ashrrev_i32_e32 v22, 31, v26
	v_add_u32_e32 v20, v26, v20
	v_cndmask_b32_e32 v23, 0, v22, vcc
	v_cndmask_b32_e32 v22, v21, v26, vcc
	v_ashrrev_i32_e32 v20, 14, v20
	v_cndmask_b32_e32 v25, v137, v1, vcc
	v_cndmask_b32_e32 v24, v136, v0, vcc
	v_lshlrev_b64 v[22:23], 12, v[22:23]
	v_cndmask_b32_e32 v20, 2, v20, vcc
	v_lshl_add_u64 v[22:23], v[24:25], 0, v[22:23]
	v_mul_hi_i32_i24_e32 v21, 0x6000, v20
	v_mul_i32_i24_e32 v20, 0x6000, v20
	v_lshl_add_u64 v[20:21], v[134:135], 0, v[20:21]
	v_lshl_add_u64 v[26:27], v[22:23], 0, v[18:19]
	v_lshl_add_u64 v[28:29], v[20:21], 0, v[18:19]
	global_load_dwordx4 v[18:21], v[26:27], off
	global_load_dwordx4 v[22:25], v[28:29], off
	s_waitcnt vmcnt(0)
	v_pk_fma_f32 v[14:15], v[14:15], v[22:23], v[18:19]
	v_pk_fma_f32 v[16:17], v[16:17], v[24:25], v[20:21]
	global_store_dwordx4 v[26:27], v[14:17], off
	global_load_dwordx4 v[14:17], v[26:27], off offset:64
	s_nop 0
	global_load_dwordx4 v[18:21], v[28:29], off offset:64
	s_waitcnt vmcnt(0)
	v_pk_fma_f32 v[10:11], v[10:11], v[18:19], v[14:15]
	v_pk_fma_f32 v[12:13], v[12:13], v[20:21], v[16:17]
	global_store_dwordx4 v[26:27], v[10:13], off offset:64
	global_load_dwordx4 v[10:13], v[26:27], off offset:128
	s_nop 0
	global_load_dwordx4 v[14:17], v[28:29], off offset:128
	s_waitcnt vmcnt(0)
	v_pk_fma_f32 v[6:7], v[6:7], v[14:15], v[10:11]
	v_pk_fma_f32 v[8:9], v[8:9], v[16:17], v[12:13]
	global_store_dwordx4 v[26:27], v[6:9], off offset:128
	global_load_dwordx4 v[6:9], v[26:27], off offset:192
	s_nop 0
	global_load_dwordx4 v[10:13], v[28:29], off offset:192
	s_waitcnt vmcnt(0)
	v_pk_fma_f32 v[2:3], v[2:3], v[10:11], v[6:7]
	v_pk_fma_f32 v[4:5], v[4:5], v[12:13], v[8:9]
	global_store_dwordx4 v[26:27], v[2:5], off offset:192
	s_cbranch_scc0 .LBB0_1456
